# speedup vs baseline: 1.0092x; 1.0092x over previous
; #define PG8_STAGE(bufoff, gbase, voff) do { _Pragma("unroll") for (int _i = 0; _i < 2; ++_i) \
;         __builtin_amdgcn_global_load_lds((const unsigned*)((const char*)(gbase) + (voff)[_i]), (LAS unsigned*)(lds + (bufoff) + ldsw + _i * 8192), 16, 0, 0); } while (0)
; #define PG8_LDA(dst, b, h) do { _Pragma("unroll") for (int m = 0; m < 4; ++m) _Pragma("unroll") for (int k = 0; k < 2; ++k) dst[m][k] = *(const LAS bf16x8*)(lds + PG8_SA(b, h) + aoff + m * 2048 + k * 1024); } while (0)
; #define PG8_LDB(dst, b, h) do { _Pragma("unroll") for (int n = 0; n < 2; ++n) _Pragma("unroll") for (int k = 0; k < 2; ++k) dst[n][k] = *(const LAS bf16x8*)(lds + PG8_SB(b, h) + boff + n * 2048 + k * 1024); } while (0)
; #define PG8_MMA(ai, bj, At, Bt) do { __builtin_amdgcn_s_setprio(1); _Pragma("unroll") for (int m = 0; m < 4; ++m) _Pragma("unroll") for (int n = 0; n < 2; ++n) _Pragma("unroll") for (int k = 0; k < 2; ++k) \
;         acc[ai][bj][m][n] = __builtin_amdgcn_mfma_f32_16x16x32_bf16(Bt[n][k], At[m][k], acc[ai][bj][m][n], 0, 0, 0); __builtin_amdgcn_s_setprio(0); } while (0)
; #define PG8_WAIT_V(n) asm volatile("s_waitcnt vmcnt(" #n ")" ::: "memory")
; #define PG8_WAIT_L(n) asm volatile("s_waitcnt lgkmcnt(" #n ")" ::: "memory")
; #define PG8_BAR __builtin_amdgcn_s_barrier()
; template <class Epi, class Sched>
; __device__ __forceinline__ void gemm_phase(LAS unsigned char* lds, const Gemm g, const Sched& S, const Epi& E, const int tid) {
;     ...
;             const bool last = (t == nt - 2);
;             const char* a1 = cA + (size_t)(t + 1) * kstepA;
;             const char* a2 = last ? nA : cA + (size_t)(t + 2) * kstepA; const char* b2 = last ? nB : cB + (size_t)(t + 2) * kstep;
;             const char* a3 = a2 + kstepA; const char* b3 = b2 + kstep;
;             if constexpr (Epi::HAS_MID) { if (t == g.tmid) E.mid(acc, cur, ui, wr, wc, fr, fq); }
;             PG8_LDB(B0, 0, 0); PG8_LDB(B1, 0, 1); PG8_SCHED; PG8_LDA(At, 0, 0); PG8_STAGE(PG8_SA(1, 1), a1 + hstepA, voffA);
;             PG8_WAIT_V(8); PG8_WAIT_L(0); PG8_BAR; PG8_MMA(0, 0, At, B0); PG8_MMA(0, 1, At, B1); PG8_BAR; PG8_SCHED;
;             PG8_LDA(At, 0, 1); PG8_STAGE(PG8_SB(0, 0), b2, voffB); PG8_STAGE(PG8_SB(0, 1), b2 + hstepB, voffB); PG8_STAGE(PG8_SA(0, 0), a2, voffA);
;             PG8_WAIT_V(8); PG8_WAIT_L(0); PG8_BAR; PG8_MMA(1, 0, At, B0); PG8_MMA(1, 1, At, B1); PG8_BAR; PG8_SCHED;
.LBB0_285:
	ds_read_b128 v[128:131], v173
	ds_read_b128 v[158:161], v173 offset:1024
	ds_read_b128 v[178:181], v173 offset:2048
	ds_read_b128 v[182:185], v173 offset:3072
	ds_read_b128 v[186:189], v174
	ds_read_b128 v[190:193], v174 offset:1024
	ds_read_b128 v[194:197], v174 offset:2048
	ds_read_b128 v[198:201], v174 offset:3072
	s_add_u32 s16, s8, 0xfff80080
	s_addc_u32 s17, s9, -1
	s_cmp_eq_u32 s48, 28
	s_cselect_b32 s31, s7, s17
	s_cselect_b32 s30, s18, s16
	s_cselect_b32 s27, s19, s39
	s_cselect_b32 s26, s29, s38
	v_lshl_add_u64 v[162:163], s[8:9], 0, v[150:151]
	s_add_i32 m0, s41, 0xc000
	ds_read_b128 v[202:205], v175
	ds_read_b128 v[206:209], v175 offset:1024
	ds_read_b128 v[210:213], v175 offset:2048
	ds_read_b128 v[214:217], v175 offset:3072
	ds_read_b128 v[218:221], v175 offset:4096
	ds_read_b128 v[222:225], v175 offset:5120
	ds_read_b128 v[226:229], v175 offset:6144
	ds_read_b128 v[230:233], v175 offset:7168
	global_load_lds_dwordx4 v[162:163], off
	v_lshl_add_u64 v[162:163], s[8:9], 0, v[152:153]
	s_add_i32 m0, s41, 0xe000
	s_nop 0
	global_load_lds_dwordx4 v[162:163], off
	s_waitcnt vmcnt(8)
	s_waitcnt lgkmcnt(0)
	s_setprio 1
	s_waitcnt lgkmcnt(0)
	s_barrier
	v_mfma_f32_16x16x32_bf16 v[124:127], v[128:131], v[202:205], v[124:127]
	v_mfma_f32_16x16x32_bf16 v[120:123], v[178:181], v[202:205], v[120:123]
	v_mfma_f32_16x16x32_bf16 v[108:111], v[128:131], v[210:213], v[108:111]
	v_mfma_f32_16x16x32_bf16 v[104:107], v[178:181], v[210:213], v[104:107]
	v_mfma_f32_16x16x32_bf16 v[92:95], v[128:131], v[218:221], v[92:95]
	v_mfma_f32_16x16x32_bf16 v[88:91], v[178:181], v[218:221], v[88:91]
	v_mfma_f32_16x16x32_bf16 v[76:79], v[128:131], v[226:229], v[76:79]
	v_mfma_f32_16x16x32_bf16 v[72:75], v[178:181], v[226:229], v[72:75]
	v_mfma_f32_16x16x32_bf16 v[124:127], v[158:161], v[206:209], v[124:127]
	v_mfma_f32_16x16x32_bf16 v[120:123], v[182:185], v[206:209], v[120:123]
	v_mfma_f32_16x16x32_bf16 v[108:111], v[158:161], v[214:217], v[108:111]
	v_mfma_f32_16x16x32_bf16 v[104:107], v[182:185], v[214:217], v[104:107]
	v_mfma_f32_16x16x32_bf16 v[92:95], v[158:161], v[222:225], v[92:95]
	v_mfma_f32_16x16x32_bf16 v[88:91], v[182:185], v[222:225], v[88:91]
	v_mfma_f32_16x16x32_bf16 v[76:79], v[158:161], v[230:233], v[76:79]
	v_mfma_f32_16x16x32_bf16 v[72:75], v[182:185], v[230:233], v[72:75]
	s_setprio 0
	s_setprio 1
	s_cmp_eq_u32 s52, 12
	s_cbranch_scc1 .Lp2_skip0
	v_mfma_f32_16x16x32_bf16 v[116:119], v[186:189], v[202:205], v[116:119]
	v_mfma_f32_16x16x32_bf16 v[112:115], v[194:197], v[202:205], v[112:115]
	v_mfma_f32_16x16x32_bf16 v[100:103], v[186:189], v[210:213], v[100:103]
	v_mfma_f32_16x16x32_bf16 v[96:99], v[194:197], v[210:213], v[96:99]
	v_mfma_f32_16x16x32_bf16 v[84:87], v[186:189], v[218:221], v[84:87]
	v_mfma_f32_16x16x32_bf16 v[80:83], v[194:197], v[218:221], v[80:83]
	v_mfma_f32_16x16x32_bf16 v[68:71], v[186:189], v[226:229], v[68:71]
	v_mfma_f32_16x16x32_bf16 v[64:67], v[194:197], v[226:229], v[64:67]
	v_mfma_f32_16x16x32_bf16 v[116:119], v[190:193], v[206:209], v[116:119]
	v_mfma_f32_16x16x32_bf16 v[112:115], v[198:201], v[206:209], v[112:115]
	v_mfma_f32_16x16x32_bf16 v[100:103], v[190:193], v[214:217], v[100:103]
	v_mfma_f32_16x16x32_bf16 v[96:99], v[198:201], v[214:217], v[96:99]
	v_mfma_f32_16x16x32_bf16 v[84:87], v[190:193], v[222:225], v[84:87]
	v_mfma_f32_16x16x32_bf16 v[80:83], v[198:201], v[222:225], v[80:83]
	v_mfma_f32_16x16x32_bf16 v[68:71], v[190:193], v[230:233], v[68:71]
	v_mfma_f32_16x16x32_bf16 v[64:67], v[198:201], v[230:233], v[64:67]
.Lp2_skip0:
	s_barrier
	s_setprio 0
	s_add_i32 s16, s51, s33
	v_lshl_add_u64 v[162:163], s[26:27], 0, v[134:135]
	s_mov_b32 m0, s16
	ds_read_b128 v[202:205], v175 offset:16384
	ds_read_b128 v[206:209], v175 offset:17408
	ds_read_b128 v[210:213], v175 offset:18432
	ds_read_b128 v[214:217], v175 offset:19456
	ds_read_b128 v[218:221], v175 offset:20480
	ds_read_b128 v[222:225], v175 offset:21504
	ds_read_b128 v[226:229], v175 offset:22528
	ds_read_b128 v[230:233], v175 offset:23552
	global_load_lds_dwordx4 v[162:163], off
	s_add_i32 m0, s16, 0x2000
	s_add_u32 s54, s26, 0x80000
	v_lshl_add_u64 v[234:235], s[26:27], 0, v[138:139]
	s_addc_u32 s55, s27, 0
	s_add_i32 s16, s20, s33
	global_load_lds_dwordx4 v[234:235], off
	v_lshl_add_u64 v[236:237], s[54:55], 0, v[134:135]
	s_mov_b32 m0, s16
	v_lshl_add_u64 v[238:239], s[30:31], 0, v[136:137]
	global_load_lds_dwordx4 v[236:237], off
	v_lshl_add_u64 v[236:237], s[54:55], 0, v[138:139]
	s_add_i32 m0, s16, 0x2000
	s_nop 0
	global_load_lds_dwordx4 v[236:237], off
	v_lshl_add_u64 v[236:237], s[30:31], 0, v[132:133]
	s_mov_b32 m0, s41
	s_nop 0
	global_load_lds_dwordx4 v[236:237], off
	s_mov_b32 m0, s43
	s_nop 0
	global_load_lds_dwordx4 v[238:239], off
	s_waitcnt vmcnt(8)
	s_waitcnt lgkmcnt(0)
	s_setprio 1
	s_waitcnt lgkmcnt(0)
	s_barrier
	v_mfma_f32_16x16x32_bf16 v[60:63], v[128:131], v[202:205], v[60:63]
	v_mfma_f32_16x16x32_bf16 v[56:59], v[178:181], v[202:205], v[56:59]
	v_mfma_f32_16x16x32_bf16 v[44:47], v[128:131], v[210:213], v[44:47]
	v_mfma_f32_16x16x32_bf16 v[40:43], v[178:181], v[210:213], v[40:43]
	v_mfma_f32_16x16x32_bf16 v[28:31], v[128:131], v[218:221], v[28:31]
	v_mfma_f32_16x16x32_bf16 v[24:27], v[178:181], v[218:221], v[24:27]
	v_mfma_f32_16x16x32_bf16 v[12:15], v[128:131], v[226:229], v[12:15]
	v_mfma_f32_16x16x32_bf16 v[8:11], v[178:181], v[226:229], v[8:11]
	v_mfma_f32_16x16x32_bf16 v[60:63], v[158:161], v[206:209], v[60:63]
	v_mfma_f32_16x16x32_bf16 v[56:59], v[182:185], v[206:209], v[56:59]
	v_mfma_f32_16x16x32_bf16 v[44:47], v[158:161], v[214:217], v[44:47]
	v_mfma_f32_16x16x32_bf16 v[40:43], v[182:185], v[214:217], v[40:43]
	v_mfma_f32_16x16x32_bf16 v[28:31], v[158:161], v[222:225], v[28:31]
	v_mfma_f32_16x16x32_bf16 v[24:27], v[182:185], v[222:225], v[24:27]
	v_mfma_f32_16x16x32_bf16 v[12:15], v[158:161], v[230:233], v[12:15]
	v_mfma_f32_16x16x32_bf16 v[8:11], v[182:185], v[230:233], v[8:11]
	s_setprio 0
	s_setprio 1
	s_cmp_eq_u32 s52, 12
	s_cbranch_scc1 .Lp2_skip1
; #define PG8_STAGE(bufoff, gbase, voff) do { _Pragma("unroll") for (int _i = 0; _i < 2; ++_i) \
;         __builtin_amdgcn_global_load_lds((const unsigned*)((const char*)(gbase) + (voff)[_i]), (LAS unsigned*)(lds + (bufoff) + ldsw + _i * 8192), 16, 0, 0); } while (0)
; #define PG8_LDA(dst, b, h) do { _Pragma("unroll") for (int m = 0; m < 4; ++m) _Pragma("unroll") for (int k = 0; k < 2; ++k) dst[m][k] = *(const LAS bf16x8*)(lds + PG8_SA(b, h) + aoff + m * 2048 + k * 1024); } while (0)
; #define PG8_LDB(dst, b, h) do { _Pragma("unroll") for (int n = 0; n < 2; ++n) _Pragma("unroll") for (int k = 0; k < 2; ++k) dst[n][k] = *(const LAS bf16x8*)(lds + PG8_SB(b, h) + boff + n * 2048 + k * 1024); } while (0)
; #define PG8_MMA(ai, bj, At, Bt) do { __builtin_amdgcn_s_setprio(1); _Pragma("unroll") for (int m = 0; m < 4; ++m) _Pragma("unroll") for (int n = 0; n < 2; ++n) _Pragma("unroll") for (int k = 0; k < 2; ++k) \
;         acc[ai][bj][m][n] = __builtin_amdgcn_mfma_f32_16x16x32_bf16(Bt[n][k], At[m][k], acc[ai][bj][m][n], 0, 0, 0); __builtin_amdgcn_s_setprio(0); } while (0)
; #define PG8_WAIT_V(n) asm volatile("s_waitcnt vmcnt(" #n ")" ::: "memory")
; #define PG8_WAIT_L(n) asm volatile("s_waitcnt lgkmcnt(" #n ")" ::: "memory")
; #define PG8_BAR __builtin_amdgcn_s_barrier()
; #define PG8_SCHED __builtin_amdgcn_sched_barrier(0)
; template <class Epi, class Sched>
; __device__ __forceinline__ void gemm_phase(LAS unsigned char* lds, const Gemm g, const Sched& S, const Epi& E, const int tid) {
;     ...
;             PG8_WAIT_V(8); PG8_WAIT_L(0); PG8_BAR; PG8_MMA(1, 0, At, B0); PG8_MMA(1, 1, At, B1); PG8_BAR; PG8_SCHED;
;             PG8_LDB(B0, 1, 0); PG8_LDB(B1, 1, 1); PG8_SCHED; PG8_LDA(At, 1, 0); PG8_STAGE(PG8_SA(0, 1), a2 + hstepA, voffA);
;             PG8_WAIT_V(8); PG8_WAIT_L(0); PG8_BAR; PG8_MMA(0, 0, At, B0); PG8_MMA(0, 1, At, B1); PG8_BAR; PG8_SCHED;
	v_mfma_f32_16x16x32_bf16 v[52:55], v[186:189], v[202:205], v[52:55]
	v_mfma_f32_16x16x32_bf16 v[48:51], v[194:197], v[202:205], v[48:51]
	v_mfma_f32_16x16x32_bf16 v[36:39], v[186:189], v[210:213], v[36:39]
	v_mfma_f32_16x16x32_bf16 v[32:35], v[194:197], v[210:213], v[32:35]
	v_mfma_f32_16x16x32_bf16 v[20:23], v[186:189], v[218:221], v[20:23]
	v_mfma_f32_16x16x32_bf16 v[16:19], v[194:197], v[218:221], v[16:19]
	v_mfma_f32_16x16x32_bf16 v[4:7], v[186:189], v[226:229], v[4:7]
	v_mfma_f32_16x16x32_bf16 v[0:3], v[194:197], v[226:229], v[0:3]
	v_mfma_f32_16x16x32_bf16 v[52:55], v[190:193], v[206:209], v[52:55]
	v_mfma_f32_16x16x32_bf16 v[48:51], v[198:201], v[206:209], v[48:51]
	v_mfma_f32_16x16x32_bf16 v[36:39], v[190:193], v[214:217], v[36:39]
	v_mfma_f32_16x16x32_bf16 v[32:35], v[198:201], v[214:217], v[32:35]
	v_mfma_f32_16x16x32_bf16 v[20:23], v[190:193], v[222:225], v[20:23]
	v_mfma_f32_16x16x32_bf16 v[16:19], v[198:201], v[222:225], v[16:19]
	v_mfma_f32_16x16x32_bf16 v[4:7], v[190:193], v[230:233], v[4:7]
	v_mfma_f32_16x16x32_bf16 v[0:3], v[198:201], v[230:233], v[0:3]
.Lp2_skip1:
	s_barrier
	s_setprio 0
	s_add_i32 s16, 0, 0x18000
	v_add_u32_e32 v140, s16, v164
	s_add_i32 s17, 0, 0x1c000
	ds_read_b128 v[128:131], v140
	ds_read_b128 v[158:161], v140 offset:1024
	ds_read_b128 v[178:181], v140 offset:2048
	ds_read_b128 v[182:185], v140 offset:3072
	v_add_u32_e32 v140, s17, v164
	ds_read_b128 v[186:189], v140
	ds_read_b128 v[190:193], v140 offset:1024
	ds_read_b128 v[194:197], v140 offset:2048
	ds_read_b128 v[198:201], v140 offset:3072
	s_add_u32 s30, s30, 0x80000
	s_addc_u32 s31, s31, 0
	s_mov_b32 m0, s53
	v_lshl_add_u64 v[240:241], s[30:31], 0, v[132:133]
	ds_read_b128 v[202:205], v175 offset:32768
	ds_read_b128 v[206:209], v175 offset:33792
	ds_read_b128 v[210:213], v175 offset:34816
	ds_read_b128 v[214:217], v175 offset:35840
	ds_read_b128 v[218:221], v175 offset:36864
	ds_read_b128 v[222:225], v175 offset:37888
	ds_read_b128 v[226:229], v175 offset:38912
	ds_read_b128 v[230:233], v175 offset:39936
	global_load_lds_dwordx4 v[240:241], off
	v_lshl_add_u64 v[240:241], s[30:31], 0, v[136:137]
	s_mov_b32 m0, s74
	s_nop 0
	global_load_lds_dwordx4 v[240:241], off
	s_waitcnt vmcnt(8)
	s_waitcnt lgkmcnt(0)
	s_setprio 1
	s_waitcnt lgkmcnt(0)
	s_barrier
	v_mfma_f32_16x16x32_bf16 v[124:127], v[128:131], v[202:205], v[124:127]
	v_mfma_f32_16x16x32_bf16 v[120:123], v[178:181], v[202:205], v[120:123]
	v_mfma_f32_16x16x32_bf16 v[108:111], v[128:131], v[210:213], v[108:111]
	v_mfma_f32_16x16x32_bf16 v[104:107], v[178:181], v[210:213], v[104:107]
	v_mfma_f32_16x16x32_bf16 v[92:95], v[128:131], v[218:221], v[92:95]
	v_mfma_f32_16x16x32_bf16 v[88:91], v[178:181], v[218:221], v[88:91]
	v_mfma_f32_16x16x32_bf16 v[76:79], v[128:131], v[226:229], v[76:79]
	v_mfma_f32_16x16x32_bf16 v[72:75], v[178:181], v[226:229], v[72:75]
	v_mfma_f32_16x16x32_bf16 v[124:127], v[158:161], v[206:209], v[124:127]
	v_mfma_f32_16x16x32_bf16 v[120:123], v[182:185], v[206:209], v[120:123]
	v_mfma_f32_16x16x32_bf16 v[108:111], v[158:161], v[214:217], v[108:111]
	v_mfma_f32_16x16x32_bf16 v[104:107], v[182:185], v[214:217], v[104:107]
	v_mfma_f32_16x16x32_bf16 v[92:95], v[158:161], v[222:225], v[92:95]
	v_mfma_f32_16x16x32_bf16 v[88:91], v[182:185], v[222:225], v[88:91]
	v_mfma_f32_16x16x32_bf16 v[76:79], v[158:161], v[230:233], v[76:79]
	v_mfma_f32_16x16x32_bf16 v[72:75], v[182:185], v[230:233], v[72:75]
	s_setprio 0
	s_setprio 1
	s_cmp_eq_u32 s52, 12
	s_cbranch_scc1 .Lp2_skip2
	v_mfma_f32_16x16x32_bf16 v[116:119], v[186:189], v[202:205], v[116:119]
	v_mfma_f32_16x16x32_bf16 v[112:115], v[194:197], v[202:205], v[112:115]
	v_mfma_f32_16x16x32_bf16 v[100:103], v[186:189], v[210:213], v[100:103]
	v_mfma_f32_16x16x32_bf16 v[96:99], v[194:197], v[210:213], v[96:99]
	v_mfma_f32_16x16x32_bf16 v[84:87], v[186:189], v[218:221], v[84:87]
	v_mfma_f32_16x16x32_bf16 v[80:83], v[194:197], v[218:221], v[80:83]
	v_mfma_f32_16x16x32_bf16 v[68:71], v[186:189], v[226:229], v[68:71]
	v_mfma_f32_16x16x32_bf16 v[64:67], v[194:197], v[226:229], v[64:67]
	v_mfma_f32_16x16x32_bf16 v[116:119], v[190:193], v[206:209], v[116:119]
	v_mfma_f32_16x16x32_bf16 v[112:115], v[198:201], v[206:209], v[112:115]
	v_mfma_f32_16x16x32_bf16 v[100:103], v[190:193], v[214:217], v[100:103]
	v_mfma_f32_16x16x32_bf16 v[96:99], v[198:201], v[214:217], v[96:99]
	v_mfma_f32_16x16x32_bf16 v[84:87], v[190:193], v[222:225], v[84:87]
	v_mfma_f32_16x16x32_bf16 v[80:83], v[198:201], v[222:225], v[80:83]
	v_mfma_f32_16x16x32_bf16 v[68:71], v[190:193], v[230:233], v[68:71]
	v_mfma_f32_16x16x32_bf16 v[64:67], v[198:201], v[230:233], v[64:67]
; #define PG8_STAGE(bufoff, gbase, voff) do { _Pragma("unroll") for (int _i = 0; _i < 2; ++_i) \
;         __builtin_amdgcn_global_load_lds((const unsigned*)((const char*)(gbase) + (voff)[_i]), (LAS unsigned*)(lds + (bufoff) + ldsw + _i * 8192), 16, 0, 0); } while (0)
; #define PG8_LDA(dst, b, h) do { _Pragma("unroll") for (int m = 0; m < 4; ++m) _Pragma("unroll") for (int k = 0; k < 2; ++k) dst[m][k] = *(const LAS bf16x8*)(lds + PG8_SA(b, h) + aoff + m * 2048 + k * 1024); } while (0)
; #define PG8_MMA(ai, bj, At, Bt) do { __builtin_amdgcn_s_setprio(1); _Pragma("unroll") for (int m = 0; m < 4; ++m) _Pragma("unroll") for (int n = 0; n < 2; ++n) _Pragma("unroll") for (int k = 0; k < 2; ++k) \
;         acc[ai][bj][m][n] = __builtin_amdgcn_mfma_f32_16x16x32_bf16(Bt[n][k], At[m][k], acc[ai][bj][m][n], 0, 0, 0); __builtin_amdgcn_s_setprio(0); } while (0)
; #define PG8_WAIT_V(n) asm volatile("s_waitcnt vmcnt(" #n ")" ::: "memory")
; #define PG8_WAIT_L(n) asm volatile("s_waitcnt lgkmcnt(" #n ")" ::: "memory")
; #define PG8_BAR __builtin_amdgcn_s_barrier()
; #define PG8_SCHED __builtin_amdgcn_sched_barrier(0)
; template <class Epi, class Sched>
; __device__ __forceinline__ void gemm_phase(LAS unsigned char* lds, const Gemm g, const Sched& S, const Epi& E, const int tid) {
;     ...
;         for (int t = 0; t < nt; t += 2) {
;             const bool last = (t == nt - 2);
;             const char* a1 = cA + (size_t)(t + 1) * kstepA;
;             const char* a2 = last ? nA : cA + (size_t)(t + 2) * kstepA; const char* b2 = last ? nB : cB + (size_t)(t + 2) * kstep;
;     ...
;             PG8_LDA(At, 1, 1); PG8_STAGE(PG8_SB(1, 0), b3, voffB); PG8_STAGE(PG8_SB(1, 1), b3 + hstepB, voffB); PG8_STAGE(PG8_SA(1, 0), a3, voffA);
;             PG8_WAIT_V(8); PG8_WAIT_L(0); PG8_BAR; PG8_MMA(1, 0, At, B0); PG8_MMA(1, 1, At, B1); PG8_BAR; PG8_SCHED;
;         }
.Lp2_skip2:
	s_barrier
	s_setprio 0
	s_add_i32 s16, s16, s33
	v_lshl_add_u64 v[162:163], v[162:163], 0, s[78:79]
	s_mov_b32 m0, s16
	ds_read_b128 v[202:205], v175 offset:49152
	ds_read_b128 v[206:209], v175 offset:50176
	ds_read_b128 v[210:213], v175 offset:51200
	ds_read_b128 v[214:217], v175 offset:52224
	ds_read_b128 v[218:221], v175 offset:53248
	ds_read_b128 v[222:225], v175 offset:54272
	ds_read_b128 v[226:229], v175 offset:55296
	ds_read_b128 v[230:233], v175 offset:56320
	global_load_lds_dwordx4 v[162:163], off
	s_add_i32 m0, s16, 0x2000
	s_add_u32 s26, s26, 0x80080
	v_lshl_add_u64 v[162:163], v[234:235], 0, s[78:79]
	s_addc_u32 s27, s27, 0
	s_add_i32 s16, s17, s33
	global_load_lds_dwordx4 v[162:163], off
	v_lshl_add_u64 v[162:163], s[26:27], 0, v[134:135]
	s_mov_b32 m0, s16
	s_nop 0
	global_load_lds_dwordx4 v[162:163], off
	v_lshl_add_u64 v[162:163], s[26:27], 0, v[138:139]
	s_add_i32 m0, s16, 0x2000
	s_nop 0
	global_load_lds_dwordx4 v[162:163], off
	v_lshl_add_u64 v[162:163], v[236:237], 0, s[78:79]
	s_mov_b32 m0, s95
	s_nop 0
	global_load_lds_dwordx4 v[162:163], off
	v_lshl_add_u64 v[162:163], v[238:239], 0, s[78:79]
	s_mov_b32 m0, s0
	s_nop 0
	global_load_lds_dwordx4 v[162:163], off
	s_waitcnt vmcnt(8)
	s_waitcnt lgkmcnt(0)
	s_setprio 1
	s_waitcnt lgkmcnt(0)
	s_barrier
	v_mfma_f32_16x16x32_bf16 v[60:63], v[128:131], v[202:205], v[60:63]
	v_mfma_f32_16x16x32_bf16 v[56:59], v[178:181], v[202:205], v[56:59]
	v_mfma_f32_16x16x32_bf16 v[44:47], v[128:131], v[210:213], v[44:47]
	v_mfma_f32_16x16x32_bf16 v[40:43], v[178:181], v[210:213], v[40:43]
	v_mfma_f32_16x16x32_bf16 v[28:31], v[128:131], v[218:221], v[28:31]
	v_mfma_f32_16x16x32_bf16 v[24:27], v[178:181], v[218:221], v[24:27]
	v_mfma_f32_16x16x32_bf16 v[12:15], v[128:131], v[226:229], v[12:15]
	v_mfma_f32_16x16x32_bf16 v[8:11], v[178:181], v[226:229], v[8:11]
	v_mfma_f32_16x16x32_bf16 v[60:63], v[158:161], v[206:209], v[60:63]
	v_mfma_f32_16x16x32_bf16 v[56:59], v[182:185], v[206:209], v[56:59]
	v_mfma_f32_16x16x32_bf16 v[44:47], v[158:161], v[214:217], v[44:47]
	v_mfma_f32_16x16x32_bf16 v[40:43], v[182:185], v[214:217], v[40:43]
	v_mfma_f32_16x16x32_bf16 v[28:31], v[158:161], v[222:225], v[28:31]
	v_mfma_f32_16x16x32_bf16 v[24:27], v[182:185], v[222:225], v[24:27]
	v_mfma_f32_16x16x32_bf16 v[12:15], v[158:161], v[230:233], v[12:15]
	v_mfma_f32_16x16x32_bf16 v[8:11], v[182:185], v[230:233], v[8:11]
	s_setprio 0
	s_setprio 1
	s_cmp_eq_u32 s52, 12
	s_cbranch_scc1 .Lp2_skip3
	v_mfma_f32_16x16x32_bf16 v[52:55], v[186:189], v[202:205], v[52:55]
	v_mfma_f32_16x16x32_bf16 v[48:51], v[194:197], v[202:205], v[48:51]
	v_mfma_f32_16x16x32_bf16 v[36:39], v[186:189], v[210:213], v[36:39]
	v_mfma_f32_16x16x32_bf16 v[32:35], v[194:197], v[210:213], v[32:35]
	v_mfma_f32_16x16x32_bf16 v[20:23], v[186:189], v[218:221], v[20:23]
	v_mfma_f32_16x16x32_bf16 v[16:19], v[194:197], v[218:221], v[16:19]
	v_mfma_f32_16x16x32_bf16 v[4:7], v[186:189], v[226:229], v[4:7]
	v_mfma_f32_16x16x32_bf16 v[0:3], v[194:197], v[226:229], v[0:3]
	v_mfma_f32_16x16x32_bf16 v[52:55], v[190:193], v[206:209], v[52:55]
	v_mfma_f32_16x16x32_bf16 v[48:51], v[198:201], v[206:209], v[48:51]
	v_mfma_f32_16x16x32_bf16 v[36:39], v[190:193], v[214:217], v[36:39]
	v_mfma_f32_16x16x32_bf16 v[32:35], v[198:201], v[214:217], v[32:35]
	v_mfma_f32_16x16x32_bf16 v[20:23], v[190:193], v[222:225], v[20:23]
	v_mfma_f32_16x16x32_bf16 v[16:19], v[198:201], v[222:225], v[16:19]
	v_mfma_f32_16x16x32_bf16 v[4:7], v[190:193], v[230:233], v[4:7]
	v_mfma_f32_16x16x32_bf16 v[0:3], v[198:201], v[230:233], v[0:3]
.Lp2_skip3:
	s_barrier
	s_setprio 0
	s_add_i32 s48, s48, 2
	s_add_u32 s8, s8, 0x100
	s_addc_u32 s9, s9, 0
	s_add_u32 s38, s38, 0x100
	s_addc_u32 s39, s39, 0
	s_cmp_gt_u32 s48, 29
	s_cbranch_scc0 .LBB0_285
	s_and_b64 vcc, exec, s[90:91]
	s_cbranch_vccz .LBB0_288
	s_barrier

; #define PG8_STAGE(bufoff, gbase, voff) do { _Pragma("unroll") for (int _i = 0; _i < 2; ++_i) \
;         __builtin_amdgcn_global_load_lds((const unsigned*)((const char*)(gbase) + (voff)[_i]), (LAS unsigned*)(lds + (bufoff) + ldsw + _i * 8192), 16, 0, 0); } while (0)
; #define PG8_LDA(dst, b, h) do { _Pragma("unroll") for (int m = 0; m < 4; ++m) _Pragma("unroll") for (int k = 0; k < 2; ++k) dst[m][k] = *(const LAS bf16x8*)(lds + PG8_SA(b, h) + aoff + m * 2048 + k * 1024); } while (0)
; #define PG8_LDB(dst, b, h) do { _Pragma("unroll") for (int n = 0; n < 2; ++n) _Pragma("unroll") for (int k = 0; k < 2; ++k) dst[n][k] = *(const LAS bf16x8*)(lds + PG8_SB(b, h) + boff + n * 2048 + k * 1024); } while (0)
; #define PG8_MMA(ai, bj, At, Bt) do { __builtin_amdgcn_s_setprio(1); _Pragma("unroll") for (int m = 0; m < 4; ++m) _Pragma("unroll") for (int n = 0; n < 2; ++n) _Pragma("unroll") for (int k = 0; k < 2; ++k) \
;         acc[ai][bj][m][n] = __builtin_amdgcn_mfma_f32_16x16x32_bf16(Bt[n][k], At[m][k], acc[ai][bj][m][n], 0, 0, 0); __builtin_amdgcn_s_setprio(0); } while (0)
; #define PG8_WAIT_V(n) asm volatile("s_waitcnt vmcnt(" #n ")" ::: "memory")
; #define PG8_WAIT_L(n) asm volatile("s_waitcnt lgkmcnt(" #n ")" ::: "memory")
; #define PG8_BAR __builtin_amdgcn_s_barrier()
; template <class Epi, class Sched>
; __device__ __forceinline__ void gemm_phase(LAS unsigned char* lds, const Gemm g, const Sched& S, const Epi& E, const int tid) {
;     ...
;             const bool last = (t == nt - 2);
;             const char* a1 = cA + (size_t)(t + 1) * kstepA;
;             const char* a2 = last ? nA : cA + (size_t)(t + 2) * kstepA; const char* b2 = last ? nB : cB + (size_t)(t + 2) * kstep;
;             const char* a3 = a2 + kstepA; const char* b3 = b2 + kstep;
;             if constexpr (Epi::HAS_MID) { if (t == g.tmid) E.mid(acc, cur, ui, wr, wc, fr, fq); }
;             PG8_LDB(B0, 0, 0); PG8_LDB(B1, 0, 1); PG8_SCHED; PG8_LDA(At, 0, 0); PG8_STAGE(PG8_SA(1, 1), a1 + hstepA, voffA);
;             PG8_WAIT_V(8); PG8_WAIT_L(0); PG8_BAR; PG8_MMA(0, 0, At, B0); PG8_MMA(0, 1, At, B1); PG8_BAR; PG8_SCHED;
;             PG8_LDA(At, 0, 1); PG8_STAGE(PG8_SB(0, 0), b2, voffB); PG8_STAGE(PG8_SB(0, 1), b2 + hstepB, voffB); PG8_STAGE(PG8_SA(0, 0), a2, voffA);
;             PG8_WAIT_V(8); PG8_WAIT_L(0); PG8_BAR; PG8_MMA(1, 0, At, B0); PG8_MMA(1, 1, At, B1); PG8_BAR; PG8_SCHED;
.LBB0_714:
	ds_read_b128 v[152:155], v148
	ds_read_b128 v[156:159], v148 offset:1024
	ds_read_b128 v[160:163], v148 offset:2048
	ds_read_b128 v[164:167], v148 offset:3072
	ds_read_b128 v[168:171], v149
	ds_read_b128 v[172:175], v149 offset:1024
	ds_read_b128 v[176:179], v149 offset:2048
	ds_read_b128 v[180:183], v149 offset:3072
	s_add_u32 s36, s38, 0x100
	s_addc_u32 s37, s39, 0
	s_cmp_eq_u32 s65, 4
	s_cselect_b32 s59, s29, s37
	s_cselect_b32 s58, s28, s36
	s_cselect_b32 s49, s7, s27
	s_cselect_b32 s48, s18, s19
	v_lshl_add_u64 v[216:217], s[38:39], 0, v[138:139]
	s_add_i32 m0, s50, 0xc000
	ds_read_b128 v[184:187], v150
	ds_read_b128 v[188:191], v150 offset:1024
	ds_read_b128 v[192:195], v150 offset:2048
	ds_read_b128 v[196:199], v150 offset:3072
	ds_read_b128 v[200:203], v150 offset:4096
	ds_read_b128 v[204:207], v150 offset:5120
	ds_read_b128 v[208:211], v150 offset:6144
	ds_read_b128 v[212:215], v150 offset:7168
	global_load_lds_dwordx4 v[216:217], off
	v_lshl_add_u64 v[216:217], s[38:39], 0, v[140:141]
	s_add_i32 m0, s50, 0xe000
	s_nop 0
	global_load_lds_dwordx4 v[216:217], off
	s_waitcnt vmcnt(8)
	s_waitcnt lgkmcnt(0)
	s_setprio 1
	s_waitcnt lgkmcnt(0)
	s_barrier
	v_mfma_f32_16x16x32_bf16 v[124:127], v[152:155], v[184:187], v[124:127]
	v_mfma_f32_16x16x32_bf16 v[120:123], v[160:163], v[184:187], v[120:123]
	v_mfma_f32_16x16x32_bf16 v[116:119], v[152:155], v[192:195], v[116:119]
	v_mfma_f32_16x16x32_bf16 v[112:115], v[160:163], v[192:195], v[112:115]
	v_mfma_f32_16x16x32_bf16 v[104:107], v[152:155], v[200:203], v[104:107]
	v_mfma_f32_16x16x32_bf16 v[96:99], v[160:163], v[200:203], v[96:99]
	v_mfma_f32_16x16x32_bf16 v[88:91], v[152:155], v[208:211], v[88:91]
	v_mfma_f32_16x16x32_bf16 v[80:83], v[160:163], v[208:211], v[80:83]
	v_mfma_f32_16x16x32_bf16 v[124:127], v[156:159], v[188:191], v[124:127]
	v_mfma_f32_16x16x32_bf16 v[120:123], v[164:167], v[188:191], v[120:123]
	v_mfma_f32_16x16x32_bf16 v[116:119], v[156:159], v[196:199], v[116:119]
	v_mfma_f32_16x16x32_bf16 v[112:115], v[164:167], v[196:199], v[112:115]
	v_mfma_f32_16x16x32_bf16 v[104:107], v[156:159], v[204:207], v[104:107]
	v_mfma_f32_16x16x32_bf16 v[96:99], v[164:167], v[204:207], v[96:99]
	v_mfma_f32_16x16x32_bf16 v[88:91], v[156:159], v[212:215], v[88:91]
	v_mfma_f32_16x16x32_bf16 v[80:83], v[164:167], v[212:215], v[80:83]
	s_setprio 0
	s_setprio 1
	v_mfma_f32_16x16x32_bf16 v[108:111], v[168:171], v[184:187], v[108:111]
	v_mfma_f32_16x16x32_bf16 v[100:103], v[176:179], v[184:187], v[100:103]
	v_mfma_f32_16x16x32_bf16 v[92:95], v[168:171], v[192:195], v[92:95]
	v_mfma_f32_16x16x32_bf16 v[84:87], v[176:179], v[192:195], v[84:87]
	v_mfma_f32_16x16x32_bf16 v[76:79], v[168:171], v[200:203], v[76:79]
	v_mfma_f32_16x16x32_bf16 v[72:75], v[176:179], v[200:203], v[72:75]
	v_mfma_f32_16x16x32_bf16 v[68:71], v[168:171], v[208:211], v[68:71]
	v_mfma_f32_16x16x32_bf16 v[64:67], v[176:179], v[208:211], v[64:67]
	v_mfma_f32_16x16x32_bf16 v[108:111], v[172:175], v[188:191], v[108:111]
	v_mfma_f32_16x16x32_bf16 v[100:103], v[180:183], v[188:191], v[100:103]
	v_mfma_f32_16x16x32_bf16 v[92:95], v[172:175], v[196:199], v[92:95]
	v_mfma_f32_16x16x32_bf16 v[84:87], v[180:183], v[196:199], v[84:87]
	v_mfma_f32_16x16x32_bf16 v[76:79], v[172:175], v[204:207], v[76:79]
	v_mfma_f32_16x16x32_bf16 v[72:75], v[180:183], v[204:207], v[72:75]
	v_mfma_f32_16x16x32_bf16 v[68:71], v[172:175], v[212:215], v[68:71]
	v_mfma_f32_16x16x32_bf16 v[64:67], v[180:183], v[212:215], v[64:67]
	s_barrier
	s_setprio 0
	s_add_i32 s16, s62, s41
	v_lshl_add_u64 v[216:217], s[48:49], 0, v[132:133]
	s_mov_b32 m0, s16
	ds_read_b128 v[184:187], v150 offset:16384
	ds_read_b128 v[188:191], v150 offset:17408
	ds_read_b128 v[192:195], v150 offset:18432
	ds_read_b128 v[196:199], v150 offset:19456
	ds_read_b128 v[200:203], v150 offset:20480
	ds_read_b128 v[204:207], v150 offset:21504
	ds_read_b128 v[208:211], v150 offset:22528
	ds_read_b128 v[212:215], v150 offset:23552
	global_load_lds_dwordx4 v[216:217], off
	s_add_i32 m0, s16, 0x2000
	s_add_u32 s38, s48, 0x20000
	v_lshl_add_u64 v[218:219], s[48:49], 0, v[128:129]
	s_addc_u32 s39, s49, 0
	s_add_i32 s16, s63, s41
	global_load_lds_dwordx4 v[218:219], off
	v_lshl_add_u64 v[220:221], s[38:39], 0, v[132:133]
	s_mov_b32 m0, s16
	v_lshl_add_u64 v[222:223], s[58:59], 0, v[130:131]
	global_load_lds_dwordx4 v[220:221], off
	v_lshl_add_u64 v[220:221], s[38:39], 0, v[128:129]
	s_add_i32 m0, s16, 0x2000
	s_nop 0
	global_load_lds_dwordx4 v[220:221], off
	v_lshl_add_u64 v[220:221], s[58:59], 0, v[134:135]
	s_mov_b32 m0, s50
	s_nop 0
	global_load_lds_dwordx4 v[220:221], off
	s_mov_b32 m0, s52
	s_nop 0
	global_load_lds_dwordx4 v[222:223], off
	s_waitcnt vmcnt(8)
	s_waitcnt lgkmcnt(0)
	s_setprio 1
	s_waitcnt lgkmcnt(0)
	s_barrier
; #define PG8_STAGE(bufoff, gbase, voff) do { _Pragma("unroll") for (int _i = 0; _i < 2; ++_i) \
;         __builtin_amdgcn_global_load_lds((const unsigned*)((const char*)(gbase) + (voff)[_i]), (LAS unsigned*)(lds + (bufoff) + ldsw + _i * 8192), 16, 0, 0); } while (0)
; #define PG8_LDA(dst, b, h) do { _Pragma("unroll") for (int m = 0; m < 4; ++m) _Pragma("unroll") for (int k = 0; k < 2; ++k) dst[m][k] = *(const LAS bf16x8*)(lds + PG8_SA(b, h) + aoff + m * 2048 + k * 1024); } while (0)
; #define PG8_LDB(dst, b, h) do { _Pragma("unroll") for (int n = 0; n < 2; ++n) _Pragma("unroll") for (int k = 0; k < 2; ++k) dst[n][k] = *(const LAS bf16x8*)(lds + PG8_SB(b, h) + boff + n * 2048 + k * 1024); } while (0)
; #define PG8_MMA(ai, bj, At, Bt) do { __builtin_amdgcn_s_setprio(1); _Pragma("unroll") for (int m = 0; m < 4; ++m) _Pragma("unroll") for (int n = 0; n < 2; ++n) _Pragma("unroll") for (int k = 0; k < 2; ++k) \
;         acc[ai][bj][m][n] = __builtin_amdgcn_mfma_f32_16x16x32_bf16(Bt[n][k], At[m][k], acc[ai][bj][m][n], 0, 0, 0); __builtin_amdgcn_s_setprio(0); } while (0)
; #define PG8_WAIT_V(n) asm volatile("s_waitcnt vmcnt(" #n ")" ::: "memory")
; #define PG8_WAIT_L(n) asm volatile("s_waitcnt lgkmcnt(" #n ")" ::: "memory")
; #define PG8_BAR __builtin_amdgcn_s_barrier()
; #define PG8_SCHED __builtin_amdgcn_sched_barrier(0)
; template <class Epi, class Sched>
; __device__ __forceinline__ void gemm_phase(LAS unsigned char* lds, const Gemm g, const Sched& S, const Epi& E, const int tid) {
;     ...
;             PG8_WAIT_V(8); PG8_WAIT_L(0); PG8_BAR; PG8_MMA(1, 0, At, B0); PG8_MMA(1, 1, At, B1); PG8_BAR; PG8_SCHED;
;             PG8_LDB(B0, 1, 0); PG8_LDB(B1, 1, 1); PG8_SCHED; PG8_LDA(At, 1, 0); PG8_STAGE(PG8_SA(0, 1), a2 + hstepA, voffA);
;             PG8_WAIT_V(8); PG8_WAIT_L(0); PG8_BAR; PG8_MMA(0, 0, At, B0); PG8_MMA(0, 1, At, B1); PG8_BAR; PG8_SCHED;
	v_mfma_f32_16x16x32_bf16 v[60:63], v[152:155], v[184:187], v[60:63]
	v_mfma_f32_16x16x32_bf16 v[56:59], v[160:163], v[184:187], v[56:59]
	v_mfma_f32_16x16x32_bf16 v[52:55], v[152:155], v[192:195], v[52:55]
	v_mfma_f32_16x16x32_bf16 v[48:51], v[160:163], v[192:195], v[48:51]
	v_mfma_f32_16x16x32_bf16 v[40:43], v[152:155], v[200:203], v[40:43]
	v_mfma_f32_16x16x32_bf16 v[32:35], v[160:163], v[200:203], v[32:35]
	v_mfma_f32_16x16x32_bf16 v[24:27], v[152:155], v[208:211], v[24:27]
	v_mfma_f32_16x16x32_bf16 v[16:19], v[160:163], v[208:211], v[16:19]
	v_mfma_f32_16x16x32_bf16 v[60:63], v[156:159], v[188:191], v[60:63]
	v_mfma_f32_16x16x32_bf16 v[56:59], v[164:167], v[188:191], v[56:59]
	v_mfma_f32_16x16x32_bf16 v[52:55], v[156:159], v[196:199], v[52:55]
	v_mfma_f32_16x16x32_bf16 v[48:51], v[164:167], v[196:199], v[48:51]
	v_mfma_f32_16x16x32_bf16 v[40:43], v[156:159], v[204:207], v[40:43]
	v_mfma_f32_16x16x32_bf16 v[32:35], v[164:167], v[204:207], v[32:35]
	v_mfma_f32_16x16x32_bf16 v[24:27], v[156:159], v[212:215], v[24:27]
	v_mfma_f32_16x16x32_bf16 v[16:19], v[164:167], v[212:215], v[16:19]
	s_setprio 0
	s_setprio 1
	v_mfma_f32_16x16x32_bf16 v[44:47], v[168:171], v[184:187], v[44:47]
	v_mfma_f32_16x16x32_bf16 v[36:39], v[176:179], v[184:187], v[36:39]
	v_mfma_f32_16x16x32_bf16 v[28:31], v[168:171], v[192:195], v[28:31]
	v_mfma_f32_16x16x32_bf16 v[20:23], v[176:179], v[192:195], v[20:23]
	v_mfma_f32_16x16x32_bf16 v[12:15], v[168:171], v[200:203], v[12:15]
	v_mfma_f32_16x16x32_bf16 v[8:11], v[176:179], v[200:203], v[8:11]
	v_mfma_f32_16x16x32_bf16 v[4:7], v[168:171], v[208:211], v[4:7]
	v_mfma_f32_16x16x32_bf16 v[0:3], v[176:179], v[208:211], v[0:3]
	v_mfma_f32_16x16x32_bf16 v[44:47], v[172:175], v[188:191], v[44:47]
	v_mfma_f32_16x16x32_bf16 v[36:39], v[180:183], v[188:191], v[36:39]
	v_mfma_f32_16x16x32_bf16 v[28:31], v[172:175], v[196:199], v[28:31]
	v_mfma_f32_16x16x32_bf16 v[20:23], v[180:183], v[196:199], v[20:23]
	v_mfma_f32_16x16x32_bf16 v[12:15], v[172:175], v[204:207], v[12:15]
	v_mfma_f32_16x16x32_bf16 v[8:11], v[180:183], v[204:207], v[8:11]
	v_mfma_f32_16x16x32_bf16 v[4:7], v[172:175], v[212:215], v[4:7]
	v_mfma_f32_16x16x32_bf16 v[0:3], v[180:183], v[212:215], v[0:3]
	s_barrier
	s_setprio 0
	s_add_i32 s16, 0, 0x18000
	s_add_i32 s17, 0, 0x1c000
	v_add_u32_e32 v164, s16, v147
	v_add_u32_e32 v180, s17, v147
	ds_read_b128 v[152:155], v164
	ds_read_b128 v[156:159], v164 offset:1024
	ds_read_b128 v[160:163], v164 offset:2048
	ds_read_b128 v[164:167], v164 offset:3072
	ds_read_b128 v[168:171], v180
	ds_read_b128 v[172:175], v180 offset:1024
	ds_read_b128 v[176:179], v180 offset:2048
	ds_read_b128 v[180:183], v180 offset:3072
	s_add_u32 s38, s58, 0x30000
	s_addc_u32 s39, s59, 0
	s_mov_b32 m0, s53
	v_lshl_add_u64 v[224:225], s[38:39], 0, v[134:135]
	ds_read_b128 v[184:187], v150 offset:32768
	ds_read_b128 v[188:191], v150 offset:33792
	ds_read_b128 v[192:195], v150 offset:34816
	ds_read_b128 v[196:199], v150 offset:35840
	ds_read_b128 v[200:203], v150 offset:36864
	ds_read_b128 v[204:207], v150 offset:37888
	ds_read_b128 v[208:211], v150 offset:38912
	ds_read_b128 v[212:215], v150 offset:39936
	global_load_lds_dwordx4 v[224:225], off
	v_lshl_add_u64 v[224:225], s[38:39], 0, v[130:131]
	s_mov_b32 m0, s54
	s_nop 0
	global_load_lds_dwordx4 v[224:225], off
	s_waitcnt vmcnt(8)
	s_waitcnt lgkmcnt(0)
	s_setprio 1
	s_waitcnt lgkmcnt(0)
	s_barrier
	v_mfma_f32_16x16x32_bf16 v[124:127], v[152:155], v[184:187], v[124:127]
	v_mfma_f32_16x16x32_bf16 v[120:123], v[160:163], v[184:187], v[120:123]
	v_mfma_f32_16x16x32_bf16 v[116:119], v[152:155], v[192:195], v[116:119]
	v_mfma_f32_16x16x32_bf16 v[112:115], v[160:163], v[192:195], v[112:115]
	v_mfma_f32_16x16x32_bf16 v[104:107], v[152:155], v[200:203], v[104:107]
	v_mfma_f32_16x16x32_bf16 v[96:99], v[160:163], v[200:203], v[96:99]
	v_mfma_f32_16x16x32_bf16 v[88:91], v[152:155], v[208:211], v[88:91]
	v_mfma_f32_16x16x32_bf16 v[80:83], v[160:163], v[208:211], v[80:83]
	v_mfma_f32_16x16x32_bf16 v[124:127], v[156:159], v[188:191], v[124:127]
	v_mfma_f32_16x16x32_bf16 v[120:123], v[164:167], v[188:191], v[120:123]
	v_mfma_f32_16x16x32_bf16 v[116:119], v[156:159], v[196:199], v[116:119]
	v_mfma_f32_16x16x32_bf16 v[112:115], v[164:167], v[196:199], v[112:115]
	v_mfma_f32_16x16x32_bf16 v[104:107], v[156:159], v[204:207], v[104:107]
	v_mfma_f32_16x16x32_bf16 v[96:99], v[164:167], v[204:207], v[96:99]
	v_mfma_f32_16x16x32_bf16 v[88:91], v[156:159], v[212:215], v[88:91]
	v_mfma_f32_16x16x32_bf16 v[80:83], v[164:167], v[212:215], v[80:83]
	s_setprio 0
	s_setprio 1
	v_mfma_f32_16x16x32_bf16 v[108:111], v[168:171], v[184:187], v[108:111]
	v_mfma_f32_16x16x32_bf16 v[100:103], v[176:179], v[184:187], v[100:103]
	v_mfma_f32_16x16x32_bf16 v[92:95], v[168:171], v[192:195], v[92:95]
	v_mfma_f32_16x16x32_bf16 v[84:87], v[176:179], v[192:195], v[84:87]
	v_mfma_f32_16x16x32_bf16 v[76:79], v[168:171], v[200:203], v[76:79]
	v_mfma_f32_16x16x32_bf16 v[72:75], v[176:179], v[200:203], v[72:75]
	v_mfma_f32_16x16x32_bf16 v[68:71], v[168:171], v[208:211], v[68:71]
	v_mfma_f32_16x16x32_bf16 v[64:67], v[176:179], v[208:211], v[64:67]
	v_mfma_f32_16x16x32_bf16 v[108:111], v[172:175], v[188:191], v[108:111]
	v_mfma_f32_16x16x32_bf16 v[100:103], v[180:183], v[188:191], v[100:103]
	v_mfma_f32_16x16x32_bf16 v[92:95], v[172:175], v[196:199], v[92:95]
	v_mfma_f32_16x16x32_bf16 v[84:87], v[180:183], v[196:199], v[84:87]
	v_mfma_f32_16x16x32_bf16 v[76:79], v[172:175], v[204:207], v[76:79]
	v_mfma_f32_16x16x32_bf16 v[72:75], v[180:183], v[204:207], v[72:75]
	v_mfma_f32_16x16x32_bf16 v[68:71], v[172:175], v[212:215], v[68:71]
	v_mfma_f32_16x16x32_bf16 v[64:67], v[180:183], v[212:215], v[64:67]
	s_barrier
; #define PG8_STAGE(bufoff, gbase, voff) do { _Pragma("unroll") for (int _i = 0; _i < 2; ++_i) \
;         __builtin_amdgcn_global_load_lds((const unsigned*)((const char*)(gbase) + (voff)[_i]), (LAS unsigned*)(lds + (bufoff) + ldsw + _i * 8192), 16, 0, 0); } while (0)
; #define PG8_LDA(dst, b, h) do { _Pragma("unroll") for (int m = 0; m < 4; ++m) _Pragma("unroll") for (int k = 0; k < 2; ++k) dst[m][k] = *(const LAS bf16x8*)(lds + PG8_SA(b, h) + aoff + m * 2048 + k * 1024); } while (0)
; #define PG8_MMA(ai, bj, At, Bt) do { __builtin_amdgcn_s_setprio(1); _Pragma("unroll") for (int m = 0; m < 4; ++m) _Pragma("unroll") for (int n = 0; n < 2; ++n) _Pragma("unroll") for (int k = 0; k < 2; ++k) \
;         acc[ai][bj][m][n] = __builtin_amdgcn_mfma_f32_16x16x32_bf16(Bt[n][k], At[m][k], acc[ai][bj][m][n], 0, 0, 0); __builtin_amdgcn_s_setprio(0); } while (0)
; #define PG8_WAIT_V(n) asm volatile("s_waitcnt vmcnt(" #n ")" ::: "memory")
; #define PG8_WAIT_L(n) asm volatile("s_waitcnt lgkmcnt(" #n ")" ::: "memory")
; #define PG8_BAR __builtin_amdgcn_s_barrier()
; #define PG8_SCHED __builtin_amdgcn_sched_barrier(0)
; template <class Epi, class Sched>
; __device__ __forceinline__ void gemm_phase(LAS unsigned char* lds, const Gemm g, const Sched& S, const Epi& E, const int tid) {
;     ...
;         for (int t = 0; t < nt; t += 2) {
;             const bool last = (t == nt - 2);
;             const char* a1 = cA + (size_t)(t + 1) * kstepA;
;             const char* a2 = last ? nA : cA + (size_t)(t + 2) * kstepA; const char* b2 = last ? nB : cB + (size_t)(t + 2) * kstep;
;     ...
;             PG8_LDA(At, 1, 1); PG8_STAGE(PG8_SB(1, 0), b3, voffB); PG8_STAGE(PG8_SB(1, 1), b3 + hstepB, voffB); PG8_STAGE(PG8_SA(1, 0), a3, voffA);
;             PG8_WAIT_V(8); PG8_WAIT_L(0); PG8_BAR; PG8_MMA(1, 0, At, B0); PG8_MMA(1, 1, At, B1); PG8_BAR; PG8_SCHED;
;         }
	s_setprio 0
	s_add_i32 s16, s16, s41
	v_lshl_add_u64 v[216:217], v[216:217], 0, s[20:21]
	s_mov_b32 m0, s16
	ds_read_b128 v[184:187], v150 offset:49152
	ds_read_b128 v[188:191], v150 offset:50176
	ds_read_b128 v[192:195], v150 offset:51200
	ds_read_b128 v[196:199], v150 offset:52224
	ds_read_b128 v[200:203], v150 offset:53248
	ds_read_b128 v[204:207], v150 offset:54272
	ds_read_b128 v[208:211], v150 offset:55296
	ds_read_b128 v[212:215], v150 offset:56320
	global_load_lds_dwordx4 v[216:217], off
	s_add_i32 m0, s16, 0x2000
	s_add_u32 s38, s48, 0x20080
	v_lshl_add_u64 v[216:217], v[218:219], 0, s[20:21]
	s_addc_u32 s39, s49, 0
	s_add_i32 s16, s17, s41
	global_load_lds_dwordx4 v[216:217], off
	v_lshl_add_u64 v[216:217], s[38:39], 0, v[132:133]
	s_mov_b32 m0, s16
	s_nop 0
	global_load_lds_dwordx4 v[216:217], off
	v_lshl_add_u64 v[216:217], s[38:39], 0, v[128:129]
	s_add_i32 m0, s16, 0x2000
	s_nop 0
	global_load_lds_dwordx4 v[216:217], off
	v_lshl_add_u64 v[216:217], v[220:221], 0, s[20:21]
	s_mov_b32 m0, s60
	s_nop 0
	global_load_lds_dwordx4 v[216:217], off
	v_lshl_add_u64 v[216:217], v[222:223], 0, s[20:21]
	s_mov_b32 m0, s61
	s_nop 0
	global_load_lds_dwordx4 v[216:217], off
	s_waitcnt vmcnt(8)
	s_waitcnt lgkmcnt(0)
	s_setprio 1
	s_waitcnt lgkmcnt(0)
	s_barrier
	v_mfma_f32_16x16x32_bf16 v[60:63], v[152:155], v[184:187], v[60:63]
	v_mfma_f32_16x16x32_bf16 v[56:59], v[160:163], v[184:187], v[56:59]
	v_mfma_f32_16x16x32_bf16 v[52:55], v[152:155], v[192:195], v[52:55]
	v_mfma_f32_16x16x32_bf16 v[48:51], v[160:163], v[192:195], v[48:51]
	v_mfma_f32_16x16x32_bf16 v[40:43], v[152:155], v[200:203], v[40:43]
	v_mfma_f32_16x16x32_bf16 v[32:35], v[160:163], v[200:203], v[32:35]
	v_mfma_f32_16x16x32_bf16 v[24:27], v[152:155], v[208:211], v[24:27]
	v_mfma_f32_16x16x32_bf16 v[16:19], v[160:163], v[208:211], v[16:19]
	v_mfma_f32_16x16x32_bf16 v[60:63], v[156:159], v[188:191], v[60:63]
	v_mfma_f32_16x16x32_bf16 v[56:59], v[164:167], v[188:191], v[56:59]
	v_mfma_f32_16x16x32_bf16 v[52:55], v[156:159], v[196:199], v[52:55]
	v_mfma_f32_16x16x32_bf16 v[48:51], v[164:167], v[196:199], v[48:51]
	v_mfma_f32_16x16x32_bf16 v[40:43], v[156:159], v[204:207], v[40:43]
	v_mfma_f32_16x16x32_bf16 v[32:35], v[164:167], v[204:207], v[32:35]
	v_mfma_f32_16x16x32_bf16 v[24:27], v[156:159], v[212:215], v[24:27]
	v_mfma_f32_16x16x32_bf16 v[16:19], v[164:167], v[212:215], v[16:19]
	s_setprio 0
	s_setprio 1
	v_mfma_f32_16x16x32_bf16 v[44:47], v[168:171], v[184:187], v[44:47]
	v_mfma_f32_16x16x32_bf16 v[36:39], v[176:179], v[184:187], v[36:39]
	v_mfma_f32_16x16x32_bf16 v[28:31], v[168:171], v[192:195], v[28:31]
	v_mfma_f32_16x16x32_bf16 v[20:23], v[176:179], v[192:195], v[20:23]
	v_mfma_f32_16x16x32_bf16 v[12:15], v[168:171], v[200:203], v[12:15]
	v_mfma_f32_16x16x32_bf16 v[8:11], v[176:179], v[200:203], v[8:11]
	v_mfma_f32_16x16x32_bf16 v[4:7], v[168:171], v[208:211], v[4:7]
	v_mfma_f32_16x16x32_bf16 v[0:3], v[176:179], v[208:211], v[0:3]
	v_mfma_f32_16x16x32_bf16 v[44:47], v[172:175], v[188:191], v[44:47]
	v_mfma_f32_16x16x32_bf16 v[36:39], v[180:183], v[188:191], v[36:39]
	v_mfma_f32_16x16x32_bf16 v[28:31], v[172:175], v[196:199], v[28:31]
	v_mfma_f32_16x16x32_bf16 v[20:23], v[180:183], v[196:199], v[20:23]
	v_mfma_f32_16x16x32_bf16 v[12:15], v[172:175], v[204:207], v[12:15]
	v_mfma_f32_16x16x32_bf16 v[8:11], v[180:183], v[204:207], v[8:11]
	v_mfma_f32_16x16x32_bf16 v[4:7], v[172:175], v[212:215], v[4:7]
	v_mfma_f32_16x16x32_bf16 v[0:3], v[180:183], v[212:215], v[0:3]
	s_barrier
	s_setprio 0
	s_add_i32 s65, s65, 2
	s_add_u32 s19, s19, 0x100
	s_addc_u32 s27, s27, 0
	s_cmp_gt_u32 s65, 5
	s_mov_b64 s[38:39], s[36:37]
	s_cbranch_scc0 .LBB0_714
	s_and_b64 vcc, exec, s[24:25]
	s_cbranch_vccz .LBB0_717
	s_barrier

; #define PG8_STAGE(bufoff, gbase, voff) do { _Pragma("unroll") for (int _i = 0; _i < 2; ++_i) \
;         __builtin_amdgcn_global_load_lds((const unsigned*)((const char*)(gbase) + (voff)[_i]), (LAS unsigned*)(lds + (bufoff) + ldsw + _i * 8192), 16, 0, 0); } while (0)
; #define PG8_LDA(dst, b, h) do { _Pragma("unroll") for (int m = 0; m < 4; ++m) _Pragma("unroll") for (int k = 0; k < 2; ++k) dst[m][k] = *(const LAS bf16x8*)(lds + PG8_SA(b, h) + aoff + m * 2048 + k * 1024); } while (0)
; #define PG8_LDB(dst, b, h) do { _Pragma("unroll") for (int n = 0; n < 2; ++n) _Pragma("unroll") for (int k = 0; k < 2; ++k) dst[n][k] = *(const LAS bf16x8*)(lds + PG8_SB(b, h) + boff + n * 2048 + k * 1024); } while (0)
; #define PG8_MMA(ai, bj, At, Bt) do { __builtin_amdgcn_s_setprio(1); _Pragma("unroll") for (int m = 0; m < 4; ++m) _Pragma("unroll") for (int n = 0; n < 2; ++n) _Pragma("unroll") for (int k = 0; k < 2; ++k) \
;         acc[ai][bj][m][n] = __builtin_amdgcn_mfma_f32_16x16x32_bf16(Bt[n][k], At[m][k], acc[ai][bj][m][n], 0, 0, 0); __builtin_amdgcn_s_setprio(0); } while (0)
; #define PG8_WAIT_V(n) asm volatile("s_waitcnt vmcnt(" #n ")" ::: "memory")
; #define PG8_WAIT_L(n) asm volatile("s_waitcnt lgkmcnt(" #n ")" ::: "memory")
; #define PG8_BAR __builtin_amdgcn_s_barrier()
; template <class Epi, class Sched>
; __device__ __forceinline__ void gemm_phase(LAS unsigned char* lds, const Gemm g, const Sched& S, const Epi& E, const int tid) {
;     ...
;             const bool last = (t == nt - 2);
;             const char* a1 = cA + (size_t)(t + 1) * kstepA;
;             const char* a2 = last ? nA : cA + (size_t)(t + 2) * kstepA; const char* b2 = last ? nB : cB + (size_t)(t + 2) * kstep;
;             const char* a3 = a2 + kstepA; const char* b3 = b2 + kstep;
;             if constexpr (Epi::HAS_MID) { if (t == g.tmid) E.mid(acc, cur, ui, wr, wc, fr, fq); }
;             PG8_LDB(B0, 0, 0); PG8_LDB(B1, 0, 1); PG8_SCHED; PG8_LDA(At, 0, 0); PG8_STAGE(PG8_SA(1, 1), a1 + hstepA, voffA);
;             PG8_WAIT_V(8); PG8_WAIT_L(0); PG8_BAR; PG8_MMA(0, 0, At, B0); PG8_MMA(0, 1, At, B1); PG8_BAR; PG8_SCHED;
;             PG8_LDA(At, 0, 1); PG8_STAGE(PG8_SB(0, 0), b2, voffB); PG8_STAGE(PG8_SB(0, 1), b2 + hstepB, voffB); PG8_STAGE(PG8_SA(0, 0), a2, voffA);
;             PG8_WAIT_V(8); PG8_WAIT_L(0); PG8_BAR; PG8_MMA(1, 0, At, B0); PG8_MMA(1, 1, At, B1); PG8_BAR; PG8_SCHED;
.LBB0_802:
	ds_read_b128 v[16:19], v209
	ds_read_b128 v[20:23], v209 offset:1024
	ds_read_b128 v[104:107], v209 offset:2048
	ds_read_b128 v[140:143], v209 offset:3072
	ds_read_b128 v[144:147], v210
	ds_read_b128 v[148:151], v210 offset:1024
	ds_read_b128 v[178:181], v210 offset:2048
	ds_read_b128 v[212:215], v210 offset:3072
	s_add_u32 s4, s8, 0xfffe0080
	s_addc_u32 s5, s9, -1
	s_cmp_eq_u32 s83, 4
	s_cselect_b32 s29, s18, s5
	s_cselect_b32 s28, s19, s4
	s_cselect_b32 s27, s50, s75
	s_cselect_b32 s26, s51, s65
	v_lshl_add_u64 v[182:183], s[8:9], 0, v[168:169]
	s_add_i32 m0, s25, 0xc000
	ds_read_b128 v[216:219], v206
	ds_read_b128 v[220:223], v206 offset:1024
	ds_read_b128 v[224:227], v206 offset:2048
	ds_read_b128 v[228:231], v206 offset:3072
	ds_read_b128 v[232:235], v206 offset:4096
	ds_read_b128 v[236:239], v206 offset:5120
	ds_read_b128 v[240:243], v206 offset:6144
	ds_read_b128 v[244:247], v206 offset:7168
	global_load_lds_dwordx4 v[182:183], off
	v_lshl_add_u64 v[182:183], s[8:9], 0, v[170:171]
	s_add_i32 m0, s25, 0xe000
	s_nop 0
	global_load_lds_dwordx4 v[182:183], off
	s_waitcnt vmcnt(8)
	s_waitcnt lgkmcnt(0)
	s_setprio 1
	s_waitcnt lgkmcnt(0)
	s_barrier
	v_mfma_f32_16x16x32_bf16 v[136:139], v[16:19], v[216:219], v[136:139]
	v_mfma_f32_16x16x32_bf16 v[132:135], v[104:107], v[216:219], v[132:135]
	v_mfma_f32_16x16x32_bf16 v[120:123], v[16:19], v[224:227], v[120:123]
	v_mfma_f32_16x16x32_bf16 v[116:119], v[104:107], v[224:227], v[116:119]
	v_mfma_f32_16x16x32_bf16 v[100:103], v[16:19], v[232:235], v[100:103]
	v_mfma_f32_16x16x32_bf16 v[96:99], v[104:107], v[232:235], v[96:99]
	v_mfma_f32_16x16x32_bf16 v[84:87], v[16:19], v[240:243], v[84:87]
	v_mfma_f32_16x16x32_bf16 v[80:83], v[104:107], v[240:243], v[80:83]
	v_mfma_f32_16x16x32_bf16 v[136:139], v[20:23], v[220:223], v[136:139]
	v_mfma_f32_16x16x32_bf16 v[132:135], v[140:143], v[220:223], v[132:135]
	v_mfma_f32_16x16x32_bf16 v[120:123], v[20:23], v[228:231], v[120:123]
	v_mfma_f32_16x16x32_bf16 v[116:119], v[140:143], v[228:231], v[116:119]
	v_mfma_f32_16x16x32_bf16 v[100:103], v[20:23], v[236:239], v[100:103]
	v_mfma_f32_16x16x32_bf16 v[96:99], v[140:143], v[236:239], v[96:99]
	v_mfma_f32_16x16x32_bf16 v[84:87], v[20:23], v[244:247], v[84:87]
	v_mfma_f32_16x16x32_bf16 v[80:83], v[140:143], v[244:247], v[80:83]
	s_setprio 0
	s_setprio 1
	v_mfma_f32_16x16x32_bf16 v[128:131], v[144:147], v[216:219], v[128:131]
	v_mfma_f32_16x16x32_bf16 v[124:127], v[178:181], v[216:219], v[124:127]
	v_mfma_f32_16x16x32_bf16 v[112:115], v[144:147], v[224:227], v[112:115]
	v_mfma_f32_16x16x32_bf16 v[108:111], v[178:181], v[224:227], v[108:111]
	v_mfma_f32_16x16x32_bf16 v[92:95], v[144:147], v[232:235], v[92:95]
	v_mfma_f32_16x16x32_bf16 v[88:91], v[178:181], v[232:235], v[88:91]
	v_mfma_f32_16x16x32_bf16 v[76:79], v[144:147], v[240:243], v[76:79]
	v_mfma_f32_16x16x32_bf16 v[72:75], v[178:181], v[240:243], v[72:75]
	v_mfma_f32_16x16x32_bf16 v[128:131], v[148:151], v[220:223], v[128:131]
	v_mfma_f32_16x16x32_bf16 v[124:127], v[212:215], v[220:223], v[124:127]
	v_mfma_f32_16x16x32_bf16 v[112:115], v[148:151], v[228:231], v[112:115]
	v_mfma_f32_16x16x32_bf16 v[108:111], v[212:215], v[228:231], v[108:111]
	v_mfma_f32_16x16x32_bf16 v[92:95], v[148:151], v[236:239], v[92:95]
	v_mfma_f32_16x16x32_bf16 v[88:91], v[212:215], v[236:239], v[88:91]
	v_mfma_f32_16x16x32_bf16 v[76:79], v[148:151], v[244:247], v[76:79]
	v_mfma_f32_16x16x32_bf16 v[72:75], v[212:215], v[244:247], v[72:75]
	s_barrier
	s_setprio 0
	s_add_i32 s4, s54, s30
	v_lshl_add_u64 v[182:183], s[26:27], 0, v[154:155]
	s_mov_b32 m0, s4
	ds_read_b128 v[216:219], v206 offset:16384
	ds_read_b128 v[220:223], v206 offset:17408
	ds_read_b128 v[224:227], v206 offset:18432
	ds_read_b128 v[228:231], v206 offset:19456
	ds_read_b128 v[232:235], v206 offset:20480
	ds_read_b128 v[236:239], v206 offset:21504
	ds_read_b128 v[240:243], v206 offset:22528
	ds_read_b128 v[244:247], v206 offset:23552
	global_load_lds_dwordx4 v[182:183], off
	s_add_i32 m0, s4, 0x2000
	s_add_u32 s96, s26, 0x20000
	v_lshl_add_u64 v[248:249], s[26:27], 0, v[158:159]
	s_addc_u32 s97, s27, 0
	s_add_i32 s4, s55, s30
	global_load_lds_dwordx4 v[248:249], off
	v_lshl_add_u64 v[250:251], s[96:97], 0, v[154:155]
	s_mov_b32 m0, s4
	v_lshl_add_u64 v[174:175], s[28:29], 0, v[156:157]
	global_load_lds_dwordx4 v[250:251], off
	v_lshl_add_u64 v[250:251], s[96:97], 0, v[158:159]
	s_add_i32 m0, s4, 0x2000
	s_nop 0
	global_load_lds_dwordx4 v[250:251], off
	v_lshl_add_u64 v[250:251], s[28:29], 0, v[152:153]
	s_mov_b32 m0, s25
	s_nop 0
	global_load_lds_dwordx4 v[250:251], off
	s_mov_b32 m0, s31
	s_nop 0
	global_load_lds_dwordx4 v[174:175], off
	s_waitcnt vmcnt(8)
	s_waitcnt lgkmcnt(0)
	s_setprio 1
	s_waitcnt lgkmcnt(0)
	s_barrier
; #define PG8_STAGE(bufoff, gbase, voff) do { _Pragma("unroll") for (int _i = 0; _i < 2; ++_i) \
;         __builtin_amdgcn_global_load_lds((const unsigned*)((const char*)(gbase) + (voff)[_i]), (LAS unsigned*)(lds + (bufoff) + ldsw + _i * 8192), 16, 0, 0); } while (0)
; #define PG8_LDA(dst, b, h) do { _Pragma("unroll") for (int m = 0; m < 4; ++m) _Pragma("unroll") for (int k = 0; k < 2; ++k) dst[m][k] = *(const LAS bf16x8*)(lds + PG8_SA(b, h) + aoff + m * 2048 + k * 1024); } while (0)
; #define PG8_LDB(dst, b, h) do { _Pragma("unroll") for (int n = 0; n < 2; ++n) _Pragma("unroll") for (int k = 0; k < 2; ++k) dst[n][k] = *(const LAS bf16x8*)(lds + PG8_SB(b, h) + boff + n * 2048 + k * 1024); } while (0)
; #define PG8_MMA(ai, bj, At, Bt) do { __builtin_amdgcn_s_setprio(1); _Pragma("unroll") for (int m = 0; m < 4; ++m) _Pragma("unroll") for (int n = 0; n < 2; ++n) _Pragma("unroll") for (int k = 0; k < 2; ++k) \
;         acc[ai][bj][m][n] = __builtin_amdgcn_mfma_f32_16x16x32_bf16(Bt[n][k], At[m][k], acc[ai][bj][m][n], 0, 0, 0); __builtin_amdgcn_s_setprio(0); } while (0)
; #define PG8_WAIT_V(n) asm volatile("s_waitcnt vmcnt(" #n ")" ::: "memory")
; #define PG8_WAIT_L(n) asm volatile("s_waitcnt lgkmcnt(" #n ")" ::: "memory")
; #define PG8_BAR __builtin_amdgcn_s_barrier()
; #define PG8_SCHED __builtin_amdgcn_sched_barrier(0)
; template <class Epi, class Sched>
; __device__ __forceinline__ void gemm_phase(LAS unsigned char* lds, const Gemm g, const Sched& S, const Epi& E, const int tid) {
;     ...
;             PG8_WAIT_V(8); PG8_WAIT_L(0); PG8_BAR; PG8_MMA(1, 0, At, B0); PG8_MMA(1, 1, At, B1); PG8_BAR; PG8_SCHED;
;             PG8_LDB(B0, 1, 0); PG8_LDB(B1, 1, 1); PG8_SCHED; PG8_LDA(At, 1, 0); PG8_STAGE(PG8_SA(0, 1), a2 + hstepA, voffA);
;             PG8_WAIT_V(8); PG8_WAIT_L(0); PG8_BAR; PG8_MMA(0, 0, At, B0); PG8_MMA(0, 1, At, B1); PG8_BAR; PG8_SCHED;
	v_mfma_f32_16x16x32_bf16 v[68:71], v[16:19], v[216:219], v[68:71]
	v_mfma_f32_16x16x32_bf16 v[64:67], v[104:107], v[216:219], v[64:67]
	v_mfma_f32_16x16x32_bf16 v[52:55], v[16:19], v[224:227], v[52:55]
	v_mfma_f32_16x16x32_bf16 v[48:51], v[104:107], v[224:227], v[48:51]
	v_mfma_f32_16x16x32_bf16 v[36:39], v[16:19], v[232:235], v[36:39]
	v_mfma_f32_16x16x32_bf16 v[32:35], v[104:107], v[232:235], v[32:35]
	v_mfma_f32_16x16x32_bf16 v[12:15], v[16:19], v[240:243], v[12:15]
	v_mfma_f32_16x16x32_bf16 v[8:11], v[104:107], v[240:243], v[8:11]
	v_mfma_f32_16x16x32_bf16 v[68:71], v[20:23], v[220:223], v[68:71]
	v_mfma_f32_16x16x32_bf16 v[64:67], v[140:143], v[220:223], v[64:67]
	v_mfma_f32_16x16x32_bf16 v[52:55], v[20:23], v[228:231], v[52:55]
	v_mfma_f32_16x16x32_bf16 v[48:51], v[140:143], v[228:231], v[48:51]
	v_mfma_f32_16x16x32_bf16 v[36:39], v[20:23], v[236:239], v[36:39]
	v_mfma_f32_16x16x32_bf16 v[32:35], v[140:143], v[236:239], v[32:35]
	v_mfma_f32_16x16x32_bf16 v[12:15], v[20:23], v[244:247], v[12:15]
	v_mfma_f32_16x16x32_bf16 v[8:11], v[140:143], v[244:247], v[8:11]
	s_setprio 0
	s_setprio 1
	v_mfma_f32_16x16x32_bf16 v[44:47], v[144:147], v[224:227], v[44:47]
	v_mfma_f32_16x16x32_bf16 v[40:43], v[178:181], v[224:227], v[40:43]
	v_mfma_f32_16x16x32_bf16 v[28:31], v[144:147], v[232:235], v[28:31]
	v_mfma_f32_16x16x32_bf16 v[24:27], v[178:181], v[232:235], v[24:27]
	v_mfma_f32_16x16x32_bf16 v[4:7], v[144:147], v[240:243], v[4:7]
	v_mfma_f32_16x16x32_bf16 v[0:3], v[178:181], v[240:243], v[0:3]
	v_mfma_f32_16x16x32_bf16 v[16:19], v[144:147], v[216:219], v[60:63]
	v_mfma_f32_16x16x32_bf16 v[20:23], v[178:181], v[216:219], v[56:59]
	v_mfma_f32_16x16x32_bf16 v[44:47], v[148:151], v[228:231], v[44:47]
	v_mfma_f32_16x16x32_bf16 v[40:43], v[212:215], v[228:231], v[40:43]
	v_mfma_f32_16x16x32_bf16 v[28:31], v[148:151], v[236:239], v[28:31]
	v_mfma_f32_16x16x32_bf16 v[24:27], v[212:215], v[236:239], v[24:27]
	v_mfma_f32_16x16x32_bf16 v[4:7], v[148:151], v[244:247], v[4:7]
	v_mfma_f32_16x16x32_bf16 v[0:3], v[212:215], v[244:247], v[0:3]
	v_mfma_f32_16x16x32_bf16 v[16:19], v[148:151], v[220:223], v[16:19]
	v_mfma_f32_16x16x32_bf16 v[20:23], v[212:215], v[220:223], v[20:23]
	s_barrier
	s_setprio 0
	s_add_i32 s4, 0, 0x18000
	s_add_i32 s5, 0, 0x1c000
	v_add_u32_e32 v140, s4, v185
	v_add_u32_e32 v173, s5, v185
	ds_read_b128 v[56:59], v140
	ds_read_b128 v[60:63], v140 offset:1024
	ds_read_b128 v[104:107], v140 offset:2048
	ds_read_b128 v[140:143], v140 offset:3072
	ds_read_b128 v[144:147], v173
	ds_read_b128 v[148:151], v173 offset:1024
	ds_read_b128 v[178:181], v173 offset:2048
	ds_read_b128 v[212:215], v173 offset:3072
	s_add_u32 s28, s28, 0x20000
	s_addc_u32 s29, s29, 0
	s_mov_b32 m0, s41
	v_lshl_add_u64 v[176:177], s[28:29], 0, v[152:153]
	ds_read_b128 v[216:219], v206 offset:32768
	ds_read_b128 v[220:223], v206 offset:33792
	ds_read_b128 v[224:227], v206 offset:34816
	ds_read_b128 v[228:231], v206 offset:35840
	ds_read_b128 v[232:235], v206 offset:36864
	ds_read_b128 v[236:239], v206 offset:37888
	ds_read_b128 v[240:243], v206 offset:38912
	ds_read_b128 v[244:247], v206 offset:39936
	global_load_lds_dwordx4 v[176:177], off
	v_lshl_add_u64 v[176:177], s[28:29], 0, v[156:157]
	s_mov_b32 m0, s48
	s_nop 0
	global_load_lds_dwordx4 v[176:177], off
	s_waitcnt vmcnt(8)
	s_waitcnt lgkmcnt(0)
	s_setprio 1
	s_waitcnt lgkmcnt(0)
	s_barrier
	v_mfma_f32_16x16x32_bf16 v[136:139], v[56:59], v[216:219], v[136:139]
	v_mfma_f32_16x16x32_bf16 v[132:135], v[104:107], v[216:219], v[132:135]
	v_mfma_f32_16x16x32_bf16 v[120:123], v[56:59], v[224:227], v[120:123]
	v_mfma_f32_16x16x32_bf16 v[116:119], v[104:107], v[224:227], v[116:119]
	v_mfma_f32_16x16x32_bf16 v[100:103], v[56:59], v[232:235], v[100:103]
	v_mfma_f32_16x16x32_bf16 v[96:99], v[104:107], v[232:235], v[96:99]
	v_mfma_f32_16x16x32_bf16 v[84:87], v[56:59], v[240:243], v[84:87]
	v_mfma_f32_16x16x32_bf16 v[80:83], v[104:107], v[240:243], v[80:83]
	v_mfma_f32_16x16x32_bf16 v[136:139], v[60:63], v[220:223], v[136:139]
	v_mfma_f32_16x16x32_bf16 v[132:135], v[140:143], v[220:223], v[132:135]
	v_mfma_f32_16x16x32_bf16 v[120:123], v[60:63], v[228:231], v[120:123]
	v_mfma_f32_16x16x32_bf16 v[116:119], v[140:143], v[228:231], v[116:119]
	v_mfma_f32_16x16x32_bf16 v[100:103], v[60:63], v[236:239], v[100:103]
	v_mfma_f32_16x16x32_bf16 v[96:99], v[140:143], v[236:239], v[96:99]
	v_mfma_f32_16x16x32_bf16 v[84:87], v[60:63], v[244:247], v[84:87]
	v_mfma_f32_16x16x32_bf16 v[80:83], v[140:143], v[244:247], v[80:83]
	s_setprio 0
	s_setprio 1
	v_mfma_f32_16x16x32_bf16 v[128:131], v[144:147], v[216:219], v[128:131]
	v_mfma_f32_16x16x32_bf16 v[124:127], v[178:181], v[216:219], v[124:127]
	v_mfma_f32_16x16x32_bf16 v[112:115], v[144:147], v[224:227], v[112:115]
	v_mfma_f32_16x16x32_bf16 v[108:111], v[178:181], v[224:227], v[108:111]
	v_mfma_f32_16x16x32_bf16 v[92:95], v[144:147], v[232:235], v[92:95]
	v_mfma_f32_16x16x32_bf16 v[88:91], v[178:181], v[232:235], v[88:91]
	v_mfma_f32_16x16x32_bf16 v[76:79], v[144:147], v[240:243], v[76:79]
	v_mfma_f32_16x16x32_bf16 v[72:75], v[178:181], v[240:243], v[72:75]
	v_mfma_f32_16x16x32_bf16 v[128:131], v[148:151], v[220:223], v[128:131]
	v_mfma_f32_16x16x32_bf16 v[124:127], v[212:215], v[220:223], v[124:127]
	v_mfma_f32_16x16x32_bf16 v[112:115], v[148:151], v[228:231], v[112:115]
	v_mfma_f32_16x16x32_bf16 v[108:111], v[212:215], v[228:231], v[108:111]
	v_mfma_f32_16x16x32_bf16 v[92:95], v[148:151], v[236:239], v[92:95]
	v_mfma_f32_16x16x32_bf16 v[88:91], v[212:215], v[236:239], v[88:91]
	v_mfma_f32_16x16x32_bf16 v[76:79], v[148:151], v[244:247], v[76:79]
	v_mfma_f32_16x16x32_bf16 v[72:75], v[212:215], v[244:247], v[72:75]
	s_barrier
; #define PG8_STAGE(bufoff, gbase, voff) do { _Pragma("unroll") for (int _i = 0; _i < 2; ++_i) \
;         __builtin_amdgcn_global_load_lds((const unsigned*)((const char*)(gbase) + (voff)[_i]), (LAS unsigned*)(lds + (bufoff) + ldsw + _i * 8192), 16, 0, 0); } while (0)
; #define PG8_LDA(dst, b, h) do { _Pragma("unroll") for (int m = 0; m < 4; ++m) _Pragma("unroll") for (int k = 0; k < 2; ++k) dst[m][k] = *(const LAS bf16x8*)(lds + PG8_SA(b, h) + aoff + m * 2048 + k * 1024); } while (0)
; #define PG8_MMA(ai, bj, At, Bt) do { __builtin_amdgcn_s_setprio(1); _Pragma("unroll") for (int m = 0; m < 4; ++m) _Pragma("unroll") for (int n = 0; n < 2; ++n) _Pragma("unroll") for (int k = 0; k < 2; ++k) \
;         acc[ai][bj][m][n] = __builtin_amdgcn_mfma_f32_16x16x32_bf16(Bt[n][k], At[m][k], acc[ai][bj][m][n], 0, 0, 0); __builtin_amdgcn_s_setprio(0); } while (0)
; #define PG8_WAIT_V(n) asm volatile("s_waitcnt vmcnt(" #n ")" ::: "memory")
; #define PG8_WAIT_L(n) asm volatile("s_waitcnt lgkmcnt(" #n ")" ::: "memory")
; #define PG8_BAR __builtin_amdgcn_s_barrier()
; #define PG8_SCHED __builtin_amdgcn_sched_barrier(0)
; template <class Epi, class Sched>
; __device__ __forceinline__ void gemm_phase(LAS unsigned char* lds, const Gemm g, const Sched& S, const Epi& E, const int tid) {
;     ...
;             PG8_WAIT_V(8); PG8_WAIT_L(0); PG8_BAR; PG8_MMA(0, 0, At, B0); PG8_MMA(0, 1, At, B1); PG8_BAR; PG8_SCHED;
;             PG8_LDA(At, 1, 1); PG8_STAGE(PG8_SB(1, 0), b3, voffB); PG8_STAGE(PG8_SB(1, 1), b3 + hstepB, voffB); PG8_STAGE(PG8_SA(1, 0), a3, voffA);
;             PG8_WAIT_V(8); PG8_WAIT_L(0); PG8_BAR; PG8_MMA(1, 0, At, B0); PG8_MMA(1, 1, At, B1); PG8_BAR; PG8_SCHED;
;         }
;         if (wr == 0) PG8_BAR;
	s_setprio 0
	s_add_i32 s4, s4, s30
	v_lshl_add_u64 v[176:177], v[182:183], 0, s[60:61]
	s_mov_b32 m0, s4
	ds_read_b128 v[216:219], v206 offset:49152
	ds_read_b128 v[220:223], v206 offset:50176
	ds_read_b128 v[224:227], v206 offset:51200
	ds_read_b128 v[228:231], v206 offset:52224
	ds_read_b128 v[232:235], v206 offset:53248
	ds_read_b128 v[236:239], v206 offset:54272
	ds_read_b128 v[240:243], v206 offset:55296
	ds_read_b128 v[244:247], v206 offset:56320
	global_load_lds_dwordx4 v[176:177], off
	s_add_i32 m0, s4, 0x2000
	s_add_u32 s26, s26, 0x20080
	v_lshl_add_u64 v[176:177], v[248:249], 0, s[60:61]
	s_addc_u32 s27, s27, 0
	s_add_i32 s4, s5, s30
	global_load_lds_dwordx4 v[176:177], off
	v_lshl_add_u64 v[176:177], s[26:27], 0, v[154:155]
	s_mov_b32 m0, s4
	v_lshl_add_u64 v[174:175], v[174:175], 0, s[60:61]
	global_load_lds_dwordx4 v[176:177], off
	v_lshl_add_u64 v[176:177], s[26:27], 0, v[158:159]
	s_add_i32 m0, s4, 0x2000
	s_nop 0
	global_load_lds_dwordx4 v[176:177], off
	v_lshl_add_u64 v[176:177], v[250:251], 0, s[60:61]
	s_mov_b32 m0, s49
	s_nop 0
	global_load_lds_dwordx4 v[176:177], off
	s_mov_b32 m0, s52
	s_nop 0
	global_load_lds_dwordx4 v[174:175], off
	s_waitcnt vmcnt(8)
	s_waitcnt lgkmcnt(0)
	s_setprio 1
	s_waitcnt lgkmcnt(0)
	s_barrier
	v_mfma_f32_16x16x32_bf16 v[68:71], v[56:59], v[216:219], v[68:71]
	v_mfma_f32_16x16x32_bf16 v[64:67], v[104:107], v[216:219], v[64:67]
	v_mfma_f32_16x16x32_bf16 v[52:55], v[56:59], v[224:227], v[52:55]
	v_mfma_f32_16x16x32_bf16 v[48:51], v[104:107], v[224:227], v[48:51]
	v_mfma_f32_16x16x32_bf16 v[36:39], v[56:59], v[232:235], v[36:39]
	v_mfma_f32_16x16x32_bf16 v[32:35], v[104:107], v[232:235], v[32:35]
	v_mfma_f32_16x16x32_bf16 v[12:15], v[56:59], v[240:243], v[12:15]
	v_mfma_f32_16x16x32_bf16 v[8:11], v[104:107], v[240:243], v[8:11]
	v_mfma_f32_16x16x32_bf16 v[68:71], v[60:63], v[220:223], v[68:71]
	v_mfma_f32_16x16x32_bf16 v[64:67], v[140:143], v[220:223], v[64:67]
	v_mfma_f32_16x16x32_bf16 v[52:55], v[60:63], v[228:231], v[52:55]
	v_mfma_f32_16x16x32_bf16 v[48:51], v[140:143], v[228:231], v[48:51]
	v_mfma_f32_16x16x32_bf16 v[36:39], v[60:63], v[236:239], v[36:39]
	v_mfma_f32_16x16x32_bf16 v[32:35], v[140:143], v[236:239], v[32:35]
	v_mfma_f32_16x16x32_bf16 v[12:15], v[60:63], v[244:247], v[12:15]
	v_mfma_f32_16x16x32_bf16 v[8:11], v[140:143], v[244:247], v[8:11]
	s_setprio 0
	s_setprio 1
	v_mfma_f32_16x16x32_bf16 v[16:19], v[144:147], v[216:219], v[16:19]
	v_mfma_f32_16x16x32_bf16 v[60:63], v[148:151], v[220:223], v[16:19]
	v_mfma_f32_16x16x32_bf16 v[16:19], v[178:181], v[216:219], v[20:23]
	v_mfma_f32_16x16x32_bf16 v[56:59], v[212:215], v[220:223], v[16:19]
	v_mfma_f32_16x16x32_bf16 v[16:19], v[144:147], v[224:227], v[44:47]
	v_mfma_f32_16x16x32_bf16 v[44:47], v[148:151], v[228:231], v[16:19]
	v_mfma_f32_16x16x32_bf16 v[16:19], v[178:181], v[224:227], v[40:43]
	v_mfma_f32_16x16x32_bf16 v[40:43], v[212:215], v[228:231], v[16:19]
	v_mfma_f32_16x16x32_bf16 v[16:19], v[144:147], v[232:235], v[28:31]
	v_mfma_f32_16x16x32_bf16 v[28:31], v[148:151], v[236:239], v[16:19]
	v_mfma_f32_16x16x32_bf16 v[16:19], v[178:181], v[232:235], v[24:27]
	v_mfma_f32_16x16x32_bf16 v[4:7], v[144:147], v[240:243], v[4:7]
	v_mfma_f32_16x16x32_bf16 v[0:3], v[178:181], v[240:243], v[0:3]
	v_mfma_f32_16x16x32_bf16 v[24:27], v[212:215], v[236:239], v[16:19]
	v_mfma_f32_16x16x32_bf16 v[4:7], v[148:151], v[244:247], v[4:7]
	v_mfma_f32_16x16x32_bf16 v[0:3], v[212:215], v[244:247], v[0:3]
	s_barrier
	s_setprio 0
	s_add_i32 s83, s83, 2
	s_add_u32 s8, s8, 0x100
	s_addc_u32 s9, s9, 0
	s_add_u32 s65, s65, 0x100
	s_addc_u32 s75, s75, 0
	s_cmp_gt_u32 s83, 5
	s_cbranch_scc0 .LBB0_802
	s_and_b64 vcc, exec, s[62:63]
	s_cbranch_vccz .LBB0_805
	s_barrier

; #define PG8_STAGE(bufoff, gbase, voff) do { _Pragma("unroll") for (int _i = 0; _i < 2; ++_i) \
;         __builtin_amdgcn_global_load_lds((const unsigned*)((const char*)(gbase) + (voff)[_i]), (LAS unsigned*)(lds + (bufoff) + ldsw + _i * 8192), 16, 0, 0); } while (0)
; #define PG8_LDA(dst, b, h) do { _Pragma("unroll") for (int m = 0; m < 4; ++m) _Pragma("unroll") for (int k = 0; k < 2; ++k) dst[m][k] = *(const LAS bf16x8*)(lds + PG8_SA(b, h) + aoff + m * 2048 + k * 1024); } while (0)
; #define PG8_LDB(dst, b, h) do { _Pragma("unroll") for (int n = 0; n < 2; ++n) _Pragma("unroll") for (int k = 0; k < 2; ++k) dst[n][k] = *(const LAS bf16x8*)(lds + PG8_SB(b, h) + boff + n * 2048 + k * 1024); } while (0)
; #define PG8_MMA(ai, bj, At, Bt) do { __builtin_amdgcn_s_setprio(1); _Pragma("unroll") for (int m = 0; m < 4; ++m) _Pragma("unroll") for (int n = 0; n < 2; ++n) _Pragma("unroll") for (int k = 0; k < 2; ++k) \
;         acc[ai][bj][m][n] = __builtin_amdgcn_mfma_f32_16x16x32_bf16(Bt[n][k], At[m][k], acc[ai][bj][m][n], 0, 0, 0); __builtin_amdgcn_s_setprio(0); } while (0)
; #define PG8_WAIT_V(n) asm volatile("s_waitcnt vmcnt(" #n ")" ::: "memory")
; #define PG8_WAIT_L(n) asm volatile("s_waitcnt lgkmcnt(" #n ")" ::: "memory")
; #define PG8_BAR __builtin_amdgcn_s_barrier()
; template <class Epi, class Sched>
; __device__ __forceinline__ void gemm_phase(LAS unsigned char* lds, const Gemm g, const Sched& S, const Epi& E, const int tid) {
;     ...
;             const bool last = (t == nt - 2);
;             const char* a1 = cA + (size_t)(t + 1) * kstepA;
;             const char* a2 = last ? nA : cA + (size_t)(t + 2) * kstepA; const char* b2 = last ? nB : cB + (size_t)(t + 2) * kstep;
;             const char* a3 = a2 + kstepA; const char* b3 = b2 + kstep;
;             if constexpr (Epi::HAS_MID) { if (t == g.tmid) E.mid(acc, cur, ui, wr, wc, fr, fq); }
;             PG8_LDB(B0, 0, 0); PG8_LDB(B1, 0, 1); PG8_SCHED; PG8_LDA(At, 0, 0); PG8_STAGE(PG8_SA(1, 1), a1 + hstepA, voffA);
;             PG8_WAIT_V(8); PG8_WAIT_L(0); PG8_BAR; PG8_MMA(0, 0, At, B0); PG8_MMA(0, 1, At, B1); PG8_BAR; PG8_SCHED;
;             PG8_LDA(At, 0, 1); PG8_STAGE(PG8_SB(0, 0), b2, voffB); PG8_STAGE(PG8_SB(0, 1), b2 + hstepB, voffB); PG8_STAGE(PG8_SA(0, 0), a2, voffA);
;             PG8_WAIT_V(8); PG8_WAIT_L(0); PG8_BAR; PG8_MMA(1, 0, At, B0); PG8_MMA(1, 1, At, B1); PG8_BAR; PG8_SCHED;
.LBB0_936:
	ds_read_b128 v[40:43], v197
	ds_read_b128 v[44:47], v197 offset:1024
	ds_read_b128 v[116:119], v197 offset:2048
	ds_read_b128 v[124:127], v197 offset:3072
	ds_read_b128 v[136:139], v198
	ds_read_b128 v[148:151], v198 offset:1024
	ds_read_b128 v[152:155], v198 offset:2048
	ds_read_b128 v[156:159], v198 offset:3072
	s_add_u32 s8, s6, 0x100
	s_addc_u32 s9, s7, 0
	s_cmp_eq_u32 s88, 8
	s_cselect_b32 s31, s25, s9
	s_cselect_b32 s30, s24, s8
	s_cselect_b32 s27, s29, s41
	s_cselect_b32 s26, s28, s40
	v_lshl_add_u64 v[218:219], s[6:7], 0, v[174:175]
	s_add_i32 m0, s52, 0xc000
	ds_read_b128 v[160:163], v199
	ds_read_b128 v[182:185], v199 offset:1024
	ds_read_b128 v[186:189], v199 offset:2048
	ds_read_b128 v[190:193], v199 offset:3072
	ds_read_b128 v[202:205], v199 offset:4096
	ds_read_b128 v[206:209], v199 offset:5120
	ds_read_b128 v[210:213], v199 offset:6144
	ds_read_b128 v[214:217], v199 offset:7168
	global_load_lds_dwordx4 v[218:219], off
	v_lshl_add_u64 v[218:219], s[6:7], 0, v[176:177]
	s_add_i32 m0, s52, 0xe000
	s_nop 0
	global_load_lds_dwordx4 v[218:219], off
	s_waitcnt vmcnt(8)
	s_waitcnt lgkmcnt(0)
	s_setprio 1
	s_waitcnt lgkmcnt(0)
	s_barrier
	v_mfma_f32_16x16x32_bf16 v[144:147], v[40:43], v[160:163], v[144:147]
	v_mfma_f32_16x16x32_bf16 v[140:143], v[116:119], v[160:163], v[140:143]
	v_mfma_f32_16x16x32_bf16 v[132:135], v[40:43], v[186:189], v[132:135]
	v_mfma_f32_16x16x32_bf16 v[128:131], v[116:119], v[186:189], v[128:131]
	v_mfma_f32_16x16x32_bf16 v[120:123], v[40:43], v[202:205], v[120:123]
	v_mfma_f32_16x16x32_bf16 v[112:115], v[116:119], v[202:205], v[112:115]
	v_mfma_f32_16x16x32_bf16 v[108:111], v[40:43], v[210:213], v[108:111]
	v_mfma_f32_16x16x32_bf16 v[104:107], v[116:119], v[210:213], v[104:107]
	v_mfma_f32_16x16x32_bf16 v[144:147], v[44:47], v[182:185], v[144:147]
	v_mfma_f32_16x16x32_bf16 v[140:143], v[124:127], v[182:185], v[140:143]
	v_mfma_f32_16x16x32_bf16 v[132:135], v[44:47], v[190:193], v[132:135]
	v_mfma_f32_16x16x32_bf16 v[128:131], v[124:127], v[190:193], v[128:131]
	v_mfma_f32_16x16x32_bf16 v[120:123], v[44:47], v[206:209], v[120:123]
	v_mfma_f32_16x16x32_bf16 v[112:115], v[124:127], v[206:209], v[112:115]
	v_mfma_f32_16x16x32_bf16 v[108:111], v[44:47], v[214:217], v[108:111]
	v_mfma_f32_16x16x32_bf16 v[104:107], v[124:127], v[214:217], v[104:107]
	s_setprio 0
	s_setprio 1
	v_mfma_f32_16x16x32_bf16 v[100:103], v[136:139], v[160:163], v[100:103]
	v_mfma_f32_16x16x32_bf16 v[96:99], v[152:155], v[160:163], v[96:99]
	v_mfma_f32_16x16x32_bf16 v[92:95], v[136:139], v[186:189], v[92:95]
	v_mfma_f32_16x16x32_bf16 v[88:91], v[152:155], v[186:189], v[88:91]
	v_mfma_f32_16x16x32_bf16 v[84:87], v[136:139], v[202:205], v[84:87]
	v_mfma_f32_16x16x32_bf16 v[80:83], v[152:155], v[202:205], v[80:83]
	v_mfma_f32_16x16x32_bf16 v[76:79], v[136:139], v[210:213], v[76:79]
	v_mfma_f32_16x16x32_bf16 v[72:75], v[152:155], v[210:213], v[72:75]
	v_mfma_f32_16x16x32_bf16 v[100:103], v[148:151], v[182:185], v[100:103]
	v_mfma_f32_16x16x32_bf16 v[96:99], v[156:159], v[182:185], v[96:99]
	v_mfma_f32_16x16x32_bf16 v[92:95], v[148:151], v[190:193], v[92:95]
	v_mfma_f32_16x16x32_bf16 v[88:91], v[156:159], v[190:193], v[88:91]
	v_mfma_f32_16x16x32_bf16 v[84:87], v[148:151], v[206:209], v[84:87]
	v_mfma_f32_16x16x32_bf16 v[80:83], v[156:159], v[206:209], v[80:83]
	v_mfma_f32_16x16x32_bf16 v[76:79], v[148:151], v[214:217], v[76:79]
	v_mfma_f32_16x16x32_bf16 v[72:75], v[156:159], v[214:217], v[72:75]
	s_barrier
	s_setprio 0
	s_add_i32 s4, s62, s43
	v_lshl_add_u64 v[218:219], s[26:27], 0, v[168:169]
	s_mov_b32 m0, s4
	ds_read_b128 v[160:163], v199 offset:16384
	ds_read_b128 v[182:185], v199 offset:17408
	ds_read_b128 v[186:189], v199 offset:18432
	ds_read_b128 v[190:193], v199 offset:19456
	ds_read_b128 v[202:205], v199 offset:20480
	ds_read_b128 v[206:209], v199 offset:21504
	ds_read_b128 v[210:213], v199 offset:22528
	ds_read_b128 v[214:217], v199 offset:23552
	global_load_lds_dwordx4 v[218:219], off
	s_add_i32 m0, s4, 0x2000
	s_add_u32 s4, s26, 0x30000
	v_lshl_add_u64 v[220:221], s[26:27], 0, v[164:165]
	s_addc_u32 s5, s27, 0
	s_add_i32 s6, s63, s43
	global_load_lds_dwordx4 v[220:221], off
	v_lshl_add_u64 v[222:223], s[4:5], 0, v[168:169]
	s_mov_b32 m0, s6
	v_lshl_add_u64 v[224:225], s[30:31], 0, v[166:167]
	global_load_lds_dwordx4 v[222:223], off
	v_lshl_add_u64 v[222:223], s[4:5], 0, v[164:165]
	s_add_i32 m0, s6, 0x2000
	s_nop 0
	global_load_lds_dwordx4 v[222:223], off
	v_lshl_add_u64 v[222:223], s[30:31], 0, v[170:171]
	s_mov_b32 m0, s52
	s_nop 0
	global_load_lds_dwordx4 v[222:223], off
	s_mov_b32 m0, s53
	s_nop 0
	global_load_lds_dwordx4 v[224:225], off
	s_waitcnt vmcnt(8)
	s_waitcnt lgkmcnt(0)
	s_setprio 1
	s_waitcnt lgkmcnt(0)
	s_barrier
; #define PG8_STAGE(bufoff, gbase, voff) do { _Pragma("unroll") for (int _i = 0; _i < 2; ++_i) \
;         __builtin_amdgcn_global_load_lds((const unsigned*)((const char*)(gbase) + (voff)[_i]), (LAS unsigned*)(lds + (bufoff) + ldsw + _i * 8192), 16, 0, 0); } while (0)
; #define PG8_LDA(dst, b, h) do { _Pragma("unroll") for (int m = 0; m < 4; ++m) _Pragma("unroll") for (int k = 0; k < 2; ++k) dst[m][k] = *(const LAS bf16x8*)(lds + PG8_SA(b, h) + aoff + m * 2048 + k * 1024); } while (0)
; #define PG8_LDB(dst, b, h) do { _Pragma("unroll") for (int n = 0; n < 2; ++n) _Pragma("unroll") for (int k = 0; k < 2; ++k) dst[n][k] = *(const LAS bf16x8*)(lds + PG8_SB(b, h) + boff + n * 2048 + k * 1024); } while (0)
; #define PG8_MMA(ai, bj, At, Bt) do { __builtin_amdgcn_s_setprio(1); _Pragma("unroll") for (int m = 0; m < 4; ++m) _Pragma("unroll") for (int n = 0; n < 2; ++n) _Pragma("unroll") for (int k = 0; k < 2; ++k) \
;         acc[ai][bj][m][n] = __builtin_amdgcn_mfma_f32_16x16x32_bf16(Bt[n][k], At[m][k], acc[ai][bj][m][n], 0, 0, 0); __builtin_amdgcn_s_setprio(0); } while (0)
; #define PG8_WAIT_V(n) asm volatile("s_waitcnt vmcnt(" #n ")" ::: "memory")
; #define PG8_WAIT_L(n) asm volatile("s_waitcnt lgkmcnt(" #n ")" ::: "memory")
; #define PG8_BAR __builtin_amdgcn_s_barrier()
; #define PG8_SCHED __builtin_amdgcn_sched_barrier(0)
; template <class Epi, class Sched>
; __device__ __forceinline__ void gemm_phase(LAS unsigned char* lds, const Gemm g, const Sched& S, const Epi& E, const int tid) {
;     ...
;             PG8_WAIT_V(8); PG8_WAIT_L(0); PG8_BAR; PG8_MMA(1, 0, At, B0); PG8_MMA(1, 1, At, B1); PG8_BAR; PG8_SCHED;
;             PG8_LDB(B0, 1, 0); PG8_LDB(B1, 1, 1); PG8_SCHED; PG8_LDA(At, 1, 0); PG8_STAGE(PG8_SA(0, 1), a2 + hstepA, voffA);
;             PG8_WAIT_V(8); PG8_WAIT_L(0); PG8_BAR; PG8_MMA(0, 0, At, B0); PG8_MMA(0, 1, At, B1); PG8_BAR; PG8_SCHED;
	v_mfma_f32_16x16x32_bf16 v[68:71], v[40:43], v[160:163], v[68:71]
	v_mfma_f32_16x16x32_bf16 v[64:67], v[116:119], v[160:163], v[64:67]
	v_mfma_f32_16x16x32_bf16 v[60:63], v[40:43], v[186:189], v[60:63]
	v_mfma_f32_16x16x32_bf16 v[56:59], v[116:119], v[186:189], v[56:59]
	v_mfma_f32_16x16x32_bf16 v[52:55], v[40:43], v[202:205], v[52:55]
	v_mfma_f32_16x16x32_bf16 v[48:51], v[116:119], v[202:205], v[48:51]
	v_mfma_f32_16x16x32_bf16 v[36:39], v[40:43], v[210:213], v[36:39]
	v_mfma_f32_16x16x32_bf16 v[32:35], v[116:119], v[210:213], v[32:35]
	v_mfma_f32_16x16x32_bf16 v[68:71], v[44:47], v[182:185], v[68:71]
	v_mfma_f32_16x16x32_bf16 v[64:67], v[124:127], v[182:185], v[64:67]
	v_mfma_f32_16x16x32_bf16 v[60:63], v[44:47], v[190:193], v[60:63]
	v_mfma_f32_16x16x32_bf16 v[56:59], v[124:127], v[190:193], v[56:59]
	v_mfma_f32_16x16x32_bf16 v[52:55], v[44:47], v[206:209], v[52:55]
	v_mfma_f32_16x16x32_bf16 v[48:51], v[124:127], v[206:209], v[48:51]
	v_mfma_f32_16x16x32_bf16 v[36:39], v[44:47], v[214:217], v[36:39]
	v_mfma_f32_16x16x32_bf16 v[32:35], v[124:127], v[214:217], v[32:35]
	s_setprio 0
	s_setprio 1
	v_mfma_f32_16x16x32_bf16 v[28:31], v[136:139], v[160:163], v[28:31]
	v_mfma_f32_16x16x32_bf16 v[24:27], v[152:155], v[160:163], v[24:27]
	v_mfma_f32_16x16x32_bf16 v[20:23], v[136:139], v[186:189], v[20:23]
	v_mfma_f32_16x16x32_bf16 v[16:19], v[152:155], v[186:189], v[16:19]
	v_mfma_f32_16x16x32_bf16 v[12:15], v[136:139], v[202:205], v[12:15]
	v_mfma_f32_16x16x32_bf16 v[8:11], v[152:155], v[202:205], v[8:11]
	v_mfma_f32_16x16x32_bf16 v[4:7], v[136:139], v[210:213], v[4:7]
	v_mfma_f32_16x16x32_bf16 v[0:3], v[152:155], v[210:213], v[0:3]
	v_mfma_f32_16x16x32_bf16 v[28:31], v[148:151], v[182:185], v[28:31]
	v_mfma_f32_16x16x32_bf16 v[24:27], v[156:159], v[182:185], v[24:27]
	v_mfma_f32_16x16x32_bf16 v[20:23], v[148:151], v[190:193], v[20:23]
	v_mfma_f32_16x16x32_bf16 v[16:19], v[156:159], v[190:193], v[16:19]
	v_mfma_f32_16x16x32_bf16 v[12:15], v[148:151], v[206:209], v[12:15]
	v_mfma_f32_16x16x32_bf16 v[8:11], v[156:159], v[206:209], v[8:11]
	v_mfma_f32_16x16x32_bf16 v[4:7], v[148:151], v[214:217], v[4:7]
	v_mfma_f32_16x16x32_bf16 v[0:3], v[156:159], v[214:217], v[0:3]
	s_barrier
	s_setprio 0
	s_add_i32 s6, 0, 0x18000
	s_add_i32 s7, 0, 0x1c000
	v_add_u32_e32 v124, s6, v196
	v_add_u32_e32 v156, s7, v196
	ds_read_b128 v[40:43], v124
	ds_read_b128 v[44:47], v124 offset:1024
	ds_read_b128 v[116:119], v124 offset:2048
	ds_read_b128 v[124:127], v124 offset:3072
	ds_read_b128 v[136:139], v156
	ds_read_b128 v[148:151], v156 offset:1024
	ds_read_b128 v[152:155], v156 offset:2048
	ds_read_b128 v[156:159], v156 offset:3072
	s_add_u32 s4, s30, 0x30000
	s_addc_u32 s5, s31, 0
	s_mov_b32 m0, s54
	v_lshl_add_u64 v[226:227], s[4:5], 0, v[170:171]
	ds_read_b128 v[160:163], v199 offset:32768
	ds_read_b128 v[182:185], v199 offset:33792
	ds_read_b128 v[186:189], v199 offset:34816
	ds_read_b128 v[190:193], v199 offset:35840
	ds_read_b128 v[202:205], v199 offset:36864
	ds_read_b128 v[206:209], v199 offset:37888
	ds_read_b128 v[210:213], v199 offset:38912
	ds_read_b128 v[214:217], v199 offset:39936
	global_load_lds_dwordx4 v[226:227], off
	v_lshl_add_u64 v[226:227], s[4:5], 0, v[166:167]
	s_mov_b32 m0, s55
	s_nop 0
	global_load_lds_dwordx4 v[226:227], off
	s_waitcnt vmcnt(8)
	s_waitcnt lgkmcnt(0)
	s_setprio 1
	s_waitcnt lgkmcnt(0)
	s_barrier
	v_mfma_f32_16x16x32_bf16 v[144:147], v[40:43], v[160:163], v[144:147]
	v_mfma_f32_16x16x32_bf16 v[140:143], v[116:119], v[160:163], v[140:143]
	v_mfma_f32_16x16x32_bf16 v[132:135], v[40:43], v[186:189], v[132:135]
	v_mfma_f32_16x16x32_bf16 v[128:131], v[116:119], v[186:189], v[128:131]
	v_mfma_f32_16x16x32_bf16 v[120:123], v[40:43], v[202:205], v[120:123]
	v_mfma_f32_16x16x32_bf16 v[112:115], v[116:119], v[202:205], v[112:115]
	v_mfma_f32_16x16x32_bf16 v[108:111], v[40:43], v[210:213], v[108:111]
	v_mfma_f32_16x16x32_bf16 v[104:107], v[116:119], v[210:213], v[104:107]
	v_mfma_f32_16x16x32_bf16 v[144:147], v[44:47], v[182:185], v[144:147]
	v_mfma_f32_16x16x32_bf16 v[140:143], v[124:127], v[182:185], v[140:143]
	v_mfma_f32_16x16x32_bf16 v[132:135], v[44:47], v[190:193], v[132:135]
	v_mfma_f32_16x16x32_bf16 v[128:131], v[124:127], v[190:193], v[128:131]
	v_mfma_f32_16x16x32_bf16 v[120:123], v[44:47], v[206:209], v[120:123]
	v_mfma_f32_16x16x32_bf16 v[112:115], v[124:127], v[206:209], v[112:115]
	v_mfma_f32_16x16x32_bf16 v[108:111], v[44:47], v[214:217], v[108:111]
	v_mfma_f32_16x16x32_bf16 v[104:107], v[124:127], v[214:217], v[104:107]
	s_setprio 0
	s_setprio 1
	v_mfma_f32_16x16x32_bf16 v[100:103], v[136:139], v[160:163], v[100:103]
	v_mfma_f32_16x16x32_bf16 v[96:99], v[152:155], v[160:163], v[96:99]
	v_mfma_f32_16x16x32_bf16 v[92:95], v[136:139], v[186:189], v[92:95]
	v_mfma_f32_16x16x32_bf16 v[88:91], v[152:155], v[186:189], v[88:91]
	v_mfma_f32_16x16x32_bf16 v[84:87], v[136:139], v[202:205], v[84:87]
	v_mfma_f32_16x16x32_bf16 v[80:83], v[152:155], v[202:205], v[80:83]
	v_mfma_f32_16x16x32_bf16 v[76:79], v[136:139], v[210:213], v[76:79]
	v_mfma_f32_16x16x32_bf16 v[72:75], v[152:155], v[210:213], v[72:75]
	v_mfma_f32_16x16x32_bf16 v[100:103], v[148:151], v[182:185], v[100:103]
	v_mfma_f32_16x16x32_bf16 v[96:99], v[156:159], v[182:185], v[96:99]
	v_mfma_f32_16x16x32_bf16 v[92:95], v[148:151], v[190:193], v[92:95]
	v_mfma_f32_16x16x32_bf16 v[88:91], v[156:159], v[190:193], v[88:91]
	v_mfma_f32_16x16x32_bf16 v[84:87], v[148:151], v[206:209], v[84:87]
	v_mfma_f32_16x16x32_bf16 v[80:83], v[156:159], v[206:209], v[80:83]
	v_mfma_f32_16x16x32_bf16 v[76:79], v[148:151], v[214:217], v[76:79]
	v_mfma_f32_16x16x32_bf16 v[72:75], v[156:159], v[214:217], v[72:75]
	s_barrier
; #define PG8_STAGE(bufoff, gbase, voff) do { _Pragma("unroll") for (int _i = 0; _i < 2; ++_i) \
;         __builtin_amdgcn_global_load_lds((const unsigned*)((const char*)(gbase) + (voff)[_i]), (LAS unsigned*)(lds + (bufoff) + ldsw + _i * 8192), 16, 0, 0); } while (0)
; #define PG8_LDA(dst, b, h) do { _Pragma("unroll") for (int m = 0; m < 4; ++m) _Pragma("unroll") for (int k = 0; k < 2; ++k) dst[m][k] = *(const LAS bf16x8*)(lds + PG8_SA(b, h) + aoff + m * 2048 + k * 1024); } while (0)
; #define PG8_MMA(ai, bj, At, Bt) do { __builtin_amdgcn_s_setprio(1); _Pragma("unroll") for (int m = 0; m < 4; ++m) _Pragma("unroll") for (int n = 0; n < 2; ++n) _Pragma("unroll") for (int k = 0; k < 2; ++k) \
;         acc[ai][bj][m][n] = __builtin_amdgcn_mfma_f32_16x16x32_bf16(Bt[n][k], At[m][k], acc[ai][bj][m][n], 0, 0, 0); __builtin_amdgcn_s_setprio(0); } while (0)
; #define PG8_WAIT_V(n) asm volatile("s_waitcnt vmcnt(" #n ")" ::: "memory")
; #define PG8_WAIT_L(n) asm volatile("s_waitcnt lgkmcnt(" #n ")" ::: "memory")
; #define PG8_BAR __builtin_amdgcn_s_barrier()
; #define PG8_SCHED __builtin_amdgcn_sched_barrier(0)
; template <class Epi, class Sched>
; __device__ __forceinline__ void gemm_phase(LAS unsigned char* lds, const Gemm g, const Sched& S, const Epi& E, const int tid) {
;     ...
;             PG8_WAIT_V(8); PG8_WAIT_L(0); PG8_BAR; PG8_MMA(0, 0, At, B0); PG8_MMA(0, 1, At, B1); PG8_BAR; PG8_SCHED;
;             PG8_LDA(At, 1, 1); PG8_STAGE(PG8_SB(1, 0), b3, voffB); PG8_STAGE(PG8_SB(1, 1), b3 + hstepB, voffB); PG8_STAGE(PG8_SA(1, 0), a3, voffA);
;             PG8_WAIT_V(8); PG8_WAIT_L(0); PG8_BAR; PG8_MMA(1, 0, At, B0); PG8_MMA(1, 1, At, B1); PG8_BAR; PG8_SCHED;
;         }
;         if (wr == 0) PG8_BAR;
	s_setprio 0
	s_add_i32 s4, s6, s43
	v_lshl_add_u64 v[218:219], v[218:219], 0, s[36:37]
	s_mov_b32 m0, s4
	ds_read_b128 v[160:163], v199 offset:49152
	ds_read_b128 v[182:185], v199 offset:50176
	ds_read_b128 v[186:189], v199 offset:51200
	ds_read_b128 v[190:193], v199 offset:52224
	ds_read_b128 v[202:205], v199 offset:53248
	ds_read_b128 v[206:209], v199 offset:54272
	ds_read_b128 v[210:213], v199 offset:55296
	ds_read_b128 v[214:217], v199 offset:56320
	global_load_lds_dwordx4 v[218:219], off
	s_add_i32 m0, s4, 0x2000
	s_add_u32 s4, s26, 0x30080
	v_lshl_add_u64 v[218:219], v[220:221], 0, s[36:37]
	s_addc_u32 s5, s27, 0
	s_add_i32 s6, s7, s43
	global_load_lds_dwordx4 v[218:219], off
	v_lshl_add_u64 v[218:219], s[4:5], 0, v[168:169]
	s_mov_b32 m0, s6
	s_nop 0
	global_load_lds_dwordx4 v[218:219], off
	v_lshl_add_u64 v[218:219], s[4:5], 0, v[164:165]
	s_add_i32 m0, s6, 0x2000
	s_nop 0
	global_load_lds_dwordx4 v[218:219], off
	v_lshl_add_u64 v[218:219], v[222:223], 0, s[36:37]
	s_mov_b32 m0, s51
	s_nop 0
	global_load_lds_dwordx4 v[218:219], off
	v_lshl_add_u64 v[218:219], v[224:225], 0, s[36:37]
	s_mov_b32 m0, s60
	s_nop 0
	global_load_lds_dwordx4 v[218:219], off
	s_waitcnt vmcnt(8)
	s_waitcnt lgkmcnt(0)
	s_setprio 1
	s_waitcnt lgkmcnt(0)
	s_barrier
	v_mfma_f32_16x16x32_bf16 v[68:71], v[40:43], v[160:163], v[68:71]
	v_mfma_f32_16x16x32_bf16 v[64:67], v[116:119], v[160:163], v[64:67]
	v_mfma_f32_16x16x32_bf16 v[60:63], v[40:43], v[186:189], v[60:63]
	v_mfma_f32_16x16x32_bf16 v[56:59], v[116:119], v[186:189], v[56:59]
	v_mfma_f32_16x16x32_bf16 v[52:55], v[40:43], v[202:205], v[52:55]
	v_mfma_f32_16x16x32_bf16 v[48:51], v[116:119], v[202:205], v[48:51]
	v_mfma_f32_16x16x32_bf16 v[36:39], v[40:43], v[210:213], v[36:39]
	v_mfma_f32_16x16x32_bf16 v[32:35], v[116:119], v[210:213], v[32:35]
	v_mfma_f32_16x16x32_bf16 v[68:71], v[44:47], v[182:185], v[68:71]
	v_mfma_f32_16x16x32_bf16 v[64:67], v[124:127], v[182:185], v[64:67]
	v_mfma_f32_16x16x32_bf16 v[60:63], v[44:47], v[190:193], v[60:63]
	v_mfma_f32_16x16x32_bf16 v[56:59], v[124:127], v[190:193], v[56:59]
	v_mfma_f32_16x16x32_bf16 v[52:55], v[44:47], v[206:209], v[52:55]
	v_mfma_f32_16x16x32_bf16 v[48:51], v[124:127], v[206:209], v[48:51]
	v_mfma_f32_16x16x32_bf16 v[36:39], v[44:47], v[214:217], v[36:39]
	v_mfma_f32_16x16x32_bf16 v[32:35], v[124:127], v[214:217], v[32:35]
	s_setprio 0
	s_setprio 1
	v_mfma_f32_16x16x32_bf16 v[28:31], v[136:139], v[160:163], v[28:31]
	v_mfma_f32_16x16x32_bf16 v[24:27], v[152:155], v[160:163], v[24:27]
	v_mfma_f32_16x16x32_bf16 v[20:23], v[136:139], v[186:189], v[20:23]
	v_mfma_f32_16x16x32_bf16 v[16:19], v[152:155], v[186:189], v[16:19]
	v_mfma_f32_16x16x32_bf16 v[12:15], v[136:139], v[202:205], v[12:15]
	v_mfma_f32_16x16x32_bf16 v[8:11], v[152:155], v[202:205], v[8:11]
	v_mfma_f32_16x16x32_bf16 v[4:7], v[136:139], v[210:213], v[4:7]
	v_mfma_f32_16x16x32_bf16 v[0:3], v[152:155], v[210:213], v[0:3]
	v_mfma_f32_16x16x32_bf16 v[28:31], v[148:151], v[182:185], v[28:31]
	v_mfma_f32_16x16x32_bf16 v[24:27], v[156:159], v[182:185], v[24:27]
	v_mfma_f32_16x16x32_bf16 v[20:23], v[148:151], v[190:193], v[20:23]
	v_mfma_f32_16x16x32_bf16 v[16:19], v[156:159], v[190:193], v[16:19]
	v_mfma_f32_16x16x32_bf16 v[12:15], v[148:151], v[206:209], v[12:15]
	v_mfma_f32_16x16x32_bf16 v[8:11], v[156:159], v[206:209], v[8:11]
	v_mfma_f32_16x16x32_bf16 v[4:7], v[148:151], v[214:217], v[4:7]
	v_mfma_f32_16x16x32_bf16 v[0:3], v[156:159], v[214:217], v[0:3]
	s_barrier
	s_setprio 0
	s_add_i32 s88, s88, 2
	s_add_u32 s40, s40, 0x100
	s_addc_u32 s41, s41, 0
	s_cmp_gt_u32 s88, 9
	s_mov_b64 s[6:7], s[8:9]
	s_cbranch_scc0 .LBB0_936
	s_and_b64 vcc, exec, s[48:49]
	s_cbranch_vccz .LBB0_939
	s_barrier

; #define PG8_STAGE(bufoff, gbase, voff) do { _Pragma("unroll") for (int _i = 0; _i < 2; ++_i) \
;         __builtin_amdgcn_global_load_lds((const unsigned*)((const char*)(gbase) + (voff)[_i]), (LAS unsigned*)(lds + (bufoff) + ldsw + _i * 8192), 16, 0, 0); } while (0)
; #define PG8_LDA(dst, b, h) do { _Pragma("unroll") for (int m = 0; m < 4; ++m) _Pragma("unroll") for (int k = 0; k < 2; ++k) dst[m][k] = *(const LAS bf16x8*)(lds + PG8_SA(b, h) + aoff + m * 2048 + k * 1024); } while (0)
; #define PG8_LDB(dst, b, h) do { _Pragma("unroll") for (int n = 0; n < 2; ++n) _Pragma("unroll") for (int k = 0; k < 2; ++k) dst[n][k] = *(const LAS bf16x8*)(lds + PG8_SB(b, h) + boff + n * 2048 + k * 1024); } while (0)
; #define PG8_MMA(ai, bj, At, Bt) do { __builtin_amdgcn_s_setprio(1); _Pragma("unroll") for (int m = 0; m < 4; ++m) _Pragma("unroll") for (int n = 0; n < 2; ++n) _Pragma("unroll") for (int k = 0; k < 2; ++k) \
;         acc[ai][bj][m][n] = __builtin_amdgcn_mfma_f32_16x16x32_bf16(Bt[n][k], At[m][k], acc[ai][bj][m][n], 0, 0, 0); __builtin_amdgcn_s_setprio(0); } while (0)
; #define PG8_WAIT_V(n) asm volatile("s_waitcnt vmcnt(" #n ")" ::: "memory")
; #define PG8_WAIT_L(n) asm volatile("s_waitcnt lgkmcnt(" #n ")" ::: "memory")
; #define PG8_BAR __builtin_amdgcn_s_barrier()
; template <class Epi, class Sched>
; __device__ __forceinline__ void gemm_phase(LAS unsigned char* lds, const Gemm g, const Sched& S, const Epi& E, const int tid) {
;     ...
;             const bool last = (t == nt - 2);
;             const char* a1 = cA + (size_t)(t + 1) * kstepA;
;             const char* a2 = last ? nA : cA + (size_t)(t + 2) * kstepA; const char* b2 = last ? nB : cB + (size_t)(t + 2) * kstep;
;             const char* a3 = a2 + kstepA; const char* b3 = b2 + kstep;
;             if constexpr (Epi::HAS_MID) { if (t == g.tmid) E.mid(acc, cur, ui, wr, wc, fr, fq); }
;             PG8_LDB(B0, 0, 0); PG8_LDB(B1, 0, 1); PG8_SCHED; PG8_LDA(At, 0, 0); PG8_STAGE(PG8_SA(1, 1), a1 + hstepA, voffA);
;             PG8_WAIT_V(8); PG8_WAIT_L(0); PG8_BAR; PG8_MMA(0, 0, At, B0); PG8_MMA(0, 1, At, B1); PG8_BAR; PG8_SCHED;
;             PG8_LDA(At, 0, 1); PG8_STAGE(PG8_SB(0, 0), b2, voffB); PG8_STAGE(PG8_SB(0, 1), b2 + hstepB, voffB); PG8_STAGE(PG8_SA(0, 0), a2, voffA);
;             PG8_WAIT_V(8); PG8_WAIT_L(0); PG8_BAR; PG8_MMA(1, 0, At, B0); PG8_MMA(1, 1, At, B1); PG8_BAR; PG8_SCHED;
.LBB0_1040:
	ds_read_b128 v[84:87], v204
	ds_read_b128 v[92:95], v204 offset:1024
	ds_read_b128 v[136:139], v204 offset:2048
	ds_read_b128 v[140:143], v204 offset:3072
	ds_read_b128 v[144:147], v205
	ds_read_b128 v[148:151], v205 offset:1024
	ds_read_b128 v[152:155], v205 offset:2048
	ds_read_b128 v[156:159], v205 offset:3072
	s_add_u32 s40, s38, 0xa00000
	s_addc_u32 s41, s39, 0
	s_cmp_eq_u32 s75, 12
	s_cselect_b32 s52, s27, s40
	s_cselect_b32 s53, s9, s41
	s_cselect_b32 s50, s35, s72
	s_cselect_b32 s51, s25, s73
	s_add_u32 s48, s52, 0x500000
	s_addc_u32 s49, s53, 0
	v_lshl_add_u64 v[198:199], s[38:39], 0, v[174:175]
	s_add_i32 m0, s55, 0xc000
	ds_read_b128 v[160:163], v206
	ds_read_b128 v[182:185], v206 offset:1024
	ds_read_b128 v[186:189], v206 offset:2048
	ds_read_b128 v[190:193], v206 offset:3072
	ds_read_b128 v[194:197], v206 offset:4096
	ds_read_b128 v[208:211], v206 offset:5120
	ds_read_b128 v[212:215], v206 offset:6144
	ds_read_b128 v[216:219], v206 offset:7168
	global_load_lds_dwordx4 v[198:199], off
	v_lshl_add_u64 v[198:199], s[38:39], 0, v[176:177]
	s_add_i32 m0, s55, 0xe000
	s_nop 0
	global_load_lds_dwordx4 v[198:199], off
	s_waitcnt vmcnt(8)
	s_waitcnt lgkmcnt(0)
	s_setprio 1
	s_waitcnt lgkmcnt(0)
	s_barrier
	v_mfma_f32_16x16x32_bf16 v[132:135], v[84:87], v[160:163], v[132:135]
	v_mfma_f32_16x16x32_bf16 v[128:131], v[136:139], v[160:163], v[128:131]
	v_mfma_f32_16x16x32_bf16 v[124:127], v[84:87], v[186:189], v[124:127]
	v_mfma_f32_16x16x32_bf16 v[120:123], v[136:139], v[186:189], v[120:123]
	v_mfma_f32_16x16x32_bf16 v[116:119], v[84:87], v[194:197], v[116:119]
	v_mfma_f32_16x16x32_bf16 v[112:115], v[136:139], v[194:197], v[112:115]
	v_mfma_f32_16x16x32_bf16 v[108:111], v[84:87], v[212:215], v[108:111]
	v_mfma_f32_16x16x32_bf16 v[104:107], v[136:139], v[212:215], v[104:107]
	v_mfma_f32_16x16x32_bf16 v[132:135], v[92:95], v[182:185], v[132:135]
	v_mfma_f32_16x16x32_bf16 v[128:131], v[140:143], v[182:185], v[128:131]
	v_mfma_f32_16x16x32_bf16 v[124:127], v[92:95], v[190:193], v[124:127]
	v_mfma_f32_16x16x32_bf16 v[120:123], v[140:143], v[190:193], v[120:123]
	v_mfma_f32_16x16x32_bf16 v[116:119], v[92:95], v[208:211], v[116:119]
	v_mfma_f32_16x16x32_bf16 v[112:115], v[140:143], v[208:211], v[112:115]
	v_mfma_f32_16x16x32_bf16 v[108:111], v[92:95], v[216:219], v[108:111]
	v_mfma_f32_16x16x32_bf16 v[104:107], v[140:143], v[216:219], v[104:107]
	s_setprio 0
	s_setprio 1
	v_mfma_f32_16x16x32_bf16 v[60:63], v[144:147], v[160:163], v[60:63]
	v_mfma_f32_16x16x32_bf16 v[56:59], v[152:155], v[160:163], v[56:59]
	v_mfma_f32_16x16x32_bf16 v[52:55], v[144:147], v[186:189], v[52:55]
	v_mfma_f32_16x16x32_bf16 v[48:51], v[152:155], v[186:189], v[48:51]
	v_mfma_f32_16x16x32_bf16 v[44:47], v[144:147], v[194:197], v[44:47]
	v_mfma_f32_16x16x32_bf16 v[40:43], v[152:155], v[194:197], v[40:43]
	v_mfma_f32_16x16x32_bf16 v[36:39], v[144:147], v[212:215], v[36:39]
	v_mfma_f32_16x16x32_bf16 v[32:35], v[152:155], v[212:215], v[32:35]
	v_mfma_f32_16x16x32_bf16 v[60:63], v[148:151], v[182:185], v[60:63]
	v_mfma_f32_16x16x32_bf16 v[56:59], v[156:159], v[182:185], v[56:59]
	v_mfma_f32_16x16x32_bf16 v[52:55], v[148:151], v[190:193], v[52:55]
	v_mfma_f32_16x16x32_bf16 v[48:51], v[156:159], v[190:193], v[48:51]
	v_mfma_f32_16x16x32_bf16 v[44:47], v[148:151], v[208:211], v[44:47]
	v_mfma_f32_16x16x32_bf16 v[40:43], v[156:159], v[208:211], v[40:43]
	v_mfma_f32_16x16x32_bf16 v[36:39], v[148:151], v[216:219], v[36:39]
	v_mfma_f32_16x16x32_bf16 v[32:35], v[156:159], v[216:219], v[32:35]
	s_barrier
	s_setprio 0
	s_add_i32 s16, s69, s54
	v_lshl_add_u64 v[198:199], s[50:51], 0, v[166:167]
	s_mov_b32 m0, s16
	ds_read_b128 v[160:163], v206 offset:16384
	ds_read_b128 v[182:185], v206 offset:17408
	ds_read_b128 v[186:189], v206 offset:18432
	ds_read_b128 v[190:193], v206 offset:19456
	ds_read_b128 v[194:197], v206 offset:20480
	ds_read_b128 v[208:211], v206 offset:21504
	ds_read_b128 v[212:215], v206 offset:22528
	ds_read_b128 v[216:219], v206 offset:23552
	global_load_lds_dwordx4 v[198:199], off
	s_add_i32 m0, s16, 0x2000
	s_add_u32 s16, s50, 0x40000
	v_lshl_add_u64 v[220:221], s[50:51], 0, v[170:171]
	s_addc_u32 s17, s51, 0
	s_add_i32 s20, s43, s54
	global_load_lds_dwordx4 v[220:221], off
	v_lshl_add_u64 v[222:223], s[16:17], 0, v[166:167]
	s_mov_b32 m0, s20
	s_nop 0
	global_load_lds_dwordx4 v[222:223], off
	v_lshl_add_u64 v[222:223], s[16:17], 0, v[170:171]
	s_add_i32 m0, s20, 0x2000
	s_nop 0
	global_load_lds_dwordx4 v[222:223], off
	v_lshl_add_u64 v[222:223], s[52:53], 0, v[164:165]
	s_mov_b32 m0, s55
	s_nop 0
	global_load_lds_dwordx4 v[222:223], off
	v_lshl_add_u64 v[222:223], s[52:53], 0, v[168:169]
	s_mov_b32 m0, s56
	s_nop 0
	global_load_lds_dwordx4 v[222:223], off
	s_waitcnt vmcnt(8)
	s_waitcnt lgkmcnt(0)
	s_setprio 1
	s_waitcnt lgkmcnt(0)
	s_barrier
; #define PG8_STAGE(bufoff, gbase, voff) do { _Pragma("unroll") for (int _i = 0; _i < 2; ++_i) \
;         __builtin_amdgcn_global_load_lds((const unsigned*)((const char*)(gbase) + (voff)[_i]), (LAS unsigned*)(lds + (bufoff) + ldsw + _i * 8192), 16, 0, 0); } while (0)
; #define PG8_LDA(dst, b, h) do { _Pragma("unroll") for (int m = 0; m < 4; ++m) _Pragma("unroll") for (int k = 0; k < 2; ++k) dst[m][k] = *(const LAS bf16x8*)(lds + PG8_SA(b, h) + aoff + m * 2048 + k * 1024); } while (0)
; #define PG8_LDB(dst, b, h) do { _Pragma("unroll") for (int n = 0; n < 2; ++n) _Pragma("unroll") for (int k = 0; k < 2; ++k) dst[n][k] = *(const LAS bf16x8*)(lds + PG8_SB(b, h) + boff + n * 2048 + k * 1024); } while (0)
; #define PG8_MMA(ai, bj, At, Bt) do { __builtin_amdgcn_s_setprio(1); _Pragma("unroll") for (int m = 0; m < 4; ++m) _Pragma("unroll") for (int n = 0; n < 2; ++n) _Pragma("unroll") for (int k = 0; k < 2; ++k) \
;         acc[ai][bj][m][n] = __builtin_amdgcn_mfma_f32_16x16x32_bf16(Bt[n][k], At[m][k], acc[ai][bj][m][n], 0, 0, 0); __builtin_amdgcn_s_setprio(0); } while (0)
; #define PG8_WAIT_V(n) asm volatile("s_waitcnt vmcnt(" #n ")" ::: "memory")
; #define PG8_WAIT_L(n) asm volatile("s_waitcnt lgkmcnt(" #n ")" ::: "memory")
; #define PG8_BAR __builtin_amdgcn_s_barrier()
; #define PG8_SCHED __builtin_amdgcn_sched_barrier(0)
; template <class Epi, class Sched>
; __device__ __forceinline__ void gemm_phase(LAS unsigned char* lds, const Gemm g, const Sched& S, const Epi& E, const int tid) {
;     ...
;             PG8_WAIT_V(8); PG8_WAIT_L(0); PG8_BAR; PG8_MMA(1, 0, At, B0); PG8_MMA(1, 1, At, B1); PG8_BAR; PG8_SCHED;
;             PG8_LDB(B0, 1, 0); PG8_LDB(B1, 1, 1); PG8_SCHED; PG8_LDA(At, 1, 0); PG8_STAGE(PG8_SA(0, 1), a2 + hstepA, voffA);
;             PG8_WAIT_V(8); PG8_WAIT_L(0); PG8_BAR; PG8_MMA(0, 0, At, B0); PG8_MMA(0, 1, At, B1); PG8_BAR; PG8_SCHED;
	v_mfma_f32_16x16x32_bf16 v[100:103], v[84:87], v[160:163], v[100:103]
	v_mfma_f32_16x16x32_bf16 v[96:99], v[136:139], v[160:163], v[96:99]
	v_mfma_f32_16x16x32_bf16 v[88:91], v[84:87], v[186:189], v[88:91]
	v_mfma_f32_16x16x32_bf16 v[80:83], v[136:139], v[186:189], v[80:83]
	v_mfma_f32_16x16x32_bf16 v[76:79], v[84:87], v[194:197], v[76:79]
	v_mfma_f32_16x16x32_bf16 v[72:75], v[136:139], v[194:197], v[72:75]
	v_mfma_f32_16x16x32_bf16 v[68:71], v[84:87], v[212:215], v[68:71]
	v_mfma_f32_16x16x32_bf16 v[64:67], v[136:139], v[212:215], v[64:67]
	v_mfma_f32_16x16x32_bf16 v[100:103], v[92:95], v[182:185], v[100:103]
	v_mfma_f32_16x16x32_bf16 v[96:99], v[140:143], v[182:185], v[96:99]
	v_mfma_f32_16x16x32_bf16 v[88:91], v[92:95], v[190:193], v[88:91]
	v_mfma_f32_16x16x32_bf16 v[80:83], v[140:143], v[190:193], v[80:83]
	v_mfma_f32_16x16x32_bf16 v[76:79], v[92:95], v[208:211], v[76:79]
	v_mfma_f32_16x16x32_bf16 v[72:75], v[140:143], v[208:211], v[72:75]
	v_mfma_f32_16x16x32_bf16 v[68:71], v[92:95], v[216:219], v[68:71]
	v_mfma_f32_16x16x32_bf16 v[64:67], v[140:143], v[216:219], v[64:67]
	s_setprio 0
	s_setprio 1
	v_mfma_f32_16x16x32_bf16 v[28:31], v[144:147], v[160:163], v[28:31]
	v_mfma_f32_16x16x32_bf16 v[24:27], v[152:155], v[160:163], v[24:27]
	v_mfma_f32_16x16x32_bf16 v[20:23], v[144:147], v[186:189], v[20:23]
	v_mfma_f32_16x16x32_bf16 v[16:19], v[152:155], v[186:189], v[16:19]
	v_mfma_f32_16x16x32_bf16 v[12:15], v[144:147], v[194:197], v[12:15]
	v_mfma_f32_16x16x32_bf16 v[8:11], v[152:155], v[194:197], v[8:11]
	v_mfma_f32_16x16x32_bf16 v[4:7], v[144:147], v[212:215], v[4:7]
	v_mfma_f32_16x16x32_bf16 v[0:3], v[152:155], v[212:215], v[0:3]
	v_mfma_f32_16x16x32_bf16 v[28:31], v[148:151], v[182:185], v[28:31]
	v_mfma_f32_16x16x32_bf16 v[24:27], v[156:159], v[182:185], v[24:27]
	v_mfma_f32_16x16x32_bf16 v[20:23], v[148:151], v[190:193], v[20:23]
	v_mfma_f32_16x16x32_bf16 v[16:19], v[156:159], v[190:193], v[16:19]
	v_mfma_f32_16x16x32_bf16 v[12:15], v[148:151], v[208:211], v[12:15]
	v_mfma_f32_16x16x32_bf16 v[8:11], v[156:159], v[208:211], v[8:11]
	v_mfma_f32_16x16x32_bf16 v[4:7], v[148:151], v[216:219], v[4:7]
	v_mfma_f32_16x16x32_bf16 v[0:3], v[156:159], v[216:219], v[0:3]
	s_barrier
	s_setprio 0
	s_add_i32 s20, 0, 0x18000
	s_add_i32 s21, 0, 0x1c000
	v_add_u32_e32 v140, s20, v203
	v_add_u32_e32 v156, s21, v203
	ds_read_b128 v[84:87], v140
	ds_read_b128 v[92:95], v140 offset:1024
	ds_read_b128 v[136:139], v140 offset:2048
	ds_read_b128 v[140:143], v140 offset:3072
	ds_read_b128 v[144:147], v156
	ds_read_b128 v[148:151], v156 offset:1024
	ds_read_b128 v[152:155], v156 offset:2048
	ds_read_b128 v[156:159], v156 offset:3072
	s_add_u32 s16, s52, 0x1000
	s_addc_u32 s17, s53, 0
	s_mov_b32 m0, s57
	v_lshl_add_u64 v[222:223], s[16:17], 0, v[164:165]
	ds_read_b128 v[160:163], v206 offset:32768
	ds_read_b128 v[182:185], v206 offset:33792
	ds_read_b128 v[186:189], v206 offset:34816
	ds_read_b128 v[190:193], v206 offset:35840
	ds_read_b128 v[194:197], v206 offset:36864
	ds_read_b128 v[208:211], v206 offset:37888
	ds_read_b128 v[212:215], v206 offset:38912
	ds_read_b128 v[216:219], v206 offset:39936
	global_load_lds_dwordx4 v[222:223], off
	v_lshl_add_u64 v[222:223], s[16:17], 0, v[168:169]
	s_mov_b32 m0, s58
	s_nop 0
	global_load_lds_dwordx4 v[222:223], off
	s_waitcnt vmcnt(8)
	s_waitcnt lgkmcnt(0)
	s_setprio 1
	s_waitcnt lgkmcnt(0)
	s_barrier
	v_mfma_f32_16x16x32_bf16 v[132:135], v[84:87], v[160:163], v[132:135]
	v_mfma_f32_16x16x32_bf16 v[128:131], v[136:139], v[160:163], v[128:131]
	v_mfma_f32_16x16x32_bf16 v[124:127], v[84:87], v[186:189], v[124:127]
	v_mfma_f32_16x16x32_bf16 v[120:123], v[136:139], v[186:189], v[120:123]
	v_mfma_f32_16x16x32_bf16 v[116:119], v[84:87], v[194:197], v[116:119]
	v_mfma_f32_16x16x32_bf16 v[112:115], v[136:139], v[194:197], v[112:115]
	v_mfma_f32_16x16x32_bf16 v[108:111], v[84:87], v[212:215], v[108:111]
	v_mfma_f32_16x16x32_bf16 v[104:107], v[136:139], v[212:215], v[104:107]
	v_mfma_f32_16x16x32_bf16 v[132:135], v[92:95], v[182:185], v[132:135]
	v_mfma_f32_16x16x32_bf16 v[128:131], v[140:143], v[182:185], v[128:131]
	v_mfma_f32_16x16x32_bf16 v[124:127], v[92:95], v[190:193], v[124:127]
	v_mfma_f32_16x16x32_bf16 v[120:123], v[140:143], v[190:193], v[120:123]
	v_mfma_f32_16x16x32_bf16 v[116:119], v[92:95], v[208:211], v[116:119]
	v_mfma_f32_16x16x32_bf16 v[112:115], v[140:143], v[208:211], v[112:115]
	v_mfma_f32_16x16x32_bf16 v[108:111], v[92:95], v[216:219], v[108:111]
	v_mfma_f32_16x16x32_bf16 v[104:107], v[140:143], v[216:219], v[104:107]
	s_setprio 0
	s_setprio 1
	v_mfma_f32_16x16x32_bf16 v[60:63], v[144:147], v[160:163], v[60:63]
	v_mfma_f32_16x16x32_bf16 v[56:59], v[152:155], v[160:163], v[56:59]
	v_mfma_f32_16x16x32_bf16 v[52:55], v[144:147], v[186:189], v[52:55]
	v_mfma_f32_16x16x32_bf16 v[48:51], v[152:155], v[186:189], v[48:51]
	v_mfma_f32_16x16x32_bf16 v[44:47], v[144:147], v[194:197], v[44:47]
	v_mfma_f32_16x16x32_bf16 v[40:43], v[152:155], v[194:197], v[40:43]
	v_mfma_f32_16x16x32_bf16 v[36:39], v[144:147], v[212:215], v[36:39]
	v_mfma_f32_16x16x32_bf16 v[32:35], v[152:155], v[212:215], v[32:35]
	v_mfma_f32_16x16x32_bf16 v[60:63], v[148:151], v[182:185], v[60:63]
	v_mfma_f32_16x16x32_bf16 v[56:59], v[156:159], v[182:185], v[56:59]
	v_mfma_f32_16x16x32_bf16 v[52:55], v[148:151], v[190:193], v[52:55]
	v_mfma_f32_16x16x32_bf16 v[48:51], v[156:159], v[190:193], v[48:51]
	v_mfma_f32_16x16x32_bf16 v[44:47], v[148:151], v[208:211], v[44:47]
	v_mfma_f32_16x16x32_bf16 v[40:43], v[156:159], v[208:211], v[40:43]
	v_mfma_f32_16x16x32_bf16 v[36:39], v[148:151], v[216:219], v[36:39]
	v_mfma_f32_16x16x32_bf16 v[32:35], v[156:159], v[216:219], v[32:35]
	s_barrier
; #define PG8_STAGE(bufoff, gbase, voff) do { _Pragma("unroll") for (int _i = 0; _i < 2; ++_i) \
;         __builtin_amdgcn_global_load_lds((const unsigned*)((const char*)(gbase) + (voff)[_i]), (LAS unsigned*)(lds + (bufoff) + ldsw + _i * 8192), 16, 0, 0); } while (0)
; #define PG8_LDA(dst, b, h) do { _Pragma("unroll") for (int m = 0; m < 4; ++m) _Pragma("unroll") for (int k = 0; k < 2; ++k) dst[m][k] = *(const LAS bf16x8*)(lds + PG8_SA(b, h) + aoff + m * 2048 + k * 1024); } while (0)
; #define PG8_MMA(ai, bj, At, Bt) do { __builtin_amdgcn_s_setprio(1); _Pragma("unroll") for (int m = 0; m < 4; ++m) _Pragma("unroll") for (int n = 0; n < 2; ++n) _Pragma("unroll") for (int k = 0; k < 2; ++k) \
;         acc[ai][bj][m][n] = __builtin_amdgcn_mfma_f32_16x16x32_bf16(Bt[n][k], At[m][k], acc[ai][bj][m][n], 0, 0, 0); __builtin_amdgcn_s_setprio(0); } while (0)
; #define PG8_WAIT_V(n) asm volatile("s_waitcnt vmcnt(" #n ")" ::: "memory")
; #define PG8_WAIT_L(n) asm volatile("s_waitcnt lgkmcnt(" #n ")" ::: "memory")
; #define PG8_BAR __builtin_amdgcn_s_barrier()
; #define PG8_SCHED __builtin_amdgcn_sched_barrier(0)
; template <class Epi, class Sched>
; __device__ __forceinline__ void gemm_phase(LAS unsigned char* lds, const Gemm g, const Sched& S, const Epi& E, const int tid) {
;     ...
;             PG8_WAIT_V(8); PG8_WAIT_L(0); PG8_BAR; PG8_MMA(0, 0, At, B0); PG8_MMA(0, 1, At, B1); PG8_BAR; PG8_SCHED;
;             PG8_LDA(At, 1, 1); PG8_STAGE(PG8_SB(1, 0), b3, voffB); PG8_STAGE(PG8_SB(1, 1), b3 + hstepB, voffB); PG8_STAGE(PG8_SA(1, 0), a3, voffA);
;             PG8_WAIT_V(8); PG8_WAIT_L(0); PG8_BAR; PG8_MMA(1, 0, At, B0); PG8_MMA(1, 1, At, B1); PG8_BAR; PG8_SCHED;
;         }
;         if (wr == 0) PG8_BAR;
	s_setprio 0
	s_add_i32 s16, s20, s54
	v_lshl_add_u64 v[198:199], v[198:199], 0, s[4:5]
	s_mov_b32 m0, s16
	ds_read_b128 v[160:163], v206 offset:49152
	ds_read_b128 v[182:185], v206 offset:50176
	ds_read_b128 v[186:189], v206 offset:51200
	ds_read_b128 v[190:193], v206 offset:52224
	ds_read_b128 v[194:197], v206 offset:53248
	ds_read_b128 v[208:211], v206 offset:54272
	ds_read_b128 v[212:215], v206 offset:55296
	ds_read_b128 v[216:219], v206 offset:56320
	global_load_lds_dwordx4 v[198:199], off
	s_add_i32 m0, s16, 0x2000
	s_add_u32 s16, s50, 0x40080
	v_lshl_add_u64 v[198:199], v[220:221], 0, s[4:5]
	s_addc_u32 s17, s51, 0
	s_add_i32 s20, s21, s54
	global_load_lds_dwordx4 v[198:199], off
	v_lshl_add_u64 v[198:199], s[16:17], 0, v[166:167]
	s_mov_b32 m0, s20
	s_nop 0
	global_load_lds_dwordx4 v[198:199], off
	v_lshl_add_u64 v[198:199], s[16:17], 0, v[170:171]
	s_add_i32 m0, s20, 0x2000
	s_nop 0
	global_load_lds_dwordx4 v[198:199], off
	v_lshl_add_u64 v[198:199], s[48:49], 0, v[164:165]
	s_mov_b32 m0, s62
	s_nop 0
	global_load_lds_dwordx4 v[198:199], off
	v_lshl_add_u64 v[198:199], s[48:49], 0, v[168:169]
	s_mov_b32 m0, s64
	s_nop 0
	global_load_lds_dwordx4 v[198:199], off
	s_waitcnt vmcnt(8)
	s_waitcnt lgkmcnt(0)
	s_setprio 1
	s_waitcnt lgkmcnt(0)
	s_barrier
	v_mfma_f32_16x16x32_bf16 v[100:103], v[84:87], v[160:163], v[100:103]
	v_mfma_f32_16x16x32_bf16 v[96:99], v[136:139], v[160:163], v[96:99]
	v_mfma_f32_16x16x32_bf16 v[88:91], v[84:87], v[186:189], v[88:91]
	v_mfma_f32_16x16x32_bf16 v[80:83], v[136:139], v[186:189], v[80:83]
	v_mfma_f32_16x16x32_bf16 v[76:79], v[84:87], v[194:197], v[76:79]
	v_mfma_f32_16x16x32_bf16 v[72:75], v[136:139], v[194:197], v[72:75]
	v_mfma_f32_16x16x32_bf16 v[68:71], v[84:87], v[212:215], v[68:71]
	v_mfma_f32_16x16x32_bf16 v[64:67], v[136:139], v[212:215], v[64:67]
	v_mfma_f32_16x16x32_bf16 v[100:103], v[92:95], v[182:185], v[100:103]
	v_mfma_f32_16x16x32_bf16 v[96:99], v[140:143], v[182:185], v[96:99]
	v_mfma_f32_16x16x32_bf16 v[88:91], v[92:95], v[190:193], v[88:91]
	v_mfma_f32_16x16x32_bf16 v[80:83], v[140:143], v[190:193], v[80:83]
	v_mfma_f32_16x16x32_bf16 v[76:79], v[92:95], v[208:211], v[76:79]
	v_mfma_f32_16x16x32_bf16 v[72:75], v[140:143], v[208:211], v[72:75]
	v_mfma_f32_16x16x32_bf16 v[68:71], v[92:95], v[216:219], v[68:71]
	v_mfma_f32_16x16x32_bf16 v[64:67], v[140:143], v[216:219], v[64:67]
	s_setprio 0
	s_setprio 1
	v_mfma_f32_16x16x32_bf16 v[28:31], v[144:147], v[160:163], v[28:31]
	v_mfma_f32_16x16x32_bf16 v[24:27], v[152:155], v[160:163], v[24:27]
	v_mfma_f32_16x16x32_bf16 v[20:23], v[144:147], v[186:189], v[20:23]
	v_mfma_f32_16x16x32_bf16 v[16:19], v[152:155], v[186:189], v[16:19]
	v_mfma_f32_16x16x32_bf16 v[12:15], v[144:147], v[194:197], v[12:15]
	v_mfma_f32_16x16x32_bf16 v[8:11], v[152:155], v[194:197], v[8:11]
	v_mfma_f32_16x16x32_bf16 v[4:7], v[144:147], v[212:215], v[4:7]
	v_mfma_f32_16x16x32_bf16 v[0:3], v[152:155], v[212:215], v[0:3]
	v_mfma_f32_16x16x32_bf16 v[28:31], v[148:151], v[182:185], v[28:31]
	v_mfma_f32_16x16x32_bf16 v[24:27], v[156:159], v[182:185], v[24:27]
	v_mfma_f32_16x16x32_bf16 v[20:23], v[148:151], v[190:193], v[20:23]
	v_mfma_f32_16x16x32_bf16 v[16:19], v[156:159], v[190:193], v[16:19]
	v_mfma_f32_16x16x32_bf16 v[12:15], v[148:151], v[208:211], v[12:15]
	v_mfma_f32_16x16x32_bf16 v[8:11], v[156:159], v[208:211], v[8:11]
	v_mfma_f32_16x16x32_bf16 v[4:7], v[148:151], v[216:219], v[4:7]
	v_mfma_f32_16x16x32_bf16 v[0:3], v[156:159], v[216:219], v[0:3]
	s_barrier
	s_setprio 0
	s_add_i32 s75, s75, 2
	s_add_u32 s72, s72, 0x100
	s_addc_u32 s73, s73, 0
	s_cmp_gt_u32 s75, 13
	s_mov_b64 s[38:39], s[40:41]
	s_cbranch_scc0 .LBB0_1040
	s_and_b64 vcc, exec, s[6:7]
	s_cbranch_vccz .LBB0_1043
	s_barrier

; #define PG8_STAGE(bufoff, gbase, voff) do { _Pragma("unroll") for (int _i = 0; _i < 2; ++_i) \
;         __builtin_amdgcn_global_load_lds((const unsigned*)((const char*)(gbase) + (voff)[_i]), (LAS unsigned*)(lds + (bufoff) + ldsw + _i * 8192), 16, 0, 0); } while (0)
; #define PG8_LDA(dst, b, h) do { _Pragma("unroll") for (int m = 0; m < 4; ++m) _Pragma("unroll") for (int k = 0; k < 2; ++k) dst[m][k] = *(const LAS bf16x8*)(lds + PG8_SA(b, h) + aoff + m * 2048 + k * 1024); } while (0)
; #define PG8_LDB(dst, b, h) do { _Pragma("unroll") for (int n = 0; n < 2; ++n) _Pragma("unroll") for (int k = 0; k < 2; ++k) dst[n][k] = *(const LAS bf16x8*)(lds + PG8_SB(b, h) + boff + n * 2048 + k * 1024); } while (0)
; #define PG8_MMA(ai, bj, At, Bt) do { __builtin_amdgcn_s_setprio(1); _Pragma("unroll") for (int m = 0; m < 4; ++m) _Pragma("unroll") for (int n = 0; n < 2; ++n) _Pragma("unroll") for (int k = 0; k < 2; ++k) \
;         acc[ai][bj][m][n] = __builtin_amdgcn_mfma_f32_16x16x32_bf16(Bt[n][k], At[m][k], acc[ai][bj][m][n], 0, 0, 0); __builtin_amdgcn_s_setprio(0); } while (0)
; #define PG8_WAIT_V(n) asm volatile("s_waitcnt vmcnt(" #n ")" ::: "memory")
; #define PG8_WAIT_L(n) asm volatile("s_waitcnt lgkmcnt(" #n ")" ::: "memory")
; #define PG8_BAR __builtin_amdgcn_s_barrier()
; template <class Epi, class Sched>
; __device__ __forceinline__ void gemm_phase(LAS unsigned char* lds, const Gemm g, const Sched& S, const Epi& E, const int tid) {
;     ...
;             const bool last = (t == nt - 2);
;             const char* a1 = cA + (size_t)(t + 1) * kstepA;
;             const char* a2 = last ? nA : cA + (size_t)(t + 2) * kstepA; const char* b2 = last ? nB : cB + (size_t)(t + 2) * kstep;
;             const char* a3 = a2 + kstepA; const char* b3 = b2 + kstep;
;             if constexpr (Epi::HAS_MID) { if (t == g.tmid) E.mid(acc, cur, ui, wr, wc, fr, fq); }
;             PG8_LDB(B0, 0, 0); PG8_LDB(B1, 0, 1); PG8_SCHED; PG8_LDA(At, 0, 0); PG8_STAGE(PG8_SA(1, 1), a1 + hstepA, voffA);
;             PG8_WAIT_V(8); PG8_WAIT_L(0); PG8_BAR; PG8_MMA(0, 0, At, B0); PG8_MMA(0, 1, At, B1); PG8_BAR; PG8_SCHED;
;             PG8_LDA(At, 0, 1); PG8_STAGE(PG8_SB(0, 0), b2, voffB); PG8_STAGE(PG8_SB(0, 1), b2 + hstepB, voffB); PG8_STAGE(PG8_SA(0, 0), a2, voffA);
;             PG8_WAIT_V(8); PG8_WAIT_L(0); PG8_BAR; PG8_MMA(1, 0, At, B0); PG8_MMA(1, 1, At, B1); PG8_BAR; PG8_SCHED;
.LBB0_1150:
	v_add_u32_e32 v1, s67, v252
	ds_read_b128 v[132:135], v1
	ds_read_b128 v[136:139], v1 offset:1024
	ds_read_b128 v[140:143], v1 offset:2048
	ds_read_b128 v[144:147], v1 offset:3072
	v_add_u32_e32 v1, s68, v252
	s_add_u32 s16, s38, s50
	ds_read_b128 v[148:151], v1
	ds_read_b128 v[156:159], v1 offset:1024
	ds_read_b128 v[164:167], v1 offset:2048
	ds_read_b128 v[168:171], v1 offset:3072
	s_addc_u32 s17, s39, s51
	s_add_u32 s16, s16, 0x100
	s_addc_u32 s17, s17, 0
	s_add_u32 s20, s70, s50
	s_addc_u32 s21, s71, s51
	s_cmpk_eq_i32 s50, 0xf00
	s_cselect_b32 s55, s7, s17
	s_cselect_b32 s54, s9, s16
	s_cselect_b32 s53, s18, s21
	s_cselect_b32 s52, s35, s20
	v_lshl_add_u64 v[2:3], v[68:69], 0, s[50:51]
	s_add_i32 m0, s56, 0xc000
	ds_read_b128 v[172:175], v208
	ds_read_b128 v[176:179], v208 offset:1024
	ds_read_b128 v[180:183], v208 offset:2048
	ds_read_b128 v[184:187], v208 offset:3072
	ds_read_b128 v[188:191], v208 offset:4096
	ds_read_b128 v[192:195], v208 offset:5120
	ds_read_b128 v[210:213], v208 offset:6144
	ds_read_b128 v[214:217], v208 offset:7168
	global_load_lds_dwordx4 v[2:3], off
	v_lshl_add_u64 v[2:3], v[70:71], 0, s[50:51]
	s_add_i32 m0, s56, 0xe000
	s_nop 0
	global_load_lds_dwordx4 v[2:3], off
	s_waitcnt vmcnt(8)
	s_waitcnt lgkmcnt(0)
	s_setprio 1
	s_waitcnt lgkmcnt(0)
	s_barrier
	v_mfma_f32_16x16x32_bf16 v[160:163], v[132:135], v[172:175], v[160:163]
	v_mfma_f32_16x16x32_bf16 v[152:155], v[140:143], v[172:175], v[152:155]
	v_mfma_f32_16x16x32_bf16 v[128:131], v[132:135], v[180:183], v[128:131]
	v_mfma_f32_16x16x32_bf16 v[124:127], v[140:143], v[180:183], v[124:127]
	v_mfma_f32_16x16x32_bf16 v[120:123], v[132:135], v[188:191], v[120:123]
	v_mfma_f32_16x16x32_bf16 v[116:119], v[140:143], v[188:191], v[116:119]
	v_mfma_f32_16x16x32_bf16 v[112:115], v[132:135], v[210:213], v[112:115]
	v_mfma_f32_16x16x32_bf16 v[108:111], v[140:143], v[210:213], v[108:111]
	v_mfma_f32_16x16x32_bf16 v[160:163], v[136:139], v[176:179], v[160:163]
	v_mfma_f32_16x16x32_bf16 v[152:155], v[144:147], v[176:179], v[152:155]
	v_mfma_f32_16x16x32_bf16 v[128:131], v[136:139], v[184:187], v[128:131]
	v_mfma_f32_16x16x32_bf16 v[124:127], v[144:147], v[184:187], v[124:127]
	v_mfma_f32_16x16x32_bf16 v[120:123], v[136:139], v[192:195], v[120:123]
	v_mfma_f32_16x16x32_bf16 v[116:119], v[144:147], v[192:195], v[116:119]
	v_mfma_f32_16x16x32_bf16 v[112:115], v[136:139], v[214:217], v[112:115]
	v_mfma_f32_16x16x32_bf16 v[108:111], v[144:147], v[214:217], v[108:111]
	s_setprio 0
	s_setprio 1
	v_mfma_f32_16x16x32_bf16 v[64:67], v[148:151], v[172:175], v[64:67]
	v_mfma_f32_16x16x32_bf16 v[60:63], v[164:167], v[172:175], v[60:63]
	v_mfma_f32_16x16x32_bf16 v[56:59], v[148:151], v[180:183], v[56:59]
	v_mfma_f32_16x16x32_bf16 v[52:55], v[164:167], v[180:183], v[52:55]
	v_mfma_f32_16x16x32_bf16 v[48:51], v[148:151], v[188:191], v[48:51]
	v_mfma_f32_16x16x32_bf16 v[44:47], v[164:167], v[188:191], v[44:47]
	v_mfma_f32_16x16x32_bf16 v[40:43], v[148:151], v[210:213], v[40:43]
	v_mfma_f32_16x16x32_bf16 v[36:39], v[164:167], v[210:213], v[36:39]
	v_mfma_f32_16x16x32_bf16 v[64:67], v[156:159], v[176:179], v[64:67]
	v_mfma_f32_16x16x32_bf16 v[60:63], v[168:171], v[176:179], v[60:63]
	v_mfma_f32_16x16x32_bf16 v[56:59], v[156:159], v[184:187], v[56:59]
	v_mfma_f32_16x16x32_bf16 v[52:55], v[168:171], v[184:187], v[52:55]
	v_mfma_f32_16x16x32_bf16 v[48:51], v[156:159], v[192:195], v[48:51]
	v_mfma_f32_16x16x32_bf16 v[44:47], v[168:171], v[192:195], v[44:47]
	v_mfma_f32_16x16x32_bf16 v[40:43], v[156:159], v[214:217], v[40:43]
	v_mfma_f32_16x16x32_bf16 v[36:39], v[168:171], v[214:217], v[36:39]
	s_barrier
	s_setprio 0
	s_add_i32 s16, s67, s43
	v_lshl_add_u64 v[218:219], s[52:53], 0, v[198:199]
	s_mov_b32 m0, s16
	ds_read_b128 v[172:175], v208 offset:16384
	ds_read_b128 v[176:179], v208 offset:17408
	ds_read_b128 v[180:183], v208 offset:18432
	ds_read_b128 v[184:187], v208 offset:19456
	ds_read_b128 v[188:191], v208 offset:20480
	ds_read_b128 v[192:195], v208 offset:21504
	ds_read_b128 v[210:213], v208 offset:22528
	ds_read_b128 v[214:217], v208 offset:23552
	global_load_lds_dwordx4 v[218:219], off
	s_add_i32 m0, s16, 0x2000
	s_add_u32 s16, s52, 0x80000
	v_lshl_add_u64 v[220:221], s[52:53], 0, v[202:203]
	s_addc_u32 s17, s53, 0
	s_add_i32 s20, s68, s43
	global_load_lds_dwordx4 v[220:221], off
	v_lshl_add_u64 v[2:3], s[16:17], 0, v[198:199]
	s_mov_b32 m0, s20
	v_lshl_add_u64 v[222:223], s[54:55], 0, v[196:197]
	global_load_lds_dwordx4 v[2:3], off
	v_lshl_add_u64 v[2:3], s[16:17], 0, v[202:203]
	s_add_i32 m0, s20, 0x2000
	v_lshl_add_u64 v[224:225], s[54:55], 0, v[200:201]
	global_load_lds_dwordx4 v[2:3], off
	s_mov_b32 m0, s56
	s_nop 0
	global_load_lds_dwordx4 v[222:223], off
	s_mov_b32 m0, s57
	s_nop 0
	global_load_lds_dwordx4 v[224:225], off
	s_waitcnt vmcnt(8)
	s_waitcnt lgkmcnt(0)
	s_setprio 1
	s_waitcnt lgkmcnt(0)
	s_barrier
; #define PG8_STAGE(bufoff, gbase, voff) do { _Pragma("unroll") for (int _i = 0; _i < 2; ++_i) \
;         __builtin_amdgcn_global_load_lds((const unsigned*)((const char*)(gbase) + (voff)[_i]), (LAS unsigned*)(lds + (bufoff) + ldsw + _i * 8192), 16, 0, 0); } while (0)
; #define PG8_LDA(dst, b, h) do { _Pragma("unroll") for (int m = 0; m < 4; ++m) _Pragma("unroll") for (int k = 0; k < 2; ++k) dst[m][k] = *(const LAS bf16x8*)(lds + PG8_SA(b, h) + aoff + m * 2048 + k * 1024); } while (0)
; #define PG8_LDB(dst, b, h) do { _Pragma("unroll") for (int n = 0; n < 2; ++n) _Pragma("unroll") for (int k = 0; k < 2; ++k) dst[n][k] = *(const LAS bf16x8*)(lds + PG8_SB(b, h) + boff + n * 2048 + k * 1024); } while (0)
; #define PG8_MMA(ai, bj, At, Bt) do { __builtin_amdgcn_s_setprio(1); _Pragma("unroll") for (int m = 0; m < 4; ++m) _Pragma("unroll") for (int n = 0; n < 2; ++n) _Pragma("unroll") for (int k = 0; k < 2; ++k) \
;         acc[ai][bj][m][n] = __builtin_amdgcn_mfma_f32_16x16x32_bf16(Bt[n][k], At[m][k], acc[ai][bj][m][n], 0, 0, 0); __builtin_amdgcn_s_setprio(0); } while (0)
; #define PG8_WAIT_V(n) asm volatile("s_waitcnt vmcnt(" #n ")" ::: "memory")
; #define PG8_WAIT_L(n) asm volatile("s_waitcnt lgkmcnt(" #n ")" ::: "memory")
; #define PG8_BAR __builtin_amdgcn_s_barrier()
; #define PG8_SCHED __builtin_amdgcn_sched_barrier(0)
; template <class Epi, class Sched>
; __device__ __forceinline__ void gemm_phase(LAS unsigned char* lds, const Gemm g, const Sched& S, const Epi& E, const int tid) {
;     ...
;             PG8_WAIT_V(8); PG8_WAIT_L(0); PG8_BAR; PG8_MMA(1, 0, At, B0); PG8_MMA(1, 1, At, B1); PG8_BAR; PG8_SCHED;
;             PG8_LDB(B0, 1, 0); PG8_LDB(B1, 1, 1); PG8_SCHED; PG8_LDA(At, 1, 0); PG8_STAGE(PG8_SA(0, 1), a2 + hstepA, voffA);
;             PG8_WAIT_V(8); PG8_WAIT_L(0); PG8_BAR; PG8_MMA(0, 0, At, B0); PG8_MMA(0, 1, At, B1); PG8_BAR; PG8_SCHED;
	v_mfma_f32_16x16x32_bf16 v[104:107], v[132:135], v[172:175], v[104:107]
	v_mfma_f32_16x16x32_bf16 v[100:103], v[140:143], v[172:175], v[100:103]
	v_mfma_f32_16x16x32_bf16 v[96:99], v[132:135], v[180:183], v[96:99]
	v_mfma_f32_16x16x32_bf16 v[92:95], v[140:143], v[180:183], v[92:95]
	v_mfma_f32_16x16x32_bf16 v[88:91], v[132:135], v[188:191], v[88:91]
	v_mfma_f32_16x16x32_bf16 v[84:87], v[140:143], v[188:191], v[84:87]
	v_mfma_f32_16x16x32_bf16 v[80:83], v[132:135], v[210:213], v[80:83]
	v_mfma_f32_16x16x32_bf16 v[74:77], v[140:143], v[210:213], v[76:79]
	v_mfma_f32_16x16x32_bf16 v[104:107], v[136:139], v[176:179], v[104:107]
	v_mfma_f32_16x16x32_bf16 v[100:103], v[144:147], v[176:179], v[100:103]
	v_mfma_f32_16x16x32_bf16 v[96:99], v[136:139], v[184:187], v[96:99]
	v_mfma_f32_16x16x32_bf16 v[92:95], v[144:147], v[184:187], v[92:95]
	v_mfma_f32_16x16x32_bf16 v[88:91], v[136:139], v[192:195], v[88:91]
	v_mfma_f32_16x16x32_bf16 v[84:87], v[144:147], v[192:195], v[84:87]
	v_mfma_f32_16x16x32_bf16 v[80:83], v[136:139], v[214:217], v[80:83]
	v_mfma_f32_16x16x32_bf16 v[74:77], v[144:147], v[214:217], v[74:77]
	s_setprio 0
	s_setprio 1
	v_mfma_f32_16x16x32_bf16 v[32:35], v[148:151], v[172:175], v[32:35]
	v_mfma_f32_16x16x32_bf16 v[28:31], v[164:167], v[172:175], v[28:31]
	v_mfma_f32_16x16x32_bf16 v[24:27], v[148:151], v[180:183], v[24:27]
	v_mfma_f32_16x16x32_bf16 v[20:23], v[164:167], v[180:183], v[20:23]
	v_mfma_f32_16x16x32_bf16 v[16:19], v[148:151], v[188:191], v[16:19]
	v_mfma_f32_16x16x32_bf16 v[12:15], v[164:167], v[188:191], v[12:15]
	v_mfma_f32_16x16x32_bf16 v[8:11], v[148:151], v[210:213], v[8:11]
	v_mfma_f32_16x16x32_bf16 v[2:5], v[164:167], v[210:213], v[4:7]
	v_mfma_f32_16x16x32_bf16 v[32:35], v[156:159], v[176:179], v[32:35]
	v_mfma_f32_16x16x32_bf16 v[28:31], v[168:171], v[176:179], v[28:31]
	v_mfma_f32_16x16x32_bf16 v[24:27], v[156:159], v[184:187], v[24:27]
	v_mfma_f32_16x16x32_bf16 v[20:23], v[168:171], v[184:187], v[20:23]
	v_mfma_f32_16x16x32_bf16 v[16:19], v[156:159], v[192:195], v[16:19]
	v_mfma_f32_16x16x32_bf16 v[12:15], v[168:171], v[192:195], v[12:15]
	v_mfma_f32_16x16x32_bf16 v[8:11], v[156:159], v[214:217], v[8:11]
	v_mfma_f32_16x16x32_bf16 v[2:5], v[168:171], v[214:217], v[2:5]
	s_barrier
	s_setprio 0
	s_add_i32 s20, 0, 0x18000
	v_add_u32_e32 v1, s20, v252
	s_add_i32 s21, 0, 0x1c000
	ds_read_b128 v[132:135], v1
	ds_read_b128 v[136:139], v1 offset:1024
	ds_read_b128 v[140:143], v1 offset:2048
	ds_read_b128 v[144:147], v1 offset:3072
	v_add_u32_e32 v1, s21, v252
	ds_read_b128 v[148:151], v1
	ds_read_b128 v[156:159], v1 offset:1024
	ds_read_b128 v[164:167], v1 offset:2048
	ds_read_b128 v[168:171], v1 offset:3072
	s_add_u32 s16, s54, 0x80000
	s_addc_u32 s17, s55, 0
	s_mov_b32 m0, s58
	v_lshl_add_u64 v[6:7], s[16:17], 0, v[196:197]
	ds_read_b128 v[172:175], v208 offset:32768
	ds_read_b128 v[176:179], v208 offset:33792
	ds_read_b128 v[180:183], v208 offset:34816
	ds_read_b128 v[184:187], v208 offset:35840
	ds_read_b128 v[188:191], v208 offset:36864
	ds_read_b128 v[192:195], v208 offset:37888
	ds_read_b128 v[210:213], v208 offset:38912
	ds_read_b128 v[214:217], v208 offset:39936
	global_load_lds_dwordx4 v[6:7], off
	v_lshl_add_u64 v[6:7], s[16:17], 0, v[200:201]
	s_mov_b32 m0, s59
	s_nop 0
	global_load_lds_dwordx4 v[6:7], off
	s_waitcnt vmcnt(8)
	s_waitcnt lgkmcnt(0)
	s_setprio 1
	s_waitcnt lgkmcnt(0)
	s_barrier
	v_mfma_f32_16x16x32_bf16 v[160:163], v[132:135], v[172:175], v[160:163]
	v_mfma_f32_16x16x32_bf16 v[152:155], v[140:143], v[172:175], v[152:155]
	v_mfma_f32_16x16x32_bf16 v[128:131], v[132:135], v[180:183], v[128:131]
	v_mfma_f32_16x16x32_bf16 v[124:127], v[140:143], v[180:183], v[124:127]
	v_mfma_f32_16x16x32_bf16 v[120:123], v[132:135], v[188:191], v[120:123]
	v_mfma_f32_16x16x32_bf16 v[116:119], v[140:143], v[188:191], v[116:119]
	v_mfma_f32_16x16x32_bf16 v[112:115], v[132:135], v[210:213], v[112:115]
	v_mfma_f32_16x16x32_bf16 v[108:111], v[140:143], v[210:213], v[108:111]
	v_mfma_f32_16x16x32_bf16 v[160:163], v[136:139], v[176:179], v[160:163]
	v_mfma_f32_16x16x32_bf16 v[152:155], v[144:147], v[176:179], v[152:155]
	v_mfma_f32_16x16x32_bf16 v[128:131], v[136:139], v[184:187], v[128:131]
	v_mfma_f32_16x16x32_bf16 v[124:127], v[144:147], v[184:187], v[124:127]
	v_mfma_f32_16x16x32_bf16 v[120:123], v[136:139], v[192:195], v[120:123]
	v_mfma_f32_16x16x32_bf16 v[116:119], v[144:147], v[192:195], v[116:119]
	v_mfma_f32_16x16x32_bf16 v[112:115], v[136:139], v[214:217], v[112:115]
	v_mfma_f32_16x16x32_bf16 v[108:111], v[144:147], v[214:217], v[108:111]
	s_setprio 0
	s_setprio 1
	v_mfma_f32_16x16x32_bf16 v[64:67], v[148:151], v[172:175], v[64:67]
	v_mfma_f32_16x16x32_bf16 v[60:63], v[164:167], v[172:175], v[60:63]
	v_mfma_f32_16x16x32_bf16 v[56:59], v[148:151], v[180:183], v[56:59]
	v_mfma_f32_16x16x32_bf16 v[52:55], v[164:167], v[180:183], v[52:55]
	v_mfma_f32_16x16x32_bf16 v[48:51], v[148:151], v[188:191], v[48:51]
	v_mfma_f32_16x16x32_bf16 v[44:47], v[164:167], v[188:191], v[44:47]
	v_mfma_f32_16x16x32_bf16 v[40:43], v[148:151], v[210:213], v[40:43]
	v_mfma_f32_16x16x32_bf16 v[36:39], v[164:167], v[210:213], v[36:39]
	v_mfma_f32_16x16x32_bf16 v[64:67], v[156:159], v[176:179], v[64:67]
	v_mfma_f32_16x16x32_bf16 v[60:63], v[168:171], v[176:179], v[60:63]
	v_mfma_f32_16x16x32_bf16 v[56:59], v[156:159], v[184:187], v[56:59]
	v_mfma_f32_16x16x32_bf16 v[52:55], v[168:171], v[184:187], v[52:55]
	v_mfma_f32_16x16x32_bf16 v[48:51], v[156:159], v[192:195], v[48:51]
	v_mfma_f32_16x16x32_bf16 v[44:47], v[168:171], v[192:195], v[44:47]
	v_mfma_f32_16x16x32_bf16 v[40:43], v[156:159], v[214:217], v[40:43]
	v_mfma_f32_16x16x32_bf16 v[36:39], v[168:171], v[214:217], v[36:39]
	s_barrier
; #define PG8_STAGE(bufoff, gbase, voff) do { _Pragma("unroll") for (int _i = 0; _i < 2; ++_i) \
;         __builtin_amdgcn_global_load_lds((const unsigned*)((const char*)(gbase) + (voff)[_i]), (LAS unsigned*)(lds + (bufoff) + ldsw + _i * 8192), 16, 0, 0); } while (0)
; #define PG8_LDA(dst, b, h) do { _Pragma("unroll") for (int m = 0; m < 4; ++m) _Pragma("unroll") for (int k = 0; k < 2; ++k) dst[m][k] = *(const LAS bf16x8*)(lds + PG8_SA(b, h) + aoff + m * 2048 + k * 1024); } while (0)
; #define PG8_MMA(ai, bj, At, Bt) do { __builtin_amdgcn_s_setprio(1); _Pragma("unroll") for (int m = 0; m < 4; ++m) _Pragma("unroll") for (int n = 0; n < 2; ++n) _Pragma("unroll") for (int k = 0; k < 2; ++k) \
;         acc[ai][bj][m][n] = __builtin_amdgcn_mfma_f32_16x16x32_bf16(Bt[n][k], At[m][k], acc[ai][bj][m][n], 0, 0, 0); __builtin_amdgcn_s_setprio(0); } while (0)
; #define PG8_WAIT_V(n) asm volatile("s_waitcnt vmcnt(" #n ")" ::: "memory")
; #define PG8_WAIT_L(n) asm volatile("s_waitcnt lgkmcnt(" #n ")" ::: "memory")
; #define PG8_BAR __builtin_amdgcn_s_barrier()
; #define PG8_SCHED __builtin_amdgcn_sched_barrier(0)
; template <class Epi, class Sched>
; __device__ __forceinline__ void gemm_phase(LAS unsigned char* lds, const Gemm g, const Sched& S, const Epi& E, const int tid) {
;     ...
;             PG8_WAIT_V(8); PG8_WAIT_L(0); PG8_BAR; PG8_MMA(0, 0, At, B0); PG8_MMA(0, 1, At, B1); PG8_BAR; PG8_SCHED;
;             PG8_LDA(At, 1, 1); PG8_STAGE(PG8_SB(1, 0), b3, voffB); PG8_STAGE(PG8_SB(1, 1), b3 + hstepB, voffB); PG8_STAGE(PG8_SA(1, 0), a3, voffA);
;             PG8_WAIT_V(8); PG8_WAIT_L(0); PG8_BAR; PG8_MMA(1, 0, At, B0); PG8_MMA(1, 1, At, B1); PG8_BAR; PG8_SCHED;
;         }
;         if (wr == 0) PG8_BAR;
	s_setprio 0
	s_add_i32 s16, s20, s43
	v_lshl_add_u64 v[6:7], v[218:219], 0, s[26:27]
	s_mov_b32 m0, s16
	ds_read_b128 v[172:175], v208 offset:49152
	ds_read_b128 v[176:179], v208 offset:50176
	ds_read_b128 v[180:183], v208 offset:51200
	ds_read_b128 v[184:187], v208 offset:52224
	ds_read_b128 v[188:191], v208 offset:53248
	ds_read_b128 v[192:195], v208 offset:54272
	ds_read_b128 v[210:213], v208 offset:55296
	ds_read_b128 v[214:217], v208 offset:56320
	global_load_lds_dwordx4 v[6:7], off
	s_add_i32 m0, s16, 0x2000
	s_add_u32 s16, s52, 0x80080
	v_lshl_add_u64 v[6:7], v[220:221], 0, s[26:27]
	s_addc_u32 s17, s53, 0
	s_add_i32 s20, s21, s43
	global_load_lds_dwordx4 v[6:7], off
	v_lshl_add_u64 v[6:7], s[16:17], 0, v[198:199]
	s_mov_b32 m0, s20
	s_nop 0
	global_load_lds_dwordx4 v[6:7], off
	v_lshl_add_u64 v[6:7], s[16:17], 0, v[202:203]
	s_add_i32 m0, s20, 0x2000
	s_nop 0
	global_load_lds_dwordx4 v[6:7], off
	v_lshl_add_u64 v[6:7], v[222:223], 0, s[26:27]
	s_mov_b32 m0, s63
	s_nop 0
	global_load_lds_dwordx4 v[6:7], off
	v_lshl_add_u64 v[6:7], v[224:225], 0, s[26:27]
	s_mov_b32 m0, s64
	s_nop 0
	global_load_lds_dwordx4 v[6:7], off
	s_waitcnt vmcnt(8)
	s_waitcnt lgkmcnt(0)
	s_setprio 1
	s_waitcnt lgkmcnt(0)
	s_barrier
	v_mfma_f32_16x16x32_bf16 v[104:107], v[132:135], v[172:175], v[104:107]
	v_mfma_f32_16x16x32_bf16 v[100:103], v[140:143], v[172:175], v[100:103]
	v_mfma_f32_16x16x32_bf16 v[96:99], v[132:135], v[180:183], v[96:99]
	v_mfma_f32_16x16x32_bf16 v[92:95], v[140:143], v[180:183], v[92:95]
	v_mfma_f32_16x16x32_bf16 v[88:91], v[132:135], v[188:191], v[88:91]
	v_mfma_f32_16x16x32_bf16 v[84:87], v[140:143], v[188:191], v[84:87]
	v_mfma_f32_16x16x32_bf16 v[78:81], v[132:135], v[210:213], v[80:83]
	v_mfma_f32_16x16x32_bf16 v[74:77], v[140:143], v[210:213], v[74:77]
	v_mfma_f32_16x16x32_bf16 v[104:107], v[136:139], v[176:179], v[104:107]
	v_mfma_f32_16x16x32_bf16 v[100:103], v[144:147], v[176:179], v[100:103]
	v_mfma_f32_16x16x32_bf16 v[96:99], v[136:139], v[184:187], v[96:99]
	v_mfma_f32_16x16x32_bf16 v[92:95], v[144:147], v[184:187], v[92:95]
	v_mfma_f32_16x16x32_bf16 v[88:91], v[136:139], v[192:195], v[88:91]
	v_mfma_f32_16x16x32_bf16 v[84:87], v[144:147], v[192:195], v[84:87]
	v_mfma_f32_16x16x32_bf16 v[80:83], v[136:139], v[214:217], v[78:81]
	v_mfma_f32_16x16x32_bf16 v[76:79], v[144:147], v[214:217], v[74:77]
	s_setprio 0
	s_setprio 1
	v_mfma_f32_16x16x32_bf16 v[32:35], v[148:151], v[172:175], v[32:35]
	v_mfma_f32_16x16x32_bf16 v[28:31], v[164:167], v[172:175], v[28:31]
	v_mfma_f32_16x16x32_bf16 v[24:27], v[148:151], v[180:183], v[24:27]
	v_mfma_f32_16x16x32_bf16 v[20:23], v[164:167], v[180:183], v[20:23]
	v_mfma_f32_16x16x32_bf16 v[16:19], v[148:151], v[188:191], v[16:19]
	v_mfma_f32_16x16x32_bf16 v[12:15], v[164:167], v[188:191], v[12:15]
	v_mfma_f32_16x16x32_bf16 v[6:9], v[148:151], v[210:213], v[8:11]
	v_mfma_f32_16x16x32_bf16 v[2:5], v[164:167], v[210:213], v[2:5]
	v_mfma_f32_16x16x32_bf16 v[32:35], v[156:159], v[176:179], v[32:35]
	v_mfma_f32_16x16x32_bf16 v[28:31], v[168:171], v[176:179], v[28:31]
	v_mfma_f32_16x16x32_bf16 v[24:27], v[156:159], v[184:187], v[24:27]
	v_mfma_f32_16x16x32_bf16 v[20:23], v[168:171], v[184:187], v[20:23]
	v_mfma_f32_16x16x32_bf16 v[16:19], v[156:159], v[192:195], v[16:19]
	v_mfma_f32_16x16x32_bf16 v[12:15], v[168:171], v[192:195], v[12:15]
	v_mfma_f32_16x16x32_bf16 v[8:11], v[156:159], v[214:217], v[6:9]
	v_mfma_f32_16x16x32_bf16 v[4:7], v[168:171], v[214:217], v[2:5]
	s_barrier
	s_setprio 0
	s_add_i32 s72, s72, 2
	s_add_u32 s50, s50, 0x100
	s_addc_u32 s51, s51, 0
	s_cmp_gt_u32 s72, 29
	s_cbranch_scc1 .LBB0_1153

; #define PG8_STAGE(bufoff, gbase, voff) do { _Pragma("unroll") for (int _i = 0; _i < 2; ++_i) \
;         __builtin_amdgcn_global_load_lds((const unsigned*)((const char*)(gbase) + (voff)[_i]), (LAS unsigned*)(lds + (bufoff) + ldsw + _i * 8192), 16, 0, 0); } while (0)
; #define PG8_LDA(dst, b, h) do { _Pragma("unroll") for (int m = 0; m < 4; ++m) _Pragma("unroll") for (int k = 0; k < 2; ++k) dst[m][k] = *(const LAS bf16x8*)(lds + PG8_SA(b, h) + aoff + m * 2048 + k * 1024); } while (0)
; #define PG8_LDB(dst, b, h) do { _Pragma("unroll") for (int n = 0; n < 2; ++n) _Pragma("unroll") for (int k = 0; k < 2; ++k) dst[n][k] = *(const LAS bf16x8*)(lds + PG8_SB(b, h) + boff + n * 2048 + k * 1024); } while (0)
; #define PG8_MMA(ai, bj, At, Bt) do { __builtin_amdgcn_s_setprio(1); _Pragma("unroll") for (int m = 0; m < 4; ++m) _Pragma("unroll") for (int n = 0; n < 2; ++n) _Pragma("unroll") for (int k = 0; k < 2; ++k) \
;         acc[ai][bj][m][n] = __builtin_amdgcn_mfma_f32_16x16x32_bf16(Bt[n][k], At[m][k], acc[ai][bj][m][n], 0, 0, 0); __builtin_amdgcn_s_setprio(0); } while (0)
; #define PG8_WAIT_V(n) asm volatile("s_waitcnt vmcnt(" #n ")" ::: "memory")
; #define PG8_WAIT_L(n) asm volatile("s_waitcnt lgkmcnt(" #n ")" ::: "memory")
; #define PG8_BAR __builtin_amdgcn_s_barrier()
; template <class Epi, class Sched>
; __device__ __forceinline__ void gemm_phase(LAS unsigned char* lds, const Gemm g, const Sched& S, const Epi& E, const int tid) {
;     ...
;             const bool last = (t == nt - 2);
;             const char* a1 = cA + (size_t)(t + 1) * kstepA;
;             const char* a2 = last ? nA : cA + (size_t)(t + 2) * kstepA; const char* b2 = last ? nB : cB + (size_t)(t + 2) * kstep;
;             const char* a3 = a2 + kstepA; const char* b3 = b2 + kstep;
;             if constexpr (Epi::HAS_MID) { if (t == g.tmid) E.mid(acc, cur, ui, wr, wc, fr, fq); }
;             PG8_LDB(B0, 0, 0); PG8_LDB(B1, 0, 1); PG8_SCHED; PG8_LDA(At, 0, 0); PG8_STAGE(PG8_SA(1, 1), a1 + hstepA, voffA);
;             PG8_WAIT_V(8); PG8_WAIT_L(0); PG8_BAR; PG8_MMA(0, 0, At, B0); PG8_MMA(0, 1, At, B1); PG8_BAR; PG8_SCHED;
;             PG8_LDA(At, 0, 1); PG8_STAGE(PG8_SB(0, 0), b2, voffB); PG8_STAGE(PG8_SB(0, 1), b2 + hstepB, voffB); PG8_STAGE(PG8_SA(0, 0), a2, voffA);
;             PG8_WAIT_V(8); PG8_WAIT_L(0); PG8_BAR; PG8_MMA(1, 0, At, B0); PG8_MMA(1, 1, At, B1); PG8_BAR; PG8_SCHED;
.LBB0_1314:
	ds_read_b128 v[64:67], v171
	ds_read_b128 v[68:71], v171 offset:1024
	ds_read_b128 v[136:139], v171 offset:2048
	ds_read_b128 v[140:143], v171 offset:3072
	ds_read_b128 v[172:175], v177
	ds_read_b128 v[182:185], v177 offset:1024
	ds_read_b128 v[186:189], v177 offset:2048
	ds_read_b128 v[190:193], v177 offset:3072
	s_add_u32 s16, s8, 0xfff80080
	s_addc_u32 s17, s9, -1
	s_cmp_eq_u32 s62, 28
	s_cselect_b32 s45, s18, s17
	s_cselect_b32 s44, s35, s16
	s_cselect_b32 s43, s31, s61
	s_cselect_b32 s42, s59, s60
	v_lshl_add_u64 v[164:165], s[8:9], 0, v[156:157]
	s_add_i32 m0, s48, 0xc000
	ds_read_b128 v[194:197], v181
	ds_read_b128 v[198:201], v181 offset:1024
	ds_read_b128 v[202:205], v181 offset:2048
	ds_read_b128 v[206:209], v181 offset:3072
	ds_read_b128 v[210:213], v181 offset:4096
	ds_read_b128 v[214:217], v181 offset:5120
	ds_read_b128 v[218:221], v181 offset:6144
	ds_read_b128 v[222:225], v181 offset:7168
	global_load_lds_dwordx4 v[164:165], off
	v_lshl_add_u64 v[164:165], s[8:9], 0, v[158:159]
	s_add_i32 m0, s48, 0xe000
	s_nop 0
	global_load_lds_dwordx4 v[164:165], off
	s_waitcnt vmcnt(8)
	s_waitcnt lgkmcnt(0)
	s_setprio 1
	s_waitcnt lgkmcnt(0)
	s_barrier
	v_mfma_f32_16x16x32_bf16 v[132:135], v[64:67], v[194:197], v[132:135]
	v_mfma_f32_16x16x32_bf16 v[124:127], v[136:139], v[194:197], v[124:127]
	v_mfma_f32_16x16x32_bf16 v[116:119], v[64:67], v[202:205], v[116:119]
	v_mfma_f32_16x16x32_bf16 v[108:111], v[136:139], v[202:205], v[108:111]
	v_mfma_f32_16x16x32_bf16 v[100:103], v[64:67], v[210:213], v[100:103]
	v_mfma_f32_16x16x32_bf16 v[92:95], v[136:139], v[210:213], v[92:95]
	v_mfma_f32_16x16x32_bf16 v[84:87], v[64:67], v[218:221], v[84:87]
	v_mfma_f32_16x16x32_bf16 v[76:79], v[136:139], v[218:221], v[76:79]
	v_mfma_f32_16x16x32_bf16 v[132:135], v[68:71], v[198:201], v[132:135]
	v_mfma_f32_16x16x32_bf16 v[124:127], v[140:143], v[198:201], v[124:127]
	v_mfma_f32_16x16x32_bf16 v[116:119], v[68:71], v[206:209], v[116:119]
	v_mfma_f32_16x16x32_bf16 v[108:111], v[140:143], v[206:209], v[108:111]
	v_mfma_f32_16x16x32_bf16 v[100:103], v[68:71], v[214:217], v[100:103]
	v_mfma_f32_16x16x32_bf16 v[92:95], v[140:143], v[214:217], v[92:95]
	v_mfma_f32_16x16x32_bf16 v[84:87], v[68:71], v[222:225], v[84:87]
	v_mfma_f32_16x16x32_bf16 v[76:79], v[140:143], v[222:225], v[76:79]
	s_setprio 0
	s_setprio 1
	v_mfma_f32_16x16x32_bf16 v[128:131], v[172:175], v[194:197], v[128:131]
	v_mfma_f32_16x16x32_bf16 v[120:123], v[186:189], v[194:197], v[120:123]
	v_mfma_f32_16x16x32_bf16 v[112:115], v[172:175], v[202:205], v[112:115]
	v_mfma_f32_16x16x32_bf16 v[104:107], v[186:189], v[202:205], v[104:107]
	v_mfma_f32_16x16x32_bf16 v[96:99], v[172:175], v[210:213], v[96:99]
	v_mfma_f32_16x16x32_bf16 v[88:91], v[186:189], v[210:213], v[88:91]
	v_mfma_f32_16x16x32_bf16 v[80:83], v[172:175], v[218:221], v[80:83]
	v_mfma_f32_16x16x32_bf16 v[72:75], v[186:189], v[218:221], v[72:75]
	v_mfma_f32_16x16x32_bf16 v[128:131], v[182:185], v[198:201], v[128:131]
	v_mfma_f32_16x16x32_bf16 v[120:123], v[190:193], v[198:201], v[120:123]
	v_mfma_f32_16x16x32_bf16 v[112:115], v[182:185], v[206:209], v[112:115]
	v_mfma_f32_16x16x32_bf16 v[104:107], v[190:193], v[206:209], v[104:107]
	v_mfma_f32_16x16x32_bf16 v[96:99], v[182:185], v[214:217], v[96:99]
	v_mfma_f32_16x16x32_bf16 v[88:91], v[190:193], v[214:217], v[88:91]
	v_mfma_f32_16x16x32_bf16 v[80:83], v[182:185], v[222:225], v[80:83]
	v_mfma_f32_16x16x32_bf16 v[72:75], v[190:193], v[222:225], v[72:75]
	s_barrier
	s_setprio 0
	s_add_i32 s16, s55, s46
	v_lshl_add_u64 v[164:165], s[42:43], 0, v[146:147]
	s_mov_b32 m0, s16
	ds_read_b128 v[194:197], v181 offset:16384
	ds_read_b128 v[198:201], v181 offset:17408
	ds_read_b128 v[202:205], v181 offset:18432
	ds_read_b128 v[206:209], v181 offset:19456
	ds_read_b128 v[210:213], v181 offset:20480
	ds_read_b128 v[214:217], v181 offset:21504
	ds_read_b128 v[218:221], v181 offset:22528
	ds_read_b128 v[222:225], v181 offset:23552
	global_load_lds_dwordx4 v[164:165], off
	s_add_i32 m0, s16, 0x2000
	s_add_u32 s16, s42, 0x80000
	v_lshl_add_u64 v[168:169], s[42:43], 0, v[150:151]
	s_addc_u32 s17, s43, 0
	s_add_i32 s20, s56, s46
	global_load_lds_dwordx4 v[168:169], off
	v_lshl_add_u64 v[178:179], s[16:17], 0, v[146:147]
	s_mov_b32 m0, s20
	v_lshl_add_u64 v[226:227], s[44:45], 0, v[148:149]
	global_load_lds_dwordx4 v[178:179], off
	v_lshl_add_u64 v[178:179], s[16:17], 0, v[150:151]
	s_add_i32 m0, s20, 0x2000
	s_nop 0
	global_load_lds_dwordx4 v[178:179], off
	v_lshl_add_u64 v[178:179], s[44:45], 0, v[144:145]
	s_mov_b32 m0, s48
	s_nop 0
	global_load_lds_dwordx4 v[178:179], off
	s_mov_b32 m0, s49
	s_nop 0
	global_load_lds_dwordx4 v[226:227], off
	s_waitcnt vmcnt(8)
	s_waitcnt lgkmcnt(0)
	s_setprio 1
	s_waitcnt lgkmcnt(0)
	s_barrier
; #define PG8_STAGE(bufoff, gbase, voff) do { _Pragma("unroll") for (int _i = 0; _i < 2; ++_i) \
;         __builtin_amdgcn_global_load_lds((const unsigned*)((const char*)(gbase) + (voff)[_i]), (LAS unsigned*)(lds + (bufoff) + ldsw + _i * 8192), 16, 0, 0); } while (0)
; #define PG8_LDA(dst, b, h) do { _Pragma("unroll") for (int m = 0; m < 4; ++m) _Pragma("unroll") for (int k = 0; k < 2; ++k) dst[m][k] = *(const LAS bf16x8*)(lds + PG8_SA(b, h) + aoff + m * 2048 + k * 1024); } while (0)
; #define PG8_LDB(dst, b, h) do { _Pragma("unroll") for (int n = 0; n < 2; ++n) _Pragma("unroll") for (int k = 0; k < 2; ++k) dst[n][k] = *(const LAS bf16x8*)(lds + PG8_SB(b, h) + boff + n * 2048 + k * 1024); } while (0)
; #define PG8_MMA(ai, bj, At, Bt) do { __builtin_amdgcn_s_setprio(1); _Pragma("unroll") for (int m = 0; m < 4; ++m) _Pragma("unroll") for (int n = 0; n < 2; ++n) _Pragma("unroll") for (int k = 0; k < 2; ++k) \
;         acc[ai][bj][m][n] = __builtin_amdgcn_mfma_f32_16x16x32_bf16(Bt[n][k], At[m][k], acc[ai][bj][m][n], 0, 0, 0); __builtin_amdgcn_s_setprio(0); } while (0)
; #define PG8_WAIT_V(n) asm volatile("s_waitcnt vmcnt(" #n ")" ::: "memory")
; #define PG8_WAIT_L(n) asm volatile("s_waitcnt lgkmcnt(" #n ")" ::: "memory")
; #define PG8_BAR __builtin_amdgcn_s_barrier()
; #define PG8_SCHED __builtin_amdgcn_sched_barrier(0)
; template <class Epi, class Sched>
; __device__ __forceinline__ void gemm_phase(LAS unsigned char* lds, const Gemm g, const Sched& S, const Epi& E, const int tid) {
;     ...
;             PG8_WAIT_V(8); PG8_WAIT_L(0); PG8_BAR; PG8_MMA(1, 0, At, B0); PG8_MMA(1, 1, At, B1); PG8_BAR; PG8_SCHED;
;             PG8_LDB(B0, 1, 0); PG8_LDB(B1, 1, 1); PG8_SCHED; PG8_LDA(At, 1, 0); PG8_STAGE(PG8_SA(0, 1), a2 + hstepA, voffA);
;             PG8_WAIT_V(8); PG8_WAIT_L(0); PG8_BAR; PG8_MMA(0, 0, At, B0); PG8_MMA(0, 1, At, B1); PG8_BAR; PG8_SCHED;
	v_mfma_f32_16x16x32_bf16 v[60:63], v[64:67], v[194:197], v[60:63]
	v_mfma_f32_16x16x32_bf16 v[52:55], v[136:139], v[194:197], v[52:55]
	v_mfma_f32_16x16x32_bf16 v[44:47], v[64:67], v[202:205], v[44:47]
	v_mfma_f32_16x16x32_bf16 v[36:39], v[136:139], v[202:205], v[36:39]
	v_mfma_f32_16x16x32_bf16 v[28:31], v[64:67], v[210:213], v[28:31]
	v_mfma_f32_16x16x32_bf16 v[20:23], v[136:139], v[210:213], v[20:23]
	v_mfma_f32_16x16x32_bf16 v[12:15], v[64:67], v[218:221], v[12:15]
	v_mfma_f32_16x16x32_bf16 v[4:7], v[136:139], v[218:221], v[4:7]
	v_mfma_f32_16x16x32_bf16 v[60:63], v[68:71], v[198:201], v[60:63]
	v_mfma_f32_16x16x32_bf16 v[52:55], v[140:143], v[198:201], v[52:55]
	v_mfma_f32_16x16x32_bf16 v[44:47], v[68:71], v[206:209], v[44:47]
	v_mfma_f32_16x16x32_bf16 v[36:39], v[140:143], v[206:209], v[36:39]
	v_mfma_f32_16x16x32_bf16 v[28:31], v[68:71], v[214:217], v[28:31]
	v_mfma_f32_16x16x32_bf16 v[20:23], v[140:143], v[214:217], v[20:23]
	v_mfma_f32_16x16x32_bf16 v[12:15], v[68:71], v[222:225], v[12:15]
	v_mfma_f32_16x16x32_bf16 v[4:7], v[140:143], v[222:225], v[4:7]
	s_setprio 0
	s_setprio 1
	v_mfma_f32_16x16x32_bf16 v[56:59], v[172:175], v[194:197], v[56:59]
	v_mfma_f32_16x16x32_bf16 v[48:51], v[186:189], v[194:197], v[48:51]
	v_mfma_f32_16x16x32_bf16 v[40:43], v[172:175], v[202:205], v[40:43]
	v_mfma_f32_16x16x32_bf16 v[32:35], v[186:189], v[202:205], v[32:35]
	v_mfma_f32_16x16x32_bf16 v[24:27], v[172:175], v[210:213], v[24:27]
	v_mfma_f32_16x16x32_bf16 v[16:19], v[186:189], v[210:213], v[16:19]
	v_mfma_f32_16x16x32_bf16 v[8:11], v[172:175], v[218:221], v[8:11]
	v_mfma_f32_16x16x32_bf16 v[0:3], v[186:189], v[218:221], v[0:3]
	v_mfma_f32_16x16x32_bf16 v[56:59], v[182:185], v[198:201], v[56:59]
	v_mfma_f32_16x16x32_bf16 v[48:51], v[190:193], v[198:201], v[48:51]
	v_mfma_f32_16x16x32_bf16 v[40:43], v[182:185], v[206:209], v[40:43]
	v_mfma_f32_16x16x32_bf16 v[32:35], v[190:193], v[206:209], v[32:35]
	v_mfma_f32_16x16x32_bf16 v[24:27], v[182:185], v[214:217], v[24:27]
	v_mfma_f32_16x16x32_bf16 v[16:19], v[190:193], v[214:217], v[16:19]
	v_mfma_f32_16x16x32_bf16 v[8:11], v[182:185], v[222:225], v[8:11]
	v_mfma_f32_16x16x32_bf16 v[0:3], v[190:193], v[222:225], v[0:3]
	s_barrier
	s_setprio 0
	s_add_i32 s20, 0, 0x18000
	s_add_i32 s21, 0, 0x1c000
	v_add_u32_e32 v140, s20, v167
	v_add_u32_e32 v152, s21, v167
	ds_read_b128 v[64:67], v140
	ds_read_b128 v[68:71], v140 offset:1024
	ds_read_b128 v[136:139], v140 offset:2048
	ds_read_b128 v[140:143], v140 offset:3072
	ds_read_b128 v[172:175], v152
	ds_read_b128 v[182:185], v152 offset:1024
	ds_read_b128 v[186:189], v152 offset:2048
	ds_read_b128 v[190:193], v152 offset:3072
	s_add_u32 s16, s44, 0x80000
	s_addc_u32 s17, s45, 0
	s_mov_b32 m0, s50
	v_lshl_add_u64 v[228:229], s[16:17], 0, v[144:145]
	ds_read_b128 v[194:197], v181 offset:32768
	ds_read_b128 v[198:201], v181 offset:33792
	ds_read_b128 v[202:205], v181 offset:34816
	ds_read_b128 v[206:209], v181 offset:35840
	ds_read_b128 v[210:213], v181 offset:36864
	ds_read_b128 v[214:217], v181 offset:37888
	ds_read_b128 v[218:221], v181 offset:38912
	ds_read_b128 v[222:225], v181 offset:39936
	global_load_lds_dwordx4 v[228:229], off
	v_lshl_add_u64 v[228:229], s[16:17], 0, v[148:149]
	s_mov_b32 m0, s51
	s_nop 0
	global_load_lds_dwordx4 v[228:229], off
	s_waitcnt vmcnt(8)
	s_waitcnt lgkmcnt(0)
	s_setprio 1
	s_waitcnt lgkmcnt(0)
	s_barrier
	v_mfma_f32_16x16x32_bf16 v[132:135], v[64:67], v[194:197], v[132:135]
	v_mfma_f32_16x16x32_bf16 v[124:127], v[136:139], v[194:197], v[124:127]
	v_mfma_f32_16x16x32_bf16 v[116:119], v[64:67], v[202:205], v[116:119]
	v_mfma_f32_16x16x32_bf16 v[108:111], v[136:139], v[202:205], v[108:111]
	v_mfma_f32_16x16x32_bf16 v[100:103], v[64:67], v[210:213], v[100:103]
	v_mfma_f32_16x16x32_bf16 v[92:95], v[136:139], v[210:213], v[92:95]
	v_mfma_f32_16x16x32_bf16 v[84:87], v[64:67], v[218:221], v[84:87]
	v_mfma_f32_16x16x32_bf16 v[76:79], v[136:139], v[218:221], v[76:79]
	v_mfma_f32_16x16x32_bf16 v[132:135], v[68:71], v[198:201], v[132:135]
	v_mfma_f32_16x16x32_bf16 v[124:127], v[140:143], v[198:201], v[124:127]
	v_mfma_f32_16x16x32_bf16 v[116:119], v[68:71], v[206:209], v[116:119]
	v_mfma_f32_16x16x32_bf16 v[108:111], v[140:143], v[206:209], v[108:111]
	v_mfma_f32_16x16x32_bf16 v[100:103], v[68:71], v[214:217], v[100:103]
	v_mfma_f32_16x16x32_bf16 v[92:95], v[140:143], v[214:217], v[92:95]
	v_mfma_f32_16x16x32_bf16 v[84:87], v[68:71], v[222:225], v[84:87]
	v_mfma_f32_16x16x32_bf16 v[76:79], v[140:143], v[222:225], v[76:79]
	s_setprio 0
	s_setprio 1
	v_mfma_f32_16x16x32_bf16 v[128:131], v[172:175], v[194:197], v[128:131]
	v_mfma_f32_16x16x32_bf16 v[120:123], v[186:189], v[194:197], v[120:123]
	v_mfma_f32_16x16x32_bf16 v[112:115], v[172:175], v[202:205], v[112:115]
	v_mfma_f32_16x16x32_bf16 v[104:107], v[186:189], v[202:205], v[104:107]
	v_mfma_f32_16x16x32_bf16 v[96:99], v[172:175], v[210:213], v[96:99]
	v_mfma_f32_16x16x32_bf16 v[88:91], v[186:189], v[210:213], v[88:91]
	v_mfma_f32_16x16x32_bf16 v[80:83], v[172:175], v[218:221], v[80:83]
	v_mfma_f32_16x16x32_bf16 v[72:75], v[186:189], v[218:221], v[72:75]
	v_mfma_f32_16x16x32_bf16 v[128:131], v[182:185], v[198:201], v[128:131]
	v_mfma_f32_16x16x32_bf16 v[120:123], v[190:193], v[198:201], v[120:123]
	v_mfma_f32_16x16x32_bf16 v[112:115], v[182:185], v[206:209], v[112:115]
	v_mfma_f32_16x16x32_bf16 v[104:107], v[190:193], v[206:209], v[104:107]
	v_mfma_f32_16x16x32_bf16 v[96:99], v[182:185], v[214:217], v[96:99]
	v_mfma_f32_16x16x32_bf16 v[88:91], v[190:193], v[214:217], v[88:91]
	v_mfma_f32_16x16x32_bf16 v[80:83], v[182:185], v[222:225], v[80:83]
	v_mfma_f32_16x16x32_bf16 v[72:75], v[190:193], v[222:225], v[72:75]
	s_barrier
; #define PG8_STAGE(bufoff, gbase, voff) do { _Pragma("unroll") for (int _i = 0; _i < 2; ++_i) \
;         __builtin_amdgcn_global_load_lds((const unsigned*)((const char*)(gbase) + (voff)[_i]), (LAS unsigned*)(lds + (bufoff) + ldsw + _i * 8192), 16, 0, 0); } while (0)
; #define PG8_LDA(dst, b, h) do { _Pragma("unroll") for (int m = 0; m < 4; ++m) _Pragma("unroll") for (int k = 0; k < 2; ++k) dst[m][k] = *(const LAS bf16x8*)(lds + PG8_SA(b, h) + aoff + m * 2048 + k * 1024); } while (0)
; #define PG8_MMA(ai, bj, At, Bt) do { __builtin_amdgcn_s_setprio(1); _Pragma("unroll") for (int m = 0; m < 4; ++m) _Pragma("unroll") for (int n = 0; n < 2; ++n) _Pragma("unroll") for (int k = 0; k < 2; ++k) \
;         acc[ai][bj][m][n] = __builtin_amdgcn_mfma_f32_16x16x32_bf16(Bt[n][k], At[m][k], acc[ai][bj][m][n], 0, 0, 0); __builtin_amdgcn_s_setprio(0); } while (0)
; #define PG8_WAIT_V(n) asm volatile("s_waitcnt vmcnt(" #n ")" ::: "memory")
; #define PG8_WAIT_L(n) asm volatile("s_waitcnt lgkmcnt(" #n ")" ::: "memory")
; #define PG8_BAR __builtin_amdgcn_s_barrier()
; #define PG8_SCHED __builtin_amdgcn_sched_barrier(0)
; template <class Epi, class Sched>
; __device__ __forceinline__ void gemm_phase(LAS unsigned char* lds, const Gemm g, const Sched& S, const Epi& E, const int tid) {
;     ...
;             PG8_WAIT_V(8); PG8_WAIT_L(0); PG8_BAR; PG8_MMA(0, 0, At, B0); PG8_MMA(0, 1, At, B1); PG8_BAR; PG8_SCHED;
;             PG8_LDA(At, 1, 1); PG8_STAGE(PG8_SB(1, 0), b3, voffB); PG8_STAGE(PG8_SB(1, 1), b3 + hstepB, voffB); PG8_STAGE(PG8_SA(1, 0), a3, voffA);
;             PG8_WAIT_V(8); PG8_WAIT_L(0); PG8_BAR; PG8_MMA(1, 0, At, B0); PG8_MMA(1, 1, At, B1); PG8_BAR; PG8_SCHED;
;         }
;         if (wr == 0) PG8_BAR;
	s_setprio 0
	s_add_i32 s16, s20, s46
	v_lshl_add_u64 v[164:165], v[164:165], 0, s[26:27]
	s_mov_b32 m0, s16
	ds_read_b128 v[194:197], v181 offset:49152
	ds_read_b128 v[198:201], v181 offset:50176
	ds_read_b128 v[202:205], v181 offset:51200
	ds_read_b128 v[206:209], v181 offset:52224
	ds_read_b128 v[210:213], v181 offset:53248
	ds_read_b128 v[214:217], v181 offset:54272
	ds_read_b128 v[218:221], v181 offset:55296
	ds_read_b128 v[222:225], v181 offset:56320
	global_load_lds_dwordx4 v[164:165], off
	s_add_i32 m0, s16, 0x2000
	s_add_u32 s16, s42, 0x80080
	v_lshl_add_u64 v[164:165], v[168:169], 0, s[26:27]
	s_addc_u32 s17, s43, 0
	s_add_i32 s20, s21, s46
	global_load_lds_dwordx4 v[164:165], off
	v_lshl_add_u64 v[164:165], s[16:17], 0, v[146:147]
	s_mov_b32 m0, s20
	s_nop 0
	global_load_lds_dwordx4 v[164:165], off
	v_lshl_add_u64 v[164:165], s[16:17], 0, v[150:151]
	s_add_i32 m0, s20, 0x2000
	s_nop 0
	global_load_lds_dwordx4 v[164:165], off
	v_lshl_add_u64 v[164:165], v[178:179], 0, s[26:27]
	s_mov_b32 m0, s53
	s_nop 0
	global_load_lds_dwordx4 v[164:165], off
	v_lshl_add_u64 v[164:165], v[226:227], 0, s[26:27]
	s_mov_b32 m0, s54
	s_nop 0
	global_load_lds_dwordx4 v[164:165], off
	s_waitcnt vmcnt(8)
	s_waitcnt lgkmcnt(0)
	s_setprio 1
	s_waitcnt lgkmcnt(0)
	s_barrier
	v_mfma_f32_16x16x32_bf16 v[60:63], v[64:67], v[194:197], v[60:63]
	v_mfma_f32_16x16x32_bf16 v[52:55], v[136:139], v[194:197], v[52:55]
	v_mfma_f32_16x16x32_bf16 v[44:47], v[64:67], v[202:205], v[44:47]
	v_mfma_f32_16x16x32_bf16 v[36:39], v[136:139], v[202:205], v[36:39]
	v_mfma_f32_16x16x32_bf16 v[28:31], v[64:67], v[210:213], v[28:31]
	v_mfma_f32_16x16x32_bf16 v[20:23], v[136:139], v[210:213], v[20:23]
	v_mfma_f32_16x16x32_bf16 v[12:15], v[64:67], v[218:221], v[12:15]
	v_mfma_f32_16x16x32_bf16 v[4:7], v[136:139], v[218:221], v[4:7]
	v_mfma_f32_16x16x32_bf16 v[60:63], v[68:71], v[198:201], v[60:63]
	v_mfma_f32_16x16x32_bf16 v[52:55], v[140:143], v[198:201], v[52:55]
	v_mfma_f32_16x16x32_bf16 v[44:47], v[68:71], v[206:209], v[44:47]
	v_mfma_f32_16x16x32_bf16 v[36:39], v[140:143], v[206:209], v[36:39]
	v_mfma_f32_16x16x32_bf16 v[28:31], v[68:71], v[214:217], v[28:31]
	v_mfma_f32_16x16x32_bf16 v[20:23], v[140:143], v[214:217], v[20:23]
	v_mfma_f32_16x16x32_bf16 v[12:15], v[68:71], v[222:225], v[12:15]
	v_mfma_f32_16x16x32_bf16 v[4:7], v[140:143], v[222:225], v[4:7]
	s_setprio 0
	s_setprio 1
	v_mfma_f32_16x16x32_bf16 v[56:59], v[172:175], v[194:197], v[56:59]
	v_mfma_f32_16x16x32_bf16 v[48:51], v[186:189], v[194:197], v[48:51]
	v_mfma_f32_16x16x32_bf16 v[40:43], v[172:175], v[202:205], v[40:43]
	v_mfma_f32_16x16x32_bf16 v[32:35], v[186:189], v[202:205], v[32:35]
	v_mfma_f32_16x16x32_bf16 v[24:27], v[172:175], v[210:213], v[24:27]
	v_mfma_f32_16x16x32_bf16 v[16:19], v[186:189], v[210:213], v[16:19]
	v_mfma_f32_16x16x32_bf16 v[8:11], v[172:175], v[218:221], v[8:11]
	v_mfma_f32_16x16x32_bf16 v[0:3], v[186:189], v[218:221], v[0:3]
	v_mfma_f32_16x16x32_bf16 v[56:59], v[182:185], v[198:201], v[56:59]
	v_mfma_f32_16x16x32_bf16 v[48:51], v[190:193], v[198:201], v[48:51]
	v_mfma_f32_16x16x32_bf16 v[40:43], v[182:185], v[206:209], v[40:43]
	v_mfma_f32_16x16x32_bf16 v[32:35], v[190:193], v[206:209], v[32:35]
	v_mfma_f32_16x16x32_bf16 v[24:27], v[182:185], v[214:217], v[24:27]
	v_mfma_f32_16x16x32_bf16 v[16:19], v[190:193], v[214:217], v[16:19]
	v_mfma_f32_16x16x32_bf16 v[8:11], v[182:185], v[222:225], v[8:11]
	v_mfma_f32_16x16x32_bf16 v[0:3], v[190:193], v[222:225], v[0:3]
	s_barrier
	s_setprio 0
	s_add_i32 s62, s62, 2
	s_add_u32 s8, s8, 0x100
	s_addc_u32 s9, s9, 0
	s_add_u32 s60, s60, 0x100
	s_addc_u32 s61, s61, 0
	s_cmp_gt_u32 s62, 29
	s_cbranch_scc0 .LBB0_1314
	s_and_b64 vcc, exec, s[28:29]
	s_cbranch_vccz .LBB0_1317
	s_barrier

; #define PG8_STAGE(bufoff, gbase, voff) do { _Pragma("unroll") for (int _i = 0; _i < 2; ++_i) \
;         __builtin_amdgcn_global_load_lds((const unsigned*)((const char*)(gbase) + (voff)[_i]), (LAS unsigned*)(lds + (bufoff) + ldsw + _i * 8192), 16, 0, 0); } while (0)
; #define PG8_LDA(dst, b, h) do { _Pragma("unroll") for (int m = 0; m < 4; ++m) _Pragma("unroll") for (int k = 0; k < 2; ++k) dst[m][k] = *(const LAS bf16x8*)(lds + PG8_SA(b, h) + aoff + m * 2048 + k * 1024); } while (0)
; #define PG8_LDB(dst, b, h) do { _Pragma("unroll") for (int n = 0; n < 2; ++n) _Pragma("unroll") for (int k = 0; k < 2; ++k) dst[n][k] = *(const LAS bf16x8*)(lds + PG8_SB(b, h) + boff + n * 2048 + k * 1024); } while (0)
; #define PG8_MMA(ai, bj, At, Bt) do { __builtin_amdgcn_s_setprio(1); _Pragma("unroll") for (int m = 0; m < 4; ++m) _Pragma("unroll") for (int n = 0; n < 2; ++n) _Pragma("unroll") for (int k = 0; k < 2; ++k) \
;         acc[ai][bj][m][n] = __builtin_amdgcn_mfma_f32_16x16x32_bf16(Bt[n][k], At[m][k], acc[ai][bj][m][n], 0, 0, 0); __builtin_amdgcn_s_setprio(0); } while (0)
; #define PG8_WAIT_V(n) asm volatile("s_waitcnt vmcnt(" #n ")" ::: "memory")
; #define PG8_WAIT_L(n) asm volatile("s_waitcnt lgkmcnt(" #n ")" ::: "memory")
; #define PG8_BAR __builtin_amdgcn_s_barrier()
; template <class Epi, class Sched>
; __device__ __forceinline__ void gemm_phase(LAS unsigned char* lds, const Gemm g, const Sched& S, const Epi& E, const int tid) {
;     ...
;             const bool last = (t == nt - 2);
;             const char* a1 = cA + (size_t)(t + 1) * kstepA;
;             const char* a2 = last ? nA : cA + (size_t)(t + 2) * kstepA; const char* b2 = last ? nB : cB + (size_t)(t + 2) * kstep;
;             const char* a3 = a2 + kstepA; const char* b3 = b2 + kstep;
;             if constexpr (Epi::HAS_MID) { if (t == g.tmid) E.mid(acc, cur, ui, wr, wc, fr, fq); }
;             PG8_LDB(B0, 0, 0); PG8_LDB(B1, 0, 1); PG8_SCHED; PG8_LDA(At, 0, 0); PG8_STAGE(PG8_SA(1, 1), a1 + hstepA, voffA);
;             PG8_WAIT_V(8); PG8_WAIT_L(0); PG8_BAR; PG8_MMA(0, 0, At, B0); PG8_MMA(0, 1, At, B1); PG8_BAR; PG8_SCHED;
;             PG8_LDA(At, 0, 1); PG8_STAGE(PG8_SB(0, 0), b2, voffB); PG8_STAGE(PG8_SB(0, 1), b2 + hstepB, voffB); PG8_STAGE(PG8_SA(0, 0), a2, voffA);
;             PG8_WAIT_V(8); PG8_WAIT_L(0); PG8_BAR; PG8_MMA(1, 0, At, B0); PG8_MMA(1, 1, At, B1); PG8_BAR; PG8_SCHED;
.LBB0_1390:
	ds_read_b128 v[128:131], v189
	ds_read_b128 v[132:135], v189 offset:1024
	ds_read_b128 v[136:139], v189 offset:2048
	ds_read_b128 v[140:143], v189 offset:3072
	ds_read_b128 v[144:147], v190
	ds_read_b128 v[164:167], v190 offset:1024
	ds_read_b128 v[168:171], v190 offset:2048
	ds_read_b128 v[172:175], v190 offset:3072
	s_add_u32 s24, s20, 0x100
	s_addc_u32 s25, s21, 0
	s_cmpk_eq_i32 s53, 0x54
	s_cselect_b32 s29, s5, s25
	s_cselect_b32 s28, s4, s24
	s_cselect_b32 s27, s19, s52
	s_cselect_b32 s26, s18, s51
	v_lshl_add_u64 v[184:185], s[20:21], 0, v[156:157]
	s_add_i32 m0, s34, 0xc000
	ds_read_b128 v[176:179], v191
	ds_read_b128 v[180:183], v191 offset:1024
	ds_read_b128 v[192:195], v191 offset:2048
	ds_read_b128 v[196:199], v191 offset:3072
	ds_read_b128 v[200:203], v191 offset:4096
	ds_read_b128 v[204:207], v191 offset:5120
	ds_read_b128 v[208:211], v191 offset:6144
	ds_read_b128 v[212:215], v191 offset:7168
	global_load_lds_dwordx4 v[184:185], off
	v_lshl_add_u64 v[184:185], s[20:21], 0, v[158:159]
	s_add_i32 m0, s34, 0xe000
	s_nop 0
	global_load_lds_dwordx4 v[184:185], off
	s_waitcnt vmcnt(8)
	s_waitcnt lgkmcnt(0)
	s_setprio 1
	s_waitcnt lgkmcnt(0)
	s_barrier
	v_mfma_f32_16x16x32_bf16 v[124:127], v[128:131], v[176:179], v[124:127]
	v_mfma_f32_16x16x32_bf16 v[120:123], v[136:139], v[176:179], v[120:123]
	v_mfma_f32_16x16x32_bf16 v[116:119], v[128:131], v[192:195], v[116:119]
	v_mfma_f32_16x16x32_bf16 v[112:115], v[136:139], v[192:195], v[112:115]
	v_mfma_f32_16x16x32_bf16 v[108:111], v[128:131], v[200:203], v[108:111]
	v_mfma_f32_16x16x32_bf16 v[104:107], v[136:139], v[200:203], v[104:107]
	v_mfma_f32_16x16x32_bf16 v[100:103], v[128:131], v[208:211], v[100:103]
	v_mfma_f32_16x16x32_bf16 v[96:99], v[136:139], v[208:211], v[96:99]
	v_mfma_f32_16x16x32_bf16 v[124:127], v[132:135], v[180:183], v[124:127]
	v_mfma_f32_16x16x32_bf16 v[120:123], v[140:143], v[180:183], v[120:123]
	v_mfma_f32_16x16x32_bf16 v[116:119], v[132:135], v[196:199], v[116:119]
	v_mfma_f32_16x16x32_bf16 v[112:115], v[140:143], v[196:199], v[112:115]
	v_mfma_f32_16x16x32_bf16 v[108:111], v[132:135], v[204:207], v[108:111]
	v_mfma_f32_16x16x32_bf16 v[104:107], v[140:143], v[204:207], v[104:107]
	v_mfma_f32_16x16x32_bf16 v[100:103], v[132:135], v[212:215], v[100:103]
	v_mfma_f32_16x16x32_bf16 v[96:99], v[140:143], v[212:215], v[96:99]
	s_setprio 0
	s_setprio 1
	v_mfma_f32_16x16x32_bf16 v[68:71], v[144:147], v[176:179], v[68:71]
	v_mfma_f32_16x16x32_bf16 v[60:63], v[168:171], v[176:179], v[60:63]
	v_mfma_f32_16x16x32_bf16 v[52:55], v[144:147], v[192:195], v[52:55]
	v_mfma_f32_16x16x32_bf16 v[48:51], v[168:171], v[192:195], v[48:51]
	v_mfma_f32_16x16x32_bf16 v[44:47], v[144:147], v[200:203], v[44:47]
	v_mfma_f32_16x16x32_bf16 v[40:43], v[168:171], v[200:203], v[40:43]
	v_mfma_f32_16x16x32_bf16 v[36:39], v[144:147], v[208:211], v[36:39]
	v_mfma_f32_16x16x32_bf16 v[32:35], v[168:171], v[208:211], v[32:35]
	v_mfma_f32_16x16x32_bf16 v[68:71], v[164:167], v[180:183], v[68:71]
	v_mfma_f32_16x16x32_bf16 v[60:63], v[172:175], v[180:183], v[60:63]
	v_mfma_f32_16x16x32_bf16 v[52:55], v[164:167], v[196:199], v[52:55]
	v_mfma_f32_16x16x32_bf16 v[48:51], v[172:175], v[196:199], v[48:51]
	v_mfma_f32_16x16x32_bf16 v[44:47], v[164:167], v[204:207], v[44:47]
	v_mfma_f32_16x16x32_bf16 v[40:43], v[172:175], v[204:207], v[40:43]
	v_mfma_f32_16x16x32_bf16 v[36:39], v[164:167], v[212:215], v[36:39]
	v_mfma_f32_16x16x32_bf16 v[32:35], v[172:175], v[212:215], v[32:35]
	s_barrier
	s_setprio 0
	s_add_i32 s20, s44, s30
	v_lshl_add_u64 v[184:185], s[26:27], 0, v[152:153]
	s_mov_b32 m0, s20
	ds_read_b128 v[176:179], v191 offset:16384
	ds_read_b128 v[180:183], v191 offset:17408
	ds_read_b128 v[192:195], v191 offset:18432
	ds_read_b128 v[196:199], v191 offset:19456
	ds_read_b128 v[200:203], v191 offset:20480
	ds_read_b128 v[204:207], v191 offset:21504
	ds_read_b128 v[208:211], v191 offset:22528
	ds_read_b128 v[212:215], v191 offset:23552
	global_load_lds_dwordx4 v[184:185], off
	s_add_i32 m0, s20, 0x2000
	s_add_u32 s20, s26, 0x160000
	v_lshl_add_u64 v[216:217], s[26:27], 0, v[148:149]
	s_addc_u32 s21, s27, 0
	s_add_i32 s54, s45, s30
	global_load_lds_dwordx4 v[216:217], off
	v_lshl_add_u64 v[218:219], s[20:21], 0, v[152:153]
	s_mov_b32 m0, s54
	v_lshl_add_u64 v[220:221], s[28:29], 0, v[150:151]
	global_load_lds_dwordx4 v[218:219], off
	v_lshl_add_u64 v[218:219], s[20:21], 0, v[148:149]
	s_add_i32 m0, s54, 0x2000
	s_nop 0
	global_load_lds_dwordx4 v[218:219], off
	v_lshl_add_u64 v[218:219], s[28:29], 0, v[154:155]
	s_mov_b32 m0, s34
	s_nop 0
	global_load_lds_dwordx4 v[218:219], off
	s_mov_b32 m0, s35
	s_nop 0
	global_load_lds_dwordx4 v[220:221], off
	s_waitcnt vmcnt(8)
	s_waitcnt lgkmcnt(0)
	s_setprio 1
	s_waitcnt lgkmcnt(0)
	s_barrier
; #define PG8_STAGE(bufoff, gbase, voff) do { _Pragma("unroll") for (int _i = 0; _i < 2; ++_i) \
;         __builtin_amdgcn_global_load_lds((const unsigned*)((const char*)(gbase) + (voff)[_i]), (LAS unsigned*)(lds + (bufoff) + ldsw + _i * 8192), 16, 0, 0); } while (0)
; #define PG8_LDA(dst, b, h) do { _Pragma("unroll") for (int m = 0; m < 4; ++m) _Pragma("unroll") for (int k = 0; k < 2; ++k) dst[m][k] = *(const LAS bf16x8*)(lds + PG8_SA(b, h) + aoff + m * 2048 + k * 1024); } while (0)
; #define PG8_LDB(dst, b, h) do { _Pragma("unroll") for (int n = 0; n < 2; ++n) _Pragma("unroll") for (int k = 0; k < 2; ++k) dst[n][k] = *(const LAS bf16x8*)(lds + PG8_SB(b, h) + boff + n * 2048 + k * 1024); } while (0)
; #define PG8_MMA(ai, bj, At, Bt) do { __builtin_amdgcn_s_setprio(1); _Pragma("unroll") for (int m = 0; m < 4; ++m) _Pragma("unroll") for (int n = 0; n < 2; ++n) _Pragma("unroll") for (int k = 0; k < 2; ++k) \
;         acc[ai][bj][m][n] = __builtin_amdgcn_mfma_f32_16x16x32_bf16(Bt[n][k], At[m][k], acc[ai][bj][m][n], 0, 0, 0); __builtin_amdgcn_s_setprio(0); } while (0)
; #define PG8_WAIT_V(n) asm volatile("s_waitcnt vmcnt(" #n ")" ::: "memory")
; #define PG8_WAIT_L(n) asm volatile("s_waitcnt lgkmcnt(" #n ")" ::: "memory")
; #define PG8_BAR __builtin_amdgcn_s_barrier()
; #define PG8_SCHED __builtin_amdgcn_sched_barrier(0)
; template <class Epi, class Sched>
; __device__ __forceinline__ void gemm_phase(LAS unsigned char* lds, const Gemm g, const Sched& S, const Epi& E, const int tid) {
;     ...
;             PG8_WAIT_V(8); PG8_WAIT_L(0); PG8_BAR; PG8_MMA(1, 0, At, B0); PG8_MMA(1, 1, At, B1); PG8_BAR; PG8_SCHED;
;             PG8_LDB(B0, 1, 0); PG8_LDB(B1, 1, 1); PG8_SCHED; PG8_LDA(At, 1, 0); PG8_STAGE(PG8_SA(0, 1), a2 + hstepA, voffA);
;             PG8_WAIT_V(8); PG8_WAIT_L(0); PG8_BAR; PG8_MMA(0, 0, At, B0); PG8_MMA(0, 1, At, B1); PG8_BAR; PG8_SCHED;
	v_mfma_f32_16x16x32_bf16 v[92:95], v[128:131], v[176:179], v[92:95]
	v_mfma_f32_16x16x32_bf16 v[88:91], v[136:139], v[176:179], v[88:91]
	v_mfma_f32_16x16x32_bf16 v[84:87], v[128:131], v[192:195], v[84:87]
	v_mfma_f32_16x16x32_bf16 v[80:83], v[136:139], v[192:195], v[80:83]
	v_mfma_f32_16x16x32_bf16 v[76:79], v[128:131], v[200:203], v[76:79]
	v_mfma_f32_16x16x32_bf16 v[72:75], v[136:139], v[200:203], v[72:75]
	v_mfma_f32_16x16x32_bf16 v[64:67], v[128:131], v[208:211], v[64:67]
	v_mfma_f32_16x16x32_bf16 v[56:59], v[136:139], v[208:211], v[56:59]
	v_mfma_f32_16x16x32_bf16 v[92:95], v[132:135], v[180:183], v[92:95]
	v_mfma_f32_16x16x32_bf16 v[88:91], v[140:143], v[180:183], v[88:91]
	v_mfma_f32_16x16x32_bf16 v[84:87], v[132:135], v[196:199], v[84:87]
	v_mfma_f32_16x16x32_bf16 v[80:83], v[140:143], v[196:199], v[80:83]
	v_mfma_f32_16x16x32_bf16 v[76:79], v[132:135], v[204:207], v[76:79]
	v_mfma_f32_16x16x32_bf16 v[72:75], v[140:143], v[204:207], v[72:75]
	v_mfma_f32_16x16x32_bf16 v[64:67], v[132:135], v[212:215], v[64:67]
	v_mfma_f32_16x16x32_bf16 v[56:59], v[140:143], v[212:215], v[56:59]
	s_setprio 0
	s_setprio 1
	v_mfma_f32_16x16x32_bf16 v[28:31], v[144:147], v[176:179], v[28:31]
	v_mfma_f32_16x16x32_bf16 v[24:27], v[168:171], v[176:179], v[24:27]
	v_mfma_f32_16x16x32_bf16 v[20:23], v[144:147], v[192:195], v[20:23]
	v_mfma_f32_16x16x32_bf16 v[16:19], v[168:171], v[192:195], v[16:19]
	v_mfma_f32_16x16x32_bf16 v[12:15], v[144:147], v[200:203], v[12:15]
	v_mfma_f32_16x16x32_bf16 v[8:11], v[168:171], v[200:203], v[8:11]
	v_mfma_f32_16x16x32_bf16 v[4:7], v[144:147], v[208:211], v[4:7]
	v_mfma_f32_16x16x32_bf16 v[0:3], v[168:171], v[208:211], v[0:3]
	v_mfma_f32_16x16x32_bf16 v[28:31], v[164:167], v[180:183], v[28:31]
	v_mfma_f32_16x16x32_bf16 v[24:27], v[172:175], v[180:183], v[24:27]
	v_mfma_f32_16x16x32_bf16 v[20:23], v[164:167], v[196:199], v[20:23]
	v_mfma_f32_16x16x32_bf16 v[16:19], v[172:175], v[196:199], v[16:19]
	v_mfma_f32_16x16x32_bf16 v[12:15], v[164:167], v[204:207], v[12:15]
	v_mfma_f32_16x16x32_bf16 v[8:11], v[172:175], v[204:207], v[8:11]
	v_mfma_f32_16x16x32_bf16 v[4:7], v[164:167], v[212:215], v[4:7]
	v_mfma_f32_16x16x32_bf16 v[0:3], v[172:175], v[212:215], v[0:3]
	s_barrier
	s_setprio 0
	s_add_i32 s54, 0, 0x18000
	s_add_i32 s55, 0, 0x1c000
	v_add_u32_e32 v140, s54, v188
	v_add_u32_e32 v172, s55, v188
	ds_read_b128 v[128:131], v140
	ds_read_b128 v[132:135], v140 offset:1024
	ds_read_b128 v[136:139], v140 offset:2048
	ds_read_b128 v[140:143], v140 offset:3072
	ds_read_b128 v[144:147], v172
	ds_read_b128 v[164:167], v172 offset:1024
	ds_read_b128 v[168:171], v172 offset:2048
	ds_read_b128 v[172:175], v172 offset:3072
	s_add_u32 s20, s28, 0x160000
	s_addc_u32 s21, s29, 0
	s_mov_b32 m0, s36
	v_lshl_add_u64 v[222:223], s[20:21], 0, v[154:155]
	ds_read_b128 v[176:179], v191 offset:32768
	ds_read_b128 v[180:183], v191 offset:33792
	ds_read_b128 v[192:195], v191 offset:34816
	ds_read_b128 v[196:199], v191 offset:35840
	ds_read_b128 v[200:203], v191 offset:36864
	ds_read_b128 v[204:207], v191 offset:37888
	ds_read_b128 v[208:211], v191 offset:38912
	ds_read_b128 v[212:215], v191 offset:39936
	global_load_lds_dwordx4 v[222:223], off
	v_lshl_add_u64 v[222:223], s[20:21], 0, v[150:151]
	s_mov_b32 m0, s37
	s_nop 0
	global_load_lds_dwordx4 v[222:223], off
	s_waitcnt vmcnt(8)
	s_waitcnt lgkmcnt(0)
	s_setprio 1
	s_waitcnt lgkmcnt(0)
	s_barrier
	v_mfma_f32_16x16x32_bf16 v[124:127], v[128:131], v[176:179], v[124:127]
	v_mfma_f32_16x16x32_bf16 v[120:123], v[136:139], v[176:179], v[120:123]
	v_mfma_f32_16x16x32_bf16 v[116:119], v[128:131], v[192:195], v[116:119]
	v_mfma_f32_16x16x32_bf16 v[112:115], v[136:139], v[192:195], v[112:115]
	v_mfma_f32_16x16x32_bf16 v[108:111], v[128:131], v[200:203], v[108:111]
	v_mfma_f32_16x16x32_bf16 v[104:107], v[136:139], v[200:203], v[104:107]
	v_mfma_f32_16x16x32_bf16 v[100:103], v[128:131], v[208:211], v[100:103]
	v_mfma_f32_16x16x32_bf16 v[96:99], v[136:139], v[208:211], v[96:99]
	v_mfma_f32_16x16x32_bf16 v[124:127], v[132:135], v[180:183], v[124:127]
	v_mfma_f32_16x16x32_bf16 v[120:123], v[140:143], v[180:183], v[120:123]
	v_mfma_f32_16x16x32_bf16 v[116:119], v[132:135], v[196:199], v[116:119]
	v_mfma_f32_16x16x32_bf16 v[112:115], v[140:143], v[196:199], v[112:115]
	v_mfma_f32_16x16x32_bf16 v[108:111], v[132:135], v[204:207], v[108:111]
	v_mfma_f32_16x16x32_bf16 v[104:107], v[140:143], v[204:207], v[104:107]
	v_mfma_f32_16x16x32_bf16 v[100:103], v[132:135], v[212:215], v[100:103]
	v_mfma_f32_16x16x32_bf16 v[96:99], v[140:143], v[212:215], v[96:99]
	s_setprio 0
	s_setprio 1
	v_mfma_f32_16x16x32_bf16 v[68:71], v[144:147], v[176:179], v[68:71]
	v_mfma_f32_16x16x32_bf16 v[60:63], v[168:171], v[176:179], v[60:63]
	v_mfma_f32_16x16x32_bf16 v[52:55], v[144:147], v[192:195], v[52:55]
	v_mfma_f32_16x16x32_bf16 v[48:51], v[168:171], v[192:195], v[48:51]
	v_mfma_f32_16x16x32_bf16 v[44:47], v[144:147], v[200:203], v[44:47]
	v_mfma_f32_16x16x32_bf16 v[40:43], v[168:171], v[200:203], v[40:43]
	v_mfma_f32_16x16x32_bf16 v[36:39], v[144:147], v[208:211], v[36:39]
	v_mfma_f32_16x16x32_bf16 v[32:35], v[168:171], v[208:211], v[32:35]
	v_mfma_f32_16x16x32_bf16 v[68:71], v[164:167], v[180:183], v[68:71]
	v_mfma_f32_16x16x32_bf16 v[60:63], v[172:175], v[180:183], v[60:63]
	v_mfma_f32_16x16x32_bf16 v[52:55], v[164:167], v[196:199], v[52:55]
	v_mfma_f32_16x16x32_bf16 v[48:51], v[172:175], v[196:199], v[48:51]
	v_mfma_f32_16x16x32_bf16 v[44:47], v[164:167], v[204:207], v[44:47]
	v_mfma_f32_16x16x32_bf16 v[40:43], v[172:175], v[204:207], v[40:43]
	v_mfma_f32_16x16x32_bf16 v[36:39], v[164:167], v[212:215], v[36:39]
	v_mfma_f32_16x16x32_bf16 v[32:35], v[172:175], v[212:215], v[32:35]
	s_barrier
; #define PG8_STAGE(bufoff, gbase, voff) do { _Pragma("unroll") for (int _i = 0; _i < 2; ++_i) \
;         __builtin_amdgcn_global_load_lds((const unsigned*)((const char*)(gbase) + (voff)[_i]), (LAS unsigned*)(lds + (bufoff) + ldsw + _i * 8192), 16, 0, 0); } while (0)
; #define PG8_LDA(dst, b, h) do { _Pragma("unroll") for (int m = 0; m < 4; ++m) _Pragma("unroll") for (int k = 0; k < 2; ++k) dst[m][k] = *(const LAS bf16x8*)(lds + PG8_SA(b, h) + aoff + m * 2048 + k * 1024); } while (0)
; #define PG8_MMA(ai, bj, At, Bt) do { __builtin_amdgcn_s_setprio(1); _Pragma("unroll") for (int m = 0; m < 4; ++m) _Pragma("unroll") for (int n = 0; n < 2; ++n) _Pragma("unroll") for (int k = 0; k < 2; ++k) \
;         acc[ai][bj][m][n] = __builtin_amdgcn_mfma_f32_16x16x32_bf16(Bt[n][k], At[m][k], acc[ai][bj][m][n], 0, 0, 0); __builtin_amdgcn_s_setprio(0); } while (0)
; #define PG8_WAIT_V(n) asm volatile("s_waitcnt vmcnt(" #n ")" ::: "memory")
; #define PG8_WAIT_L(n) asm volatile("s_waitcnt lgkmcnt(" #n ")" ::: "memory")
; #define PG8_BAR __builtin_amdgcn_s_barrier()
; #define PG8_SCHED __builtin_amdgcn_sched_barrier(0)
; template <class Epi, class Sched>
; __device__ __forceinline__ void gemm_phase(LAS unsigned char* lds, const Gemm g, const Sched& S, const Epi& E, const int tid) {
;     ...
;             PG8_WAIT_V(8); PG8_WAIT_L(0); PG8_BAR; PG8_MMA(0, 0, At, B0); PG8_MMA(0, 1, At, B1); PG8_BAR; PG8_SCHED;
;             PG8_LDA(At, 1, 1); PG8_STAGE(PG8_SB(1, 0), b3, voffB); PG8_STAGE(PG8_SB(1, 1), b3 + hstepB, voffB); PG8_STAGE(PG8_SA(1, 0), a3, voffA);
;             PG8_WAIT_V(8); PG8_WAIT_L(0); PG8_BAR; PG8_MMA(1, 0, At, B0); PG8_MMA(1, 1, At, B1); PG8_BAR; PG8_SCHED;
;         }
;         if (wr == 0) PG8_BAR;
	s_setprio 0
	s_add_i32 s20, s54, s30
	v_lshl_add_u64 v[184:185], v[184:185], 0, s[12:13]
	s_mov_b32 m0, s20
	ds_read_b128 v[176:179], v191 offset:49152
	ds_read_b128 v[180:183], v191 offset:50176
	ds_read_b128 v[192:195], v191 offset:51200
	ds_read_b128 v[196:199], v191 offset:52224
	ds_read_b128 v[200:203], v191 offset:53248
	ds_read_b128 v[204:207], v191 offset:54272
	ds_read_b128 v[208:211], v191 offset:55296
	ds_read_b128 v[212:215], v191 offset:56320
	global_load_lds_dwordx4 v[184:185], off
	s_add_i32 m0, s20, 0x2000
	s_add_u32 s20, s26, 0x160080
	v_lshl_add_u64 v[184:185], v[216:217], 0, s[12:13]
	s_addc_u32 s21, s27, 0
	s_add_i32 s26, s55, s30
	global_load_lds_dwordx4 v[184:185], off
	v_lshl_add_u64 v[184:185], s[20:21], 0, v[152:153]
	s_mov_b32 m0, s26
	s_nop 0
	global_load_lds_dwordx4 v[184:185], off
	v_lshl_add_u64 v[184:185], s[20:21], 0, v[148:149]
	s_add_i32 m0, s26, 0x2000
	s_nop 0
	global_load_lds_dwordx4 v[184:185], off
	v_lshl_add_u64 v[184:185], v[218:219], 0, s[12:13]
	s_mov_b32 m0, s39
	s_nop 0
	global_load_lds_dwordx4 v[184:185], off
	v_lshl_add_u64 v[184:185], v[220:221], 0, s[12:13]
	s_mov_b32 m0, s40
	s_nop 0
	global_load_lds_dwordx4 v[184:185], off
	s_waitcnt vmcnt(8)
	s_waitcnt lgkmcnt(0)
	s_setprio 1
	s_waitcnt lgkmcnt(0)
	s_barrier
	v_mfma_f32_16x16x32_bf16 v[92:95], v[128:131], v[176:179], v[92:95]
	v_mfma_f32_16x16x32_bf16 v[88:91], v[136:139], v[176:179], v[88:91]
	v_mfma_f32_16x16x32_bf16 v[84:87], v[128:131], v[192:195], v[84:87]
	v_mfma_f32_16x16x32_bf16 v[80:83], v[136:139], v[192:195], v[80:83]
	v_mfma_f32_16x16x32_bf16 v[76:79], v[128:131], v[200:203], v[76:79]
	v_mfma_f32_16x16x32_bf16 v[72:75], v[136:139], v[200:203], v[72:75]
	v_mfma_f32_16x16x32_bf16 v[64:67], v[128:131], v[208:211], v[64:67]
	v_mfma_f32_16x16x32_bf16 v[56:59], v[136:139], v[208:211], v[56:59]
	v_mfma_f32_16x16x32_bf16 v[92:95], v[132:135], v[180:183], v[92:95]
	v_mfma_f32_16x16x32_bf16 v[88:91], v[140:143], v[180:183], v[88:91]
	v_mfma_f32_16x16x32_bf16 v[84:87], v[132:135], v[196:199], v[84:87]
	v_mfma_f32_16x16x32_bf16 v[80:83], v[140:143], v[196:199], v[80:83]
	v_mfma_f32_16x16x32_bf16 v[76:79], v[132:135], v[204:207], v[76:79]
	v_mfma_f32_16x16x32_bf16 v[72:75], v[140:143], v[204:207], v[72:75]
	v_mfma_f32_16x16x32_bf16 v[64:67], v[132:135], v[212:215], v[64:67]
	v_mfma_f32_16x16x32_bf16 v[56:59], v[140:143], v[212:215], v[56:59]
	s_setprio 0
	s_setprio 1
	v_mfma_f32_16x16x32_bf16 v[28:31], v[144:147], v[176:179], v[28:31]
	v_mfma_f32_16x16x32_bf16 v[24:27], v[168:171], v[176:179], v[24:27]
	v_mfma_f32_16x16x32_bf16 v[20:23], v[144:147], v[192:195], v[20:23]
	v_mfma_f32_16x16x32_bf16 v[16:19], v[168:171], v[192:195], v[16:19]
	v_mfma_f32_16x16x32_bf16 v[12:15], v[144:147], v[200:203], v[12:15]
	v_mfma_f32_16x16x32_bf16 v[8:11], v[168:171], v[200:203], v[8:11]
	v_mfma_f32_16x16x32_bf16 v[4:7], v[144:147], v[208:211], v[4:7]
	v_mfma_f32_16x16x32_bf16 v[0:3], v[168:171], v[208:211], v[0:3]
	v_mfma_f32_16x16x32_bf16 v[28:31], v[164:167], v[180:183], v[28:31]
	v_mfma_f32_16x16x32_bf16 v[24:27], v[172:175], v[180:183], v[24:27]
	v_mfma_f32_16x16x32_bf16 v[20:23], v[164:167], v[196:199], v[20:23]
	v_mfma_f32_16x16x32_bf16 v[16:19], v[172:175], v[196:199], v[16:19]
	v_mfma_f32_16x16x32_bf16 v[12:15], v[164:167], v[204:207], v[12:15]
	v_mfma_f32_16x16x32_bf16 v[8:11], v[172:175], v[204:207], v[8:11]
	v_mfma_f32_16x16x32_bf16 v[4:7], v[164:167], v[212:215], v[4:7]
	v_mfma_f32_16x16x32_bf16 v[0:3], v[172:175], v[212:215], v[0:3]
	s_barrier
	s_setprio 0
	s_add_i32 s53, s53, 2
	s_add_u32 s51, s51, 0x100
	s_addc_u32 s52, s52, 0
	s_cmpk_gt_u32 s53, 0x55
	s_mov_b64 s[20:21], s[24:25]
	s_cbranch_scc0 .LBB0_1390
	s_and_b64 vcc, exec, s[14:15]
	s_cbranch_vccz .LBB0_1393
	s_barrier
